# adds: in-proj epilogue loads bias vectors once per gate tile and drops redundant vmcnt(0) waits; attention O-store epilogue batched to 4 stores per exec mask
# speedup vs baseline: 1.0041x; 1.0041x over previous
.LBB0_254:
	v_add_u32_e32 v14, s9, v17
	v_ashrrev_i32_e32 v15, 31, v14
	v_lshlrev_b64 v[168:169], 13, v[14:15]
	s_and_b64 vcc, exec, s[22:23]
	s_cbranch_vccz .LBB0_274
	s_cmp_gt_i32 s1, 2
	s_mov_b64 s[46:47], -1
	s_cbranch_scc0 .LBB0_257
	v_lshl_add_u64 v[146:147], s[18:19], 2, v[160:161]
	global_load_dwordx4 v[200:203], v[146:147], off
	global_load_dwordx4 v[204:207], v[146:147], off offset:16
	global_load_dwordx4 v[208:211], v[146:147], off offset:512
	global_load_dwordx4 v[216:219], v[146:147], off offset:528
	s_nop 0
	s_mov_b64 s[46:47], 0
	s_waitcnt vmcnt(0)
	v_mov_b64_e32 v[142:143], v[204:205]
	v_mov_b64_e32 v[144:145], v[206:207]
	v_mov_b64_e32 v[146:147], v[200:201]
	v_mov_b64_e32 v[148:149], v[202:203]
	v_add_f32_e32 v142, v134, v142
	v_mul_f32_e32 v142, 0xbfb8aa3b, v142
	v_add_f32_e32 v143, v135, v143
	v_exp_f32_e32 v142, v142
	v_mul_f32_e32 v143, 0xbfb8aa3b, v143
	v_exp_f32_e32 v143, v143
	v_add_f32_e32 v15, v138, v146
	v_add_f32_e32 v142, 1.0, v142
	v_rcp_f32_e32 v142, v142
	v_add_f32_e32 v143, 1.0, v143
	v_rcp_f32_e32 v143, v143
	v_mul_f32_e32 v15, 0xbfb8aa3b, v15
	v_mul_f32_e32 v142, 0x437f0000, v142
	v_rndne_f32_e32 v142, v142
	v_mul_f32_e32 v143, 0x437f0000, v143
	v_cvt_pk_u8_f32 v142, v142, 0, 0
	v_add_f32_e32 v146, v139, v147
	v_rndne_f32_e32 v143, v143
	v_exp_f32_e32 v15, v15
	v_mul_f32_e32 v146, 0xbfb8aa3b, v146
	v_cvt_pk_u8_f32 v142, v143, 1, v142
	v_add_f32_e32 v143, v140, v148
	v_exp_f32_e32 v146, v146
	v_mul_f32_e32 v143, 0xbfb8aa3b, v143
	v_exp_f32_e32 v143, v143
	v_add_f32_e32 v15, 1.0, v15
	v_rcp_f32_e32 v15, v15
	v_add_f32_e32 v146, 1.0, v146
	v_rcp_f32_e32 v146, v146
	v_add_f32_e32 v143, 1.0, v143
	v_rcp_f32_e32 v143, v143
	v_mul_f32_e32 v15, 0x437f0000, v15
	v_rndne_f32_e32 v15, v15
	v_mul_f32_e32 v146, 0x437f0000, v146
	v_cvt_pk_u8_f32 v15, v15, 0, 0
	v_rndne_f32_e32 v146, v146
	v_mul_f32_e32 v143, 0x437f0000, v143
	v_cvt_pk_u8_f32 v15, v146, 1, v15
	v_rndne_f32_e32 v143, v143
	v_cvt_pk_u8_f32 v15, v143, 2, v15
	v_add_f32_e32 v143, v136, v144
	v_mul_f32_e32 v143, 0xbfb8aa3b, v143
	v_exp_f32_e32 v143, v143
	s_nop 0
	v_add_f32_e32 v143, 1.0, v143
	v_rcp_f32_e32 v143, v143
	s_nop 0
	v_mul_f32_e32 v143, 0x437f0000, v143
	v_rndne_f32_e32 v143, v143
	v_cvt_pk_u8_f32 v143, v143, 2, v142
	v_add_f32_e32 v142, v141, v149
	v_mul_f32_e32 v142, 0xbfb8aa3b, v142
	v_exp_f32_e32 v142, v142
	s_nop 0
	v_add_f32_e32 v142, 1.0, v142
	v_rcp_f32_e32 v142, v142
	s_nop 0
	v_mul_f32_e32 v142, 0x437f0000, v142
	v_rndne_f32_e32 v142, v142
	v_cvt_pk_u8_f32 v142, v142, 3, v15
	v_add_f32_e32 v15, v137, v145
	v_mul_f32_e32 v15, 0xbfb8aa3b, v15
	v_exp_f32_e32 v15, v15
	v_lshl_add_u64 v[144:145], s[58:59], 0, v[168:169]
	v_lshl_add_u64 v[144:145], v[144:145], 0, s[18:19]
	v_lshl_add_u64 v[144:145], v[144:145], 0, s[26:27]
	v_add_f32_e32 v15, 1.0, v15
	v_rcp_f32_e32 v15, v15
	v_lshl_add_u64 v[144:145], v[144:145], 0, v[156:157]
	v_mul_f32_e32 v15, 0x437f0000, v15
	v_rndne_f32_e32 v15, v15
	v_cvt_pk_u8_f32 v143, v15, 3, v143
	global_store_dwordx2 v[144:145], v[142:143], off

.LBB0_265:
	v_cndmask_b32_e64 v15, 0, 1, s[22:23]
	v_cmp_ne_u32_e64 s[46:47], 1, v15
	s_andn2_b64 vcc, exec, s[22:23]
	s_cbranch_vccnz .LBB0_275
	s_cmp_gt_i32 s1, 2
	s_mov_b64 s[22:23], -1
	s_cbranch_scc0 .LBB0_268
	v_lshl_add_u64 v[138:139], s[18:19], 2, v[160:161]
	v_mov_b64_e32 v[134:135], v[208:209]
	v_mov_b64_e32 v[136:137], v[210:211]
	s_nop 0
	v_mov_b64_e32 v[138:139], v[216:217]
	v_mov_b64_e32 v[140:141], v[218:219]
	v_lshl_add_u64 v[142:143], s[58:59], 0, v[168:169]
	v_lshl_add_u64 v[142:143], v[142:143], 0, s[18:19]
	v_lshl_add_u64 v[142:143], v[142:143], 0, s[26:27]
	v_lshl_add_u64 v[142:143], v[142:143], 0, v[156:157]
	s_mov_b64 s[22:23], 0
	v_add_f32_e32 v15, v130, v134
	v_add_f32_e32 v134, v126, v138
	v_add_f32_e32 v135, v131, v135
	v_add_f32_e32 v138, v127, v139
	v_mul_f32_e32 v15, 0xbfb8aa3b, v15
	v_mul_f32_e32 v134, 0xbfb8aa3b, v134
	v_add_f32_e32 v136, v132, v136
	v_add_f32_e32 v139, v128, v140
	v_mul_f32_e32 v135, 0xbfb8aa3b, v135
	v_mul_f32_e32 v138, 0xbfb8aa3b, v138
	v_exp_f32_e32 v15, v15
	v_exp_f32_e32 v134, v134
	v_add_f32_e32 v137, v133, v137
	v_add_f32_e32 v140, v129, v141
	v_mul_f32_e32 v136, 0xbfb8aa3b, v136
	v_mul_f32_e32 v139, 0xbfb8aa3b, v139
	v_exp_f32_e32 v135, v135
	v_exp_f32_e32 v138, v138
	v_mul_f32_e32 v137, 0xbfb8aa3b, v137
	v_mul_f32_e32 v140, 0xbfb8aa3b, v140
	v_exp_f32_e32 v136, v136
	v_exp_f32_e32 v139, v139
	v_exp_f32_e32 v137, v137
	v_exp_f32_e32 v140, v140
	v_add_f32_e32 v15, 1.0, v15
	v_add_f32_e32 v134, 1.0, v134
	v_add_f32_e32 v135, 1.0, v135
	v_add_f32_e32 v138, 1.0, v138
	v_rcp_f32_e32 v15, v15
	v_rcp_f32_e32 v134, v134
	v_add_f32_e32 v136, 1.0, v136
	v_add_f32_e32 v139, 1.0, v139
	v_rcp_f32_e32 v135, v135
	v_rcp_f32_e32 v138, v138
	v_add_f32_e32 v137, 1.0, v137
	v_add_f32_e32 v140, 1.0, v140
	v_rcp_f32_e32 v136, v136
	v_rcp_f32_e32 v139, v139
	v_rcp_f32_e32 v137, v137
	v_rcp_f32_e32 v140, v140
	v_mul_f32_e32 v15, 0x437f0000, v15
	v_mul_f32_e32 v134, 0x437f0000, v134
	v_mul_f32_e32 v135, 0x437f0000, v135
	v_mul_f32_e32 v138, 0x437f0000, v138
	v_rndne_f32_e32 v15, v15
	v_rndne_f32_e32 v134, v134
	v_mul_f32_e32 v136, 0x437f0000, v136
	v_mul_f32_e32 v139, 0x437f0000, v139
	v_rndne_f32_e32 v135, v135
	v_rndne_f32_e32 v138, v138
	v_cvt_pk_u8_f32 v15, v15, 0, 0
	v_cvt_pk_u8_f32 v134, v134, 0, 0
	v_mul_f32_e32 v137, 0x437f0000, v137
	v_mul_f32_e32 v140, 0x437f0000, v140
	v_rndne_f32_e32 v136, v136
	v_rndne_f32_e32 v139, v139
	v_cvt_pk_u8_f32 v15, v135, 1, v15
	v_cvt_pk_u8_f32 v134, v138, 1, v134
	v_rndne_f32_e32 v137, v137
	v_rndne_f32_e32 v140, v140
	v_cvt_pk_u8_f32 v15, v136, 2, v15
	v_cvt_pk_u8_f32 v135, v139, 2, v134
	v_cvt_pk_u8_f32 v134, v137, 3, v15
	v_cvt_pk_u8_f32 v135, v140, 3, v135
	global_store_dwordx2 v[142:143], v[134:135], off offset:128

.LBB0_273:
	ds_read_b128 v[134:137], v175 offset:16
	s_waitcnt lgkmcnt(0)
	v_mov_b32_e32 v138, v135
	v_mov_b32_e32 v139, v136
	v_mov_b32_e32 v135, v137
	v_pk_add_f32 v[134:135], v[138:139], v[134:135]
	s_nop 0
	v_add_f32_e32 v15, v134, v135
	v_fmamk_f32 v15, v15, 0x3c000000, v250
	v_mul_f32_e32 v134, 0x4b800000, v15
	v_cmp_gt_f32_e32 vcc, s28, v15
	s_nop 1
	v_cndmask_b32_e32 v15, v15, v134, vcc
	v_rsq_f32_e32 v15, v15
	s_nop 0
	v_mul_f32_e32 v134, 0x45800000, v15
	v_cndmask_b32_e32 v134, v15, v134, vcc
	v_pk_mul_f32 v[130:131], v[130:131], v[134:135] op_sel_hi:[1,0]
	v_pk_mul_f32 v[132:133], v[132:133], v[134:135] op_sel_hi:[1,0]
	v_pk_mul_f32 v[126:127], v[126:127], v[134:135] op_sel_hi:[1,0]
	v_pk_mul_f32 v[128:129], v[128:129], v[134:135] op_sel_hi:[1,0]
	v_pk_mul_f32 v[136:137], v[12:13], v[132:133]
	v_pk_mul_f32 v[134:135], v[10:11], v[130:131]
	v_pk_mul_f32 v[140:141], v[20:21], v[128:129]
	v_pk_mul_f32 v[138:139], v[18:19], v[126:127]
	s_branch .LBB0_277

.LBB0_278:
	v_or_b32_e32 v136, 16, v14
	v_ashrrev_i32_e32 v137, 31, v136
	s_and_b64 vcc, exec, s[46:47]
	v_lshlrev_b64 v[134:135], 13, v[136:137]
	s_cbranch_vccnz .LBB0_296
	s_cmp_gt_i32 s1, 2
	s_mov_b64 s[22:23], -1
	s_cbranch_scc0 .LBB0_281
	v_lshl_add_u64 v[130:131], s[18:19], 2, v[160:161]
	v_mov_b64_e32 v[126:127], v[204:205]
	v_mov_b64_e32 v[128:129], v[206:207]
	s_nop 0
	v_mov_b64_e32 v[130:131], v[200:201]
	v_mov_b64_e32 v[132:133], v[202:203]
	s_mov_b64 s[22:23], 0
	v_add_f32_e32 v126, v118, v126
	v_mul_f32_e32 v126, 0xbfb8aa3b, v126
	v_add_f32_e32 v127, v119, v127
	v_exp_f32_e32 v126, v126
	v_mul_f32_e32 v127, 0xbfb8aa3b, v127
	v_exp_f32_e32 v127, v127
	v_add_f32_e32 v15, v122, v130
	v_add_f32_e32 v126, 1.0, v126
	v_rcp_f32_e32 v126, v126
	v_add_f32_e32 v127, 1.0, v127
	v_rcp_f32_e32 v127, v127
	v_mul_f32_e32 v15, 0xbfb8aa3b, v15
	v_mul_f32_e32 v126, 0x437f0000, v126
	v_rndne_f32_e32 v126, v126
	v_mul_f32_e32 v127, 0x437f0000, v127
	v_cvt_pk_u8_f32 v126, v126, 0, 0
	v_add_f32_e32 v130, v123, v131
	v_rndne_f32_e32 v127, v127
	v_exp_f32_e32 v15, v15
	v_mul_f32_e32 v130, 0xbfb8aa3b, v130
	v_cvt_pk_u8_f32 v126, v127, 1, v126
	v_add_f32_e32 v127, v124, v132
	v_exp_f32_e32 v130, v130
	v_mul_f32_e32 v127, 0xbfb8aa3b, v127
	v_exp_f32_e32 v127, v127
	v_add_f32_e32 v15, 1.0, v15
	v_rcp_f32_e32 v15, v15
	v_add_f32_e32 v130, 1.0, v130
	v_rcp_f32_e32 v130, v130
	v_add_f32_e32 v127, 1.0, v127
	v_rcp_f32_e32 v127, v127
	v_mul_f32_e32 v15, 0x437f0000, v15
	v_rndne_f32_e32 v15, v15
	v_mul_f32_e32 v130, 0x437f0000, v130
	v_cvt_pk_u8_f32 v15, v15, 0, 0
	v_rndne_f32_e32 v130, v130
	v_mul_f32_e32 v127, 0x437f0000, v127
	v_cvt_pk_u8_f32 v15, v130, 1, v15
	v_rndne_f32_e32 v127, v127
	v_cvt_pk_u8_f32 v15, v127, 2, v15
	v_add_f32_e32 v127, v120, v128
	v_mul_f32_e32 v127, 0xbfb8aa3b, v127
	v_exp_f32_e32 v127, v127
	s_nop 0
	v_add_f32_e32 v127, 1.0, v127
	v_rcp_f32_e32 v127, v127
	s_nop 0
	v_mul_f32_e32 v127, 0x437f0000, v127
	v_rndne_f32_e32 v127, v127
	v_cvt_pk_u8_f32 v127, v127, 2, v126
	v_add_f32_e32 v126, v125, v133
	v_mul_f32_e32 v126, 0xbfb8aa3b, v126
	v_exp_f32_e32 v126, v126
	s_nop 0
	v_add_f32_e32 v126, 1.0, v126
	v_rcp_f32_e32 v126, v126
	s_nop 0
	v_mul_f32_e32 v126, 0x437f0000, v126
	v_rndne_f32_e32 v126, v126
	v_cvt_pk_u8_f32 v126, v126, 3, v15
	v_add_f32_e32 v15, v121, v129
	v_mul_f32_e32 v15, 0xbfb8aa3b, v15
	v_exp_f32_e32 v15, v15
	v_lshl_add_u64 v[128:129], s[58:59], 0, v[134:135]
	v_lshl_add_u64 v[128:129], v[128:129], 0, s[18:19]
	v_lshl_add_u64 v[128:129], v[128:129], 0, s[26:27]
	v_add_f32_e32 v15, 1.0, v15
	v_rcp_f32_e32 v15, v15
	v_lshl_add_u64 v[128:129], v[128:129], 0, v[156:157]
	v_mul_f32_e32 v15, 0x437f0000, v15
	v_rndne_f32_e32 v15, v15
	v_cvt_pk_u8_f32 v127, v15, 3, v127
	global_store_dwordx2 v[128:129], v[126:127], off

.LBB0_286:
	ds_read_b128 v[126:129], v178
	s_waitcnt lgkmcnt(0)
	v_mov_b32_e32 v130, v127
	v_mov_b32_e32 v131, v128
	v_mov_b32_e32 v127, v129
	v_pk_add_f32 v[126:127], v[130:131], v[126:127]
	s_nop 0
	v_add_f32_e32 v15, v126, v127
	v_fmamk_f32 v15, v15, 0x3c000000, v250
	v_mul_f32_e32 v126, 0x4b800000, v15
	v_cmp_gt_f32_e32 vcc, s28, v15
	s_nop 1
	v_cndmask_b32_e32 v15, v15, v126, vcc
	v_rsq_f32_e32 v15, v15
	s_nop 0
	v_mul_f32_e32 v126, 0x45800000, v15
	v_cndmask_b32_e32 v126, v15, v126, vcc
	v_pk_mul_f32 v[122:123], v[122:123], v[126:127] op_sel_hi:[1,0]
	v_pk_mul_f32 v[124:125], v[124:125], v[126:127] op_sel_hi:[1,0]
	v_pk_mul_f32 v[118:119], v[118:119], v[126:127] op_sel_hi:[1,0]
	v_pk_mul_f32 v[120:121], v[120:121], v[126:127] op_sel_hi:[1,0]
	v_pk_mul_f32 v[128:129], v[12:13], v[124:125]
	v_pk_mul_f32 v[126:127], v[10:11], v[122:123]
	v_pk_mul_f32 v[132:133], v[20:21], v[120:121]
	v_pk_mul_f32 v[130:131], v[18:19], v[118:119]
	v_mad_i64_i32 v[136:137], s[20:21], v136, s56, v[166:167]
	s_branch .LBB0_298

.LBB0_288:
	s_cmp_gt_i32 s1, 2
	s_mov_b64 s[22:23], -1
	s_cbranch_scc0 .LBB0_290
	v_lshl_add_u64 v[122:123], s[18:19], 2, v[160:161]
	v_mov_b64_e32 v[118:119], v[208:209]
	v_mov_b64_e32 v[120:121], v[210:211]
	s_nop 0
	v_mov_b64_e32 v[122:123], v[216:217]
	v_mov_b64_e32 v[124:125], v[218:219]
	v_lshl_add_u64 v[126:127], s[58:59], 0, v[134:135]
	v_lshl_add_u64 v[126:127], v[126:127], 0, s[18:19]
	v_lshl_add_u64 v[126:127], v[126:127], 0, s[26:27]
	v_lshl_add_u64 v[126:127], v[126:127], 0, v[156:157]
	s_mov_b64 s[22:23], 0
	v_add_f32_e32 v15, v114, v118
	v_add_f32_e32 v118, v110, v122
	v_add_f32_e32 v119, v115, v119
	v_add_f32_e32 v122, v111, v123
	v_mul_f32_e32 v15, 0xbfb8aa3b, v15
	v_mul_f32_e32 v118, 0xbfb8aa3b, v118
	v_add_f32_e32 v120, v116, v120
	v_add_f32_e32 v123, v112, v124
	v_mul_f32_e32 v119, 0xbfb8aa3b, v119
	v_mul_f32_e32 v122, 0xbfb8aa3b, v122
	v_exp_f32_e32 v15, v15
	v_exp_f32_e32 v118, v118
	v_add_f32_e32 v121, v117, v121
	v_add_f32_e32 v124, v113, v125
	v_mul_f32_e32 v120, 0xbfb8aa3b, v120
	v_mul_f32_e32 v123, 0xbfb8aa3b, v123
	v_exp_f32_e32 v119, v119
	v_exp_f32_e32 v122, v122
	v_mul_f32_e32 v121, 0xbfb8aa3b, v121
	v_mul_f32_e32 v124, 0xbfb8aa3b, v124
	v_exp_f32_e32 v120, v120
	v_exp_f32_e32 v123, v123
	v_exp_f32_e32 v121, v121
	v_exp_f32_e32 v124, v124
	v_add_f32_e32 v15, 1.0, v15
	v_add_f32_e32 v118, 1.0, v118
	v_add_f32_e32 v119, 1.0, v119
	v_add_f32_e32 v122, 1.0, v122
	v_rcp_f32_e32 v15, v15
	v_rcp_f32_e32 v118, v118
	v_add_f32_e32 v120, 1.0, v120
	v_add_f32_e32 v123, 1.0, v123
	v_rcp_f32_e32 v119, v119
	v_rcp_f32_e32 v122, v122
	v_add_f32_e32 v121, 1.0, v121
	v_add_f32_e32 v124, 1.0, v124
	v_rcp_f32_e32 v120, v120
	v_rcp_f32_e32 v123, v123
	v_rcp_f32_e32 v121, v121
	v_rcp_f32_e32 v124, v124
	v_mul_f32_e32 v15, 0x437f0000, v15
	v_mul_f32_e32 v118, 0x437f0000, v118
	v_mul_f32_e32 v119, 0x437f0000, v119
	v_mul_f32_e32 v122, 0x437f0000, v122
	v_rndne_f32_e32 v15, v15
	v_rndne_f32_e32 v118, v118
	v_mul_f32_e32 v120, 0x437f0000, v120
	v_mul_f32_e32 v123, 0x437f0000, v123
	v_rndne_f32_e32 v119, v119
	v_rndne_f32_e32 v122, v122
	v_cvt_pk_u8_f32 v15, v15, 0, 0
	v_cvt_pk_u8_f32 v118, v118, 0, 0
	v_mul_f32_e32 v121, 0x437f0000, v121
	v_mul_f32_e32 v124, 0x437f0000, v124
	v_rndne_f32_e32 v120, v120
	v_rndne_f32_e32 v123, v123
	v_cvt_pk_u8_f32 v15, v119, 1, v15
	v_cvt_pk_u8_f32 v118, v122, 1, v118
	v_rndne_f32_e32 v121, v121
	v_rndne_f32_e32 v124, v124
	v_cvt_pk_u8_f32 v15, v120, 2, v15
	v_cvt_pk_u8_f32 v119, v123, 2, v118
	v_cvt_pk_u8_f32 v118, v121, 3, v15
	v_cvt_pk_u8_f32 v119, v124, 3, v119
	global_store_dwordx2 v[126:127], v[118:119], off offset:128

.LBB0_295:
	ds_read_b128 v[118:121], v178 offset:16
	s_waitcnt lgkmcnt(0)
	v_mov_b32_e32 v122, v119
	v_mov_b32_e32 v123, v120
	v_mov_b32_e32 v119, v121
	v_pk_add_f32 v[118:119], v[122:123], v[118:119]
	s_nop 0
	v_add_f32_e32 v15, v118, v119
	v_fmamk_f32 v15, v15, 0x3c000000, v250
	v_mul_f32_e32 v118, 0x4b800000, v15
	v_cmp_gt_f32_e32 vcc, s28, v15
	s_nop 1
	v_cndmask_b32_e32 v15, v15, v118, vcc
	v_rsq_f32_e32 v15, v15
	s_nop 0
	v_mul_f32_e32 v118, 0x45800000, v15
	v_cndmask_b32_e32 v118, v15, v118, vcc
	v_pk_mul_f32 v[114:115], v[114:115], v[118:119] op_sel_hi:[1,0]
	v_pk_mul_f32 v[116:117], v[116:117], v[118:119] op_sel_hi:[1,0]
	v_pk_mul_f32 v[110:111], v[110:111], v[118:119] op_sel_hi:[1,0]
	v_pk_mul_f32 v[112:113], v[112:113], v[118:119] op_sel_hi:[1,0]
	v_pk_mul_f32 v[120:121], v[12:13], v[116:117]
	v_pk_mul_f32 v[118:119], v[10:11], v[114:115]
	v_pk_mul_f32 v[124:125], v[20:21], v[112:113]
	v_pk_mul_f32 v[122:123], v[18:19], v[110:111]
	s_branch .LBB0_301

.LBB0_302:
	v_or_b32_e32 v120, 32, v14
	v_ashrrev_i32_e32 v121, 31, v120
	s_and_b64 vcc, exec, s[46:47]
	v_lshlrev_b64 v[118:119], 13, v[120:121]
	s_cbranch_vccnz .LBB0_320
	s_cmp_gt_i32 s1, 2
	s_mov_b64 s[22:23], -1
	s_cbranch_scc0 .LBB0_305
	v_lshl_add_u64 v[114:115], s[18:19], 2, v[160:161]
	v_mov_b64_e32 v[110:111], v[204:205]
	v_mov_b64_e32 v[112:113], v[206:207]
	s_nop 0
	v_mov_b64_e32 v[114:115], v[200:201]
	v_mov_b64_e32 v[116:117], v[202:203]
	s_mov_b64 s[22:23], 0
	v_add_f32_e32 v110, v102, v110
	v_mul_f32_e32 v110, 0xbfb8aa3b, v110
	v_add_f32_e32 v111, v103, v111
	v_exp_f32_e32 v110, v110
	v_mul_f32_e32 v111, 0xbfb8aa3b, v111
	v_exp_f32_e32 v111, v111
	v_add_f32_e32 v15, v106, v114
	v_add_f32_e32 v110, 1.0, v110
	v_rcp_f32_e32 v110, v110
	v_add_f32_e32 v111, 1.0, v111
	v_rcp_f32_e32 v111, v111
	v_mul_f32_e32 v15, 0xbfb8aa3b, v15
	v_mul_f32_e32 v110, 0x437f0000, v110
	v_rndne_f32_e32 v110, v110
	v_mul_f32_e32 v111, 0x437f0000, v111
	v_cvt_pk_u8_f32 v110, v110, 0, 0
	v_add_f32_e32 v114, v107, v115
	v_rndne_f32_e32 v111, v111
	v_exp_f32_e32 v15, v15
	v_mul_f32_e32 v114, 0xbfb8aa3b, v114
	v_cvt_pk_u8_f32 v110, v111, 1, v110
	v_add_f32_e32 v111, v108, v116
	v_exp_f32_e32 v114, v114
	v_mul_f32_e32 v111, 0xbfb8aa3b, v111
	v_exp_f32_e32 v111, v111
	v_add_f32_e32 v15, 1.0, v15
	v_rcp_f32_e32 v15, v15
	v_add_f32_e32 v114, 1.0, v114
	v_rcp_f32_e32 v114, v114
	v_add_f32_e32 v111, 1.0, v111
	v_rcp_f32_e32 v111, v111
	v_mul_f32_e32 v15, 0x437f0000, v15
	v_rndne_f32_e32 v15, v15
	v_mul_f32_e32 v114, 0x437f0000, v114
	v_cvt_pk_u8_f32 v15, v15, 0, 0
	v_rndne_f32_e32 v114, v114
	v_mul_f32_e32 v111, 0x437f0000, v111
	v_cvt_pk_u8_f32 v15, v114, 1, v15
	v_rndne_f32_e32 v111, v111
	v_cvt_pk_u8_f32 v15, v111, 2, v15
	v_add_f32_e32 v111, v104, v112
	v_mul_f32_e32 v111, 0xbfb8aa3b, v111
	v_exp_f32_e32 v111, v111
	s_nop 0
	v_add_f32_e32 v111, 1.0, v111
	v_rcp_f32_e32 v111, v111
	s_nop 0
	v_mul_f32_e32 v111, 0x437f0000, v111
	v_rndne_f32_e32 v111, v111
	v_cvt_pk_u8_f32 v111, v111, 2, v110
	v_add_f32_e32 v110, v109, v117
	v_mul_f32_e32 v110, 0xbfb8aa3b, v110
	v_exp_f32_e32 v110, v110
	s_nop 0
	v_add_f32_e32 v110, 1.0, v110
	v_rcp_f32_e32 v110, v110
	s_nop 0
	v_mul_f32_e32 v110, 0x437f0000, v110
	v_rndne_f32_e32 v110, v110
	v_cvt_pk_u8_f32 v110, v110, 3, v15
	v_add_f32_e32 v15, v105, v113
	v_mul_f32_e32 v15, 0xbfb8aa3b, v15
	v_exp_f32_e32 v15, v15
	v_lshl_add_u64 v[112:113], s[58:59], 0, v[118:119]
	v_lshl_add_u64 v[112:113], v[112:113], 0, s[18:19]
	v_lshl_add_u64 v[112:113], v[112:113], 0, s[26:27]
	v_add_f32_e32 v15, 1.0, v15
	v_rcp_f32_e32 v15, v15
	v_lshl_add_u64 v[112:113], v[112:113], 0, v[156:157]
	v_mul_f32_e32 v15, 0x437f0000, v15
	v_rndne_f32_e32 v15, v15
	v_cvt_pk_u8_f32 v111, v15, 3, v111
	global_store_dwordx2 v[112:113], v[110:111], off

.LBB0_310:
	ds_read_b128 v[110:113], v181
	s_waitcnt lgkmcnt(0)
	v_mov_b32_e32 v114, v111
	v_mov_b32_e32 v115, v112
	v_mov_b32_e32 v111, v113
	v_pk_add_f32 v[110:111], v[114:115], v[110:111]
	s_nop 0
	v_add_f32_e32 v15, v110, v111
	v_fmamk_f32 v15, v15, 0x3c000000, v250
	v_mul_f32_e32 v110, 0x4b800000, v15
	v_cmp_gt_f32_e32 vcc, s28, v15
	s_nop 1
	v_cndmask_b32_e32 v15, v15, v110, vcc
	v_rsq_f32_e32 v15, v15
	s_nop 0
	v_mul_f32_e32 v110, 0x45800000, v15
	v_cndmask_b32_e32 v110, v15, v110, vcc
	v_pk_mul_f32 v[106:107], v[106:107], v[110:111] op_sel_hi:[1,0]
	v_pk_mul_f32 v[108:109], v[108:109], v[110:111] op_sel_hi:[1,0]
	v_pk_mul_f32 v[102:103], v[102:103], v[110:111] op_sel_hi:[1,0]
	v_pk_mul_f32 v[104:105], v[104:105], v[110:111] op_sel_hi:[1,0]
	v_pk_mul_f32 v[112:113], v[12:13], v[108:109]
	v_pk_mul_f32 v[110:111], v[10:11], v[106:107]
	v_pk_mul_f32 v[116:117], v[20:21], v[104:105]
	v_pk_mul_f32 v[114:115], v[18:19], v[102:103]
	v_mad_i64_i32 v[120:121], s[20:21], v120, s56, v[166:167]
	s_branch .LBB0_322

.LBB0_312:
	s_cmp_gt_i32 s1, 2
	s_mov_b64 s[22:23], -1
	s_cbranch_scc0 .LBB0_314
	v_lshl_add_u64 v[106:107], s[18:19], 2, v[160:161]
	v_mov_b64_e32 v[102:103], v[208:209]
	v_mov_b64_e32 v[104:105], v[210:211]
	s_nop 0
	v_mov_b64_e32 v[106:107], v[216:217]
	v_mov_b64_e32 v[108:109], v[218:219]
	v_lshl_add_u64 v[110:111], s[58:59], 0, v[118:119]
	v_lshl_add_u64 v[110:111], v[110:111], 0, s[18:19]
	v_lshl_add_u64 v[110:111], v[110:111], 0, s[26:27]
	v_lshl_add_u64 v[110:111], v[110:111], 0, v[156:157]
	s_mov_b64 s[22:23], 0
	v_add_f32_e32 v15, v98, v102
	v_add_f32_e32 v102, v94, v106
	v_add_f32_e32 v103, v99, v103
	v_add_f32_e32 v106, v95, v107
	v_mul_f32_e32 v15, 0xbfb8aa3b, v15
	v_mul_f32_e32 v102, 0xbfb8aa3b, v102
	v_add_f32_e32 v104, v100, v104
	v_add_f32_e32 v107, v96, v108
	v_mul_f32_e32 v103, 0xbfb8aa3b, v103
	v_mul_f32_e32 v106, 0xbfb8aa3b, v106
	v_exp_f32_e32 v15, v15
	v_exp_f32_e32 v102, v102
	v_add_f32_e32 v105, v101, v105
	v_add_f32_e32 v108, v97, v109
	v_mul_f32_e32 v104, 0xbfb8aa3b, v104
	v_mul_f32_e32 v107, 0xbfb8aa3b, v107
	v_exp_f32_e32 v103, v103
	v_exp_f32_e32 v106, v106
	v_mul_f32_e32 v105, 0xbfb8aa3b, v105
	v_mul_f32_e32 v108, 0xbfb8aa3b, v108
	v_exp_f32_e32 v104, v104
	v_exp_f32_e32 v107, v107
	v_exp_f32_e32 v105, v105
	v_exp_f32_e32 v108, v108
	v_add_f32_e32 v15, 1.0, v15
	v_add_f32_e32 v102, 1.0, v102
	v_add_f32_e32 v103, 1.0, v103
	v_add_f32_e32 v106, 1.0, v106
	v_rcp_f32_e32 v15, v15
	v_rcp_f32_e32 v102, v102
	v_add_f32_e32 v104, 1.0, v104
	v_add_f32_e32 v107, 1.0, v107
	v_rcp_f32_e32 v103, v103
	v_rcp_f32_e32 v106, v106
	v_add_f32_e32 v105, 1.0, v105
	v_add_f32_e32 v108, 1.0, v108
	v_rcp_f32_e32 v104, v104
	v_rcp_f32_e32 v107, v107
	v_rcp_f32_e32 v105, v105
	v_rcp_f32_e32 v108, v108
	v_mul_f32_e32 v15, 0x437f0000, v15
	v_mul_f32_e32 v102, 0x437f0000, v102
	v_mul_f32_e32 v103, 0x437f0000, v103
	v_mul_f32_e32 v106, 0x437f0000, v106
	v_rndne_f32_e32 v15, v15
	v_rndne_f32_e32 v102, v102
	v_mul_f32_e32 v104, 0x437f0000, v104
	v_mul_f32_e32 v107, 0x437f0000, v107
	v_rndne_f32_e32 v103, v103
	v_rndne_f32_e32 v106, v106
	v_cvt_pk_u8_f32 v15, v15, 0, 0
	v_cvt_pk_u8_f32 v102, v102, 0, 0
	v_mul_f32_e32 v105, 0x437f0000, v105
	v_mul_f32_e32 v108, 0x437f0000, v108
	v_rndne_f32_e32 v104, v104
	v_rndne_f32_e32 v107, v107
	v_cvt_pk_u8_f32 v15, v103, 1, v15
	v_cvt_pk_u8_f32 v102, v106, 1, v102
	v_rndne_f32_e32 v105, v105
	v_rndne_f32_e32 v108, v108
	v_cvt_pk_u8_f32 v15, v104, 2, v15
	v_cvt_pk_u8_f32 v103, v107, 2, v102
	v_cvt_pk_u8_f32 v102, v105, 3, v15
	v_cvt_pk_u8_f32 v103, v108, 3, v103
	global_store_dwordx2 v[110:111], v[102:103], off offset:128

.LBB0_319:
	ds_read_b128 v[102:105], v181 offset:16
	s_waitcnt lgkmcnt(0)
	v_mov_b32_e32 v106, v103
	v_mov_b32_e32 v107, v104
	v_mov_b32_e32 v103, v105
	v_pk_add_f32 v[102:103], v[106:107], v[102:103]
	s_nop 0
	v_add_f32_e32 v15, v102, v103
	v_fmamk_f32 v15, v15, 0x3c000000, v250
	v_mul_f32_e32 v102, 0x4b800000, v15
	v_cmp_gt_f32_e32 vcc, s28, v15
	s_nop 1
	v_cndmask_b32_e32 v15, v15, v102, vcc
	v_rsq_f32_e32 v15, v15
	s_nop 0
	v_mul_f32_e32 v102, 0x45800000, v15
	v_cndmask_b32_e32 v102, v15, v102, vcc
	v_pk_mul_f32 v[98:99], v[98:99], v[102:103] op_sel_hi:[1,0]
	v_pk_mul_f32 v[100:101], v[100:101], v[102:103] op_sel_hi:[1,0]
	v_pk_mul_f32 v[94:95], v[94:95], v[102:103] op_sel_hi:[1,0]
	v_pk_mul_f32 v[96:97], v[96:97], v[102:103] op_sel_hi:[1,0]
	v_pk_mul_f32 v[104:105], v[12:13], v[100:101]
	v_pk_mul_f32 v[102:103], v[10:11], v[98:99]
	v_pk_mul_f32 v[108:109], v[20:21], v[96:97]
	v_pk_mul_f32 v[106:107], v[18:19], v[94:95]
	s_branch .LBB0_325

.LBB0_326:
	v_or_b32_e32 v104, 48, v14
	v_ashrrev_i32_e32 v105, 31, v104
	s_and_b64 vcc, exec, s[46:47]
	v_lshlrev_b64 v[102:103], 13, v[104:105]
	s_cbranch_vccnz .LBB0_344
	s_cmp_gt_i32 s1, 2
	s_mov_b64 s[22:23], -1
	s_cbranch_scc0 .LBB0_329
	v_lshl_add_u64 v[98:99], s[18:19], 2, v[160:161]
	v_mov_b64_e32 v[94:95], v[204:205]
	v_mov_b64_e32 v[96:97], v[206:207]
	s_nop 0
	v_mov_b64_e32 v[98:99], v[200:201]
	v_mov_b64_e32 v[100:101], v[202:203]
	s_mov_b64 s[22:23], 0
	v_add_f32_e32 v94, v86, v94
	v_mul_f32_e32 v94, 0xbfb8aa3b, v94
	v_add_f32_e32 v95, v87, v95
	v_exp_f32_e32 v94, v94
	v_mul_f32_e32 v95, 0xbfb8aa3b, v95
	v_exp_f32_e32 v95, v95
	v_add_f32_e32 v15, v90, v98
	v_add_f32_e32 v94, 1.0, v94
	v_rcp_f32_e32 v94, v94
	v_add_f32_e32 v95, 1.0, v95
	v_rcp_f32_e32 v95, v95
	v_mul_f32_e32 v15, 0xbfb8aa3b, v15
	v_mul_f32_e32 v94, 0x437f0000, v94
	v_rndne_f32_e32 v94, v94
	v_mul_f32_e32 v95, 0x437f0000, v95
	v_cvt_pk_u8_f32 v94, v94, 0, 0
	v_add_f32_e32 v98, v91, v99
	v_rndne_f32_e32 v95, v95
	v_exp_f32_e32 v15, v15
	v_mul_f32_e32 v98, 0xbfb8aa3b, v98
	v_cvt_pk_u8_f32 v94, v95, 1, v94
	v_add_f32_e32 v95, v92, v100
	v_exp_f32_e32 v98, v98
	v_mul_f32_e32 v95, 0xbfb8aa3b, v95
	v_exp_f32_e32 v95, v95
	v_add_f32_e32 v15, 1.0, v15
	v_rcp_f32_e32 v15, v15
	v_add_f32_e32 v98, 1.0, v98
	v_rcp_f32_e32 v98, v98
	v_add_f32_e32 v95, 1.0, v95
	v_rcp_f32_e32 v95, v95
	v_mul_f32_e32 v15, 0x437f0000, v15
	v_rndne_f32_e32 v15, v15
	v_mul_f32_e32 v98, 0x437f0000, v98
	v_cvt_pk_u8_f32 v15, v15, 0, 0
	v_rndne_f32_e32 v98, v98
	v_mul_f32_e32 v95, 0x437f0000, v95
	v_cvt_pk_u8_f32 v15, v98, 1, v15
	v_rndne_f32_e32 v95, v95
	v_cvt_pk_u8_f32 v15, v95, 2, v15
	v_add_f32_e32 v95, v88, v96
	v_mul_f32_e32 v95, 0xbfb8aa3b, v95
	v_exp_f32_e32 v95, v95
	s_nop 0
	v_add_f32_e32 v95, 1.0, v95
	v_rcp_f32_e32 v95, v95
	s_nop 0
	v_mul_f32_e32 v95, 0x437f0000, v95
	v_rndne_f32_e32 v95, v95
	v_cvt_pk_u8_f32 v95, v95, 2, v94
	v_add_f32_e32 v94, v93, v101
	v_mul_f32_e32 v94, 0xbfb8aa3b, v94
	v_exp_f32_e32 v94, v94
	s_nop 0
	v_add_f32_e32 v94, 1.0, v94
	v_rcp_f32_e32 v94, v94
	s_nop 0
	v_mul_f32_e32 v94, 0x437f0000, v94
	v_rndne_f32_e32 v94, v94
	v_cvt_pk_u8_f32 v94, v94, 3, v15
	v_add_f32_e32 v15, v89, v97
	v_mul_f32_e32 v15, 0xbfb8aa3b, v15
	v_exp_f32_e32 v15, v15
	v_lshl_add_u64 v[96:97], s[58:59], 0, v[102:103]
	v_lshl_add_u64 v[96:97], v[96:97], 0, s[18:19]
	v_lshl_add_u64 v[96:97], v[96:97], 0, s[26:27]
	v_add_f32_e32 v15, 1.0, v15
	v_rcp_f32_e32 v15, v15
	v_lshl_add_u64 v[96:97], v[96:97], 0, v[156:157]
	v_mul_f32_e32 v15, 0x437f0000, v15
	v_rndne_f32_e32 v15, v15
	v_cvt_pk_u8_f32 v95, v15, 3, v95
	global_store_dwordx2 v[96:97], v[94:95], off

.LBB0_334:
	ds_read_b128 v[94:97], v184
	s_waitcnt lgkmcnt(0)
	v_mov_b32_e32 v98, v95
	v_mov_b32_e32 v99, v96
	v_mov_b32_e32 v95, v97
	v_pk_add_f32 v[94:95], v[98:99], v[94:95]
	s_nop 0
	v_add_f32_e32 v15, v94, v95
	v_fmamk_f32 v15, v15, 0x3c000000, v250
	v_mul_f32_e32 v94, 0x4b800000, v15
	v_cmp_gt_f32_e32 vcc, s28, v15
	s_nop 1
	v_cndmask_b32_e32 v15, v15, v94, vcc
	v_rsq_f32_e32 v15, v15
	s_nop 0
	v_mul_f32_e32 v94, 0x45800000, v15
	v_cndmask_b32_e32 v94, v15, v94, vcc
	v_pk_mul_f32 v[90:91], v[90:91], v[94:95] op_sel_hi:[1,0]
	v_pk_mul_f32 v[92:93], v[92:93], v[94:95] op_sel_hi:[1,0]
	v_pk_mul_f32 v[86:87], v[86:87], v[94:95] op_sel_hi:[1,0]
	v_pk_mul_f32 v[88:89], v[88:89], v[94:95] op_sel_hi:[1,0]
	v_pk_mul_f32 v[96:97], v[12:13], v[92:93]
	v_pk_mul_f32 v[94:95], v[10:11], v[90:91]
	v_pk_mul_f32 v[100:101], v[20:21], v[88:89]
	v_pk_mul_f32 v[98:99], v[18:19], v[86:87]
	v_mad_i64_i32 v[104:105], s[20:21], v104, s56, v[166:167]
	s_branch .LBB0_346

.LBB0_336:
	s_cmp_gt_i32 s1, 2
	s_mov_b64 s[22:23], -1
	s_cbranch_scc0 .LBB0_338
	v_lshl_add_u64 v[90:91], s[18:19], 2, v[160:161]
	v_mov_b64_e32 v[86:87], v[208:209]
	v_mov_b64_e32 v[88:89], v[210:211]
	s_nop 0
	v_mov_b64_e32 v[90:91], v[216:217]
	v_mov_b64_e32 v[92:93], v[218:219]
	v_lshl_add_u64 v[94:95], s[58:59], 0, v[102:103]
	v_lshl_add_u64 v[94:95], v[94:95], 0, s[18:19]
	v_lshl_add_u64 v[94:95], v[94:95], 0, s[26:27]
	v_lshl_add_u64 v[94:95], v[94:95], 0, v[156:157]
	s_mov_b64 s[22:23], 0
	v_add_f32_e32 v15, v82, v86
	v_add_f32_e32 v86, v78, v90
	v_add_f32_e32 v87, v83, v87
	v_add_f32_e32 v90, v79, v91
	v_mul_f32_e32 v15, 0xbfb8aa3b, v15
	v_mul_f32_e32 v86, 0xbfb8aa3b, v86
	v_add_f32_e32 v88, v84, v88
	v_add_f32_e32 v91, v80, v92
	v_mul_f32_e32 v87, 0xbfb8aa3b, v87
	v_mul_f32_e32 v90, 0xbfb8aa3b, v90
	v_exp_f32_e32 v15, v15
	v_exp_f32_e32 v86, v86
	v_add_f32_e32 v89, v85, v89
	v_add_f32_e32 v92, v81, v93
	v_mul_f32_e32 v88, 0xbfb8aa3b, v88
	v_mul_f32_e32 v91, 0xbfb8aa3b, v91
	v_exp_f32_e32 v87, v87
	v_exp_f32_e32 v90, v90
	v_mul_f32_e32 v89, 0xbfb8aa3b, v89
	v_mul_f32_e32 v92, 0xbfb8aa3b, v92
	v_exp_f32_e32 v88, v88
	v_exp_f32_e32 v91, v91
	v_exp_f32_e32 v89, v89
	v_exp_f32_e32 v92, v92
	v_add_f32_e32 v15, 1.0, v15
	v_add_f32_e32 v86, 1.0, v86
	v_add_f32_e32 v87, 1.0, v87
	v_add_f32_e32 v90, 1.0, v90
	v_rcp_f32_e32 v15, v15
	v_rcp_f32_e32 v86, v86
	v_add_f32_e32 v88, 1.0, v88
	v_add_f32_e32 v91, 1.0, v91
	v_rcp_f32_e32 v87, v87
	v_rcp_f32_e32 v90, v90
	v_add_f32_e32 v89, 1.0, v89
	v_add_f32_e32 v92, 1.0, v92
	v_rcp_f32_e32 v88, v88
	v_rcp_f32_e32 v91, v91
	v_rcp_f32_e32 v89, v89
	v_rcp_f32_e32 v92, v92
	v_mul_f32_e32 v15, 0x437f0000, v15
	v_mul_f32_e32 v86, 0x437f0000, v86
	v_mul_f32_e32 v87, 0x437f0000, v87
	v_mul_f32_e32 v90, 0x437f0000, v90
	v_rndne_f32_e32 v15, v15
	v_rndne_f32_e32 v86, v86
	v_mul_f32_e32 v88, 0x437f0000, v88
	v_mul_f32_e32 v91, 0x437f0000, v91
	v_rndne_f32_e32 v87, v87
	v_rndne_f32_e32 v90, v90
	v_cvt_pk_u8_f32 v15, v15, 0, 0
	v_cvt_pk_u8_f32 v86, v86, 0, 0
	v_mul_f32_e32 v89, 0x437f0000, v89
	v_mul_f32_e32 v92, 0x437f0000, v92
	v_rndne_f32_e32 v88, v88
	v_rndne_f32_e32 v91, v91
	v_cvt_pk_u8_f32 v15, v87, 1, v15
	v_cvt_pk_u8_f32 v86, v90, 1, v86
	v_rndne_f32_e32 v89, v89
	v_rndne_f32_e32 v92, v92
	v_cvt_pk_u8_f32 v15, v88, 2, v15
	v_cvt_pk_u8_f32 v87, v91, 2, v86
	v_cvt_pk_u8_f32 v86, v89, 3, v15
	v_cvt_pk_u8_f32 v87, v92, 3, v87
	global_store_dwordx2 v[94:95], v[86:87], off offset:128

.LBB0_343:
	ds_read_b128 v[86:89], v184 offset:16
	s_waitcnt lgkmcnt(0)
	v_mov_b32_e32 v90, v87
	v_mov_b32_e32 v91, v88
	v_mov_b32_e32 v87, v89
	v_pk_add_f32 v[86:87], v[90:91], v[86:87]
	s_nop 0
	v_add_f32_e32 v15, v86, v87
	v_fmamk_f32 v15, v15, 0x3c000000, v250
	v_mul_f32_e32 v86, 0x4b800000, v15
	v_cmp_gt_f32_e32 vcc, s28, v15
	s_nop 1
	v_cndmask_b32_e32 v15, v15, v86, vcc
	v_rsq_f32_e32 v15, v15
	s_nop 0
	v_mul_f32_e32 v86, 0x45800000, v15
	v_cndmask_b32_e32 v86, v15, v86, vcc
	v_pk_mul_f32 v[82:83], v[82:83], v[86:87] op_sel_hi:[1,0]
	v_pk_mul_f32 v[84:85], v[84:85], v[86:87] op_sel_hi:[1,0]
	v_pk_mul_f32 v[78:79], v[78:79], v[86:87] op_sel_hi:[1,0]
	v_pk_mul_f32 v[80:81], v[80:81], v[86:87] op_sel_hi:[1,0]
	v_pk_mul_f32 v[88:89], v[12:13], v[84:85]
	v_pk_mul_f32 v[86:87], v[10:11], v[82:83]
	v_pk_mul_f32 v[92:93], v[20:21], v[80:81]
	v_pk_mul_f32 v[90:91], v[18:19], v[78:79]
	s_branch .LBB0_349

.LBB0_350:
	v_add_u32_e32 v88, 0x80, v14
	v_ashrrev_i32_e32 v89, 31, v88
	s_and_b64 vcc, exec, s[46:47]
	v_lshlrev_b64 v[86:87], 13, v[88:89]
	s_cbranch_vccnz .LBB0_368
	s_cmp_gt_i32 s1, 2
	s_mov_b64 s[22:23], -1
	s_cbranch_scc0 .LBB0_353
	v_lshl_add_u64 v[82:83], s[18:19], 2, v[160:161]
	v_mov_b64_e32 v[78:79], v[204:205]
	v_mov_b64_e32 v[80:81], v[206:207]
	s_nop 0
	v_mov_b64_e32 v[82:83], v[200:201]
	v_mov_b64_e32 v[84:85], v[202:203]
	s_mov_b64 s[22:23], 0
	v_add_f32_e32 v78, v70, v78
	v_mul_f32_e32 v78, 0xbfb8aa3b, v78
	v_add_f32_e32 v79, v71, v79
	v_exp_f32_e32 v78, v78
	v_mul_f32_e32 v79, 0xbfb8aa3b, v79
	v_exp_f32_e32 v79, v79
	v_add_f32_e32 v15, v74, v82
	v_add_f32_e32 v78, 1.0, v78
	v_rcp_f32_e32 v78, v78
	v_add_f32_e32 v79, 1.0, v79
	v_rcp_f32_e32 v79, v79
	v_mul_f32_e32 v15, 0xbfb8aa3b, v15
	v_mul_f32_e32 v78, 0x437f0000, v78
	v_rndne_f32_e32 v78, v78
	v_mul_f32_e32 v79, 0x437f0000, v79
	v_cvt_pk_u8_f32 v78, v78, 0, 0
	v_add_f32_e32 v82, v75, v83
	v_rndne_f32_e32 v79, v79
	v_exp_f32_e32 v15, v15
	v_mul_f32_e32 v82, 0xbfb8aa3b, v82
	v_cvt_pk_u8_f32 v78, v79, 1, v78
	v_add_f32_e32 v79, v76, v84
	v_exp_f32_e32 v82, v82
	v_mul_f32_e32 v79, 0xbfb8aa3b, v79
	v_exp_f32_e32 v79, v79
	v_add_f32_e32 v15, 1.0, v15
	v_rcp_f32_e32 v15, v15
	v_add_f32_e32 v82, 1.0, v82
	v_rcp_f32_e32 v82, v82
	v_add_f32_e32 v79, 1.0, v79
	v_rcp_f32_e32 v79, v79
	v_mul_f32_e32 v15, 0x437f0000, v15
	v_rndne_f32_e32 v15, v15
	v_mul_f32_e32 v82, 0x437f0000, v82
	v_cvt_pk_u8_f32 v15, v15, 0, 0
	v_rndne_f32_e32 v82, v82
	v_mul_f32_e32 v79, 0x437f0000, v79
	v_cvt_pk_u8_f32 v15, v82, 1, v15
	v_rndne_f32_e32 v79, v79
	v_cvt_pk_u8_f32 v15, v79, 2, v15
	v_add_f32_e32 v79, v72, v80
	v_mul_f32_e32 v79, 0xbfb8aa3b, v79
	v_exp_f32_e32 v79, v79
	s_nop 0
	v_add_f32_e32 v79, 1.0, v79
	v_rcp_f32_e32 v79, v79
	s_nop 0
	v_mul_f32_e32 v79, 0x437f0000, v79
	v_rndne_f32_e32 v79, v79
	v_cvt_pk_u8_f32 v79, v79, 2, v78
	v_add_f32_e32 v78, v77, v85
	v_mul_f32_e32 v78, 0xbfb8aa3b, v78
	v_exp_f32_e32 v78, v78
	s_nop 0
	v_add_f32_e32 v78, 1.0, v78
	v_rcp_f32_e32 v78, v78
	s_nop 0
	v_mul_f32_e32 v78, 0x437f0000, v78
	v_rndne_f32_e32 v78, v78
	v_cvt_pk_u8_f32 v78, v78, 3, v15
	v_add_f32_e32 v15, v73, v81
	v_mul_f32_e32 v15, 0xbfb8aa3b, v15
	v_exp_f32_e32 v15, v15
	v_lshl_add_u64 v[80:81], s[58:59], 0, v[86:87]
	v_lshl_add_u64 v[80:81], v[80:81], 0, s[18:19]
	v_lshl_add_u64 v[80:81], v[80:81], 0, s[26:27]
	v_add_f32_e32 v15, 1.0, v15
	v_rcp_f32_e32 v15, v15
	v_lshl_add_u64 v[80:81], v[80:81], 0, v[156:157]
	v_mul_f32_e32 v15, 0x437f0000, v15
	v_rndne_f32_e32 v15, v15
	v_cvt_pk_u8_f32 v79, v15, 3, v79
	global_store_dwordx2 v[80:81], v[78:79], off

.LBB0_358:
	ds_read_b128 v[78:81], v187
	s_waitcnt lgkmcnt(0)
	v_mov_b32_e32 v82, v79
	v_mov_b32_e32 v83, v80
	v_mov_b32_e32 v79, v81
	v_pk_add_f32 v[78:79], v[82:83], v[78:79]
	s_nop 0
	v_add_f32_e32 v15, v78, v79
	v_fmamk_f32 v15, v15, 0x3c000000, v250
	v_mul_f32_e32 v78, 0x4b800000, v15
	v_cmp_gt_f32_e32 vcc, s28, v15
	s_nop 1
	v_cndmask_b32_e32 v15, v15, v78, vcc
	v_rsq_f32_e32 v15, v15
	s_nop 0
	v_mul_f32_e32 v78, 0x45800000, v15
	v_cndmask_b32_e32 v78, v15, v78, vcc
	v_pk_mul_f32 v[74:75], v[74:75], v[78:79] op_sel_hi:[1,0]
	v_pk_mul_f32 v[76:77], v[76:77], v[78:79] op_sel_hi:[1,0]
	v_pk_mul_f32 v[70:71], v[70:71], v[78:79] op_sel_hi:[1,0]
	v_pk_mul_f32 v[72:73], v[72:73], v[78:79] op_sel_hi:[1,0]
	v_pk_mul_f32 v[80:81], v[12:13], v[76:77]
	v_pk_mul_f32 v[78:79], v[10:11], v[74:75]
	v_pk_mul_f32 v[84:85], v[20:21], v[72:73]
	v_pk_mul_f32 v[82:83], v[18:19], v[70:71]
	v_mad_i64_i32 v[88:89], s[20:21], v88, s56, v[166:167]
	s_branch .LBB0_370

.LBB0_360:
	s_cmp_gt_i32 s1, 2
	s_mov_b64 s[22:23], -1
	s_cbranch_scc0 .LBB0_362
	v_lshl_add_u64 v[74:75], s[18:19], 2, v[160:161]
	v_mov_b64_e32 v[70:71], v[208:209]
	v_mov_b64_e32 v[72:73], v[210:211]
	s_nop 0
	v_mov_b64_e32 v[74:75], v[216:217]
	v_mov_b64_e32 v[76:77], v[218:219]
	v_lshl_add_u64 v[78:79], s[58:59], 0, v[86:87]
	v_lshl_add_u64 v[78:79], v[78:79], 0, s[18:19]
	v_lshl_add_u64 v[78:79], v[78:79], 0, s[26:27]
	v_lshl_add_u64 v[78:79], v[78:79], 0, v[156:157]
	s_mov_b64 s[22:23], 0
	v_add_f32_e32 v15, v66, v70
	v_add_f32_e32 v70, v62, v74
	v_add_f32_e32 v71, v67, v71
	v_add_f32_e32 v74, v63, v75
	v_mul_f32_e32 v15, 0xbfb8aa3b, v15
	v_mul_f32_e32 v70, 0xbfb8aa3b, v70
	v_add_f32_e32 v72, v68, v72
	v_add_f32_e32 v75, v64, v76
	v_mul_f32_e32 v71, 0xbfb8aa3b, v71
	v_mul_f32_e32 v74, 0xbfb8aa3b, v74
	v_exp_f32_e32 v15, v15
	v_exp_f32_e32 v70, v70
	v_add_f32_e32 v73, v69, v73
	v_add_f32_e32 v76, v65, v77
	v_mul_f32_e32 v72, 0xbfb8aa3b, v72
	v_mul_f32_e32 v75, 0xbfb8aa3b, v75
	v_exp_f32_e32 v71, v71
	v_exp_f32_e32 v74, v74
	v_mul_f32_e32 v73, 0xbfb8aa3b, v73
	v_mul_f32_e32 v76, 0xbfb8aa3b, v76
	v_exp_f32_e32 v72, v72
	v_exp_f32_e32 v75, v75
	v_exp_f32_e32 v73, v73
	v_exp_f32_e32 v76, v76
	v_add_f32_e32 v15, 1.0, v15
	v_add_f32_e32 v70, 1.0, v70
	v_add_f32_e32 v71, 1.0, v71
	v_add_f32_e32 v74, 1.0, v74
	v_rcp_f32_e32 v15, v15
	v_rcp_f32_e32 v70, v70
	v_add_f32_e32 v72, 1.0, v72
	v_add_f32_e32 v75, 1.0, v75
	v_rcp_f32_e32 v71, v71
	v_rcp_f32_e32 v74, v74
	v_add_f32_e32 v73, 1.0, v73
	v_add_f32_e32 v76, 1.0, v76
	v_rcp_f32_e32 v72, v72
	v_rcp_f32_e32 v75, v75
	v_rcp_f32_e32 v73, v73
	v_rcp_f32_e32 v76, v76
	v_mul_f32_e32 v15, 0x437f0000, v15
	v_mul_f32_e32 v70, 0x437f0000, v70
	v_mul_f32_e32 v71, 0x437f0000, v71
	v_mul_f32_e32 v74, 0x437f0000, v74
	v_rndne_f32_e32 v15, v15
	v_rndne_f32_e32 v70, v70
	v_mul_f32_e32 v72, 0x437f0000, v72
	v_mul_f32_e32 v75, 0x437f0000, v75
	v_rndne_f32_e32 v71, v71
	v_rndne_f32_e32 v74, v74
	v_cvt_pk_u8_f32 v15, v15, 0, 0
	v_cvt_pk_u8_f32 v70, v70, 0, 0
	v_mul_f32_e32 v73, 0x437f0000, v73
	v_mul_f32_e32 v76, 0x437f0000, v76
	v_rndne_f32_e32 v72, v72
	v_rndne_f32_e32 v75, v75
	v_cvt_pk_u8_f32 v15, v71, 1, v15
	v_cvt_pk_u8_f32 v70, v74, 1, v70
	v_rndne_f32_e32 v73, v73
	v_rndne_f32_e32 v76, v76
	v_cvt_pk_u8_f32 v15, v72, 2, v15
	v_cvt_pk_u8_f32 v71, v75, 2, v70
	v_cvt_pk_u8_f32 v70, v73, 3, v15
	v_cvt_pk_u8_f32 v71, v76, 3, v71
	global_store_dwordx2 v[78:79], v[70:71], off offset:128

.LBB0_367:
	ds_read_b128 v[70:73], v187 offset:16
	s_waitcnt lgkmcnt(0)
	v_mov_b32_e32 v74, v71
	v_mov_b32_e32 v75, v72
	v_mov_b32_e32 v71, v73
	v_pk_add_f32 v[70:71], v[74:75], v[70:71]
	s_nop 0
	v_add_f32_e32 v15, v70, v71
	v_fmamk_f32 v15, v15, 0x3c000000, v250
	v_mul_f32_e32 v70, 0x4b800000, v15
	v_cmp_gt_f32_e32 vcc, s28, v15
	s_nop 1
	v_cndmask_b32_e32 v15, v15, v70, vcc
	v_rsq_f32_e32 v15, v15
	s_nop 0
	v_mul_f32_e32 v70, 0x45800000, v15
	v_cndmask_b32_e32 v70, v15, v70, vcc
	v_pk_mul_f32 v[66:67], v[66:67], v[70:71] op_sel_hi:[1,0]
	v_pk_mul_f32 v[68:69], v[68:69], v[70:71] op_sel_hi:[1,0]
	v_pk_mul_f32 v[62:63], v[62:63], v[70:71] op_sel_hi:[1,0]
	v_pk_mul_f32 v[64:65], v[64:65], v[70:71] op_sel_hi:[1,0]
	v_pk_mul_f32 v[72:73], v[12:13], v[68:69]
	v_pk_mul_f32 v[70:71], v[10:11], v[66:67]
	v_pk_mul_f32 v[76:77], v[20:21], v[64:65]
	v_pk_mul_f32 v[74:75], v[18:19], v[62:63]
	s_branch .LBB0_373

.LBB0_374:
	v_add_u32_e32 v72, 0x90, v14
	v_ashrrev_i32_e32 v73, 31, v72
	s_and_b64 vcc, exec, s[46:47]
	v_lshlrev_b64 v[70:71], 13, v[72:73]
	s_cbranch_vccnz .LBB0_392
	s_cmp_gt_i32 s1, 2
	s_mov_b64 s[22:23], -1
	s_cbranch_scc0 .LBB0_377
	v_lshl_add_u64 v[66:67], s[18:19], 2, v[160:161]
	v_mov_b64_e32 v[62:63], v[204:205]
	v_mov_b64_e32 v[64:65], v[206:207]
	s_nop 0
	v_mov_b64_e32 v[66:67], v[200:201]
	v_mov_b64_e32 v[68:69], v[202:203]
	s_mov_b64 s[22:23], 0
	v_add_f32_e32 v62, v54, v62
	v_mul_f32_e32 v62, 0xbfb8aa3b, v62
	v_add_f32_e32 v63, v55, v63
	v_exp_f32_e32 v62, v62
	v_mul_f32_e32 v63, 0xbfb8aa3b, v63
	v_exp_f32_e32 v63, v63
	v_add_f32_e32 v15, v58, v66
	v_add_f32_e32 v62, 1.0, v62
	v_rcp_f32_e32 v62, v62
	v_add_f32_e32 v63, 1.0, v63
	v_rcp_f32_e32 v63, v63
	v_mul_f32_e32 v15, 0xbfb8aa3b, v15
	v_mul_f32_e32 v62, 0x437f0000, v62
	v_rndne_f32_e32 v62, v62
	v_mul_f32_e32 v63, 0x437f0000, v63
	v_cvt_pk_u8_f32 v62, v62, 0, 0
	v_add_f32_e32 v66, v59, v67
	v_rndne_f32_e32 v63, v63
	v_exp_f32_e32 v15, v15
	v_mul_f32_e32 v66, 0xbfb8aa3b, v66
	v_cvt_pk_u8_f32 v62, v63, 1, v62
	v_add_f32_e32 v63, v60, v68
	v_exp_f32_e32 v66, v66
	v_mul_f32_e32 v63, 0xbfb8aa3b, v63
	v_exp_f32_e32 v63, v63
	v_add_f32_e32 v15, 1.0, v15
	v_rcp_f32_e32 v15, v15
	v_add_f32_e32 v66, 1.0, v66
	v_rcp_f32_e32 v66, v66
	v_add_f32_e32 v63, 1.0, v63
	v_rcp_f32_e32 v63, v63
	v_mul_f32_e32 v15, 0x437f0000, v15
	v_rndne_f32_e32 v15, v15
	v_mul_f32_e32 v66, 0x437f0000, v66
	v_cvt_pk_u8_f32 v15, v15, 0, 0
	v_rndne_f32_e32 v66, v66
	v_mul_f32_e32 v63, 0x437f0000, v63
	v_cvt_pk_u8_f32 v15, v66, 1, v15
	v_rndne_f32_e32 v63, v63
	v_cvt_pk_u8_f32 v15, v63, 2, v15
	v_add_f32_e32 v63, v56, v64
	v_mul_f32_e32 v63, 0xbfb8aa3b, v63
	v_exp_f32_e32 v63, v63
	s_nop 0
	v_add_f32_e32 v63, 1.0, v63
	v_rcp_f32_e32 v63, v63
	s_nop 0
	v_mul_f32_e32 v63, 0x437f0000, v63
	v_rndne_f32_e32 v63, v63
	v_cvt_pk_u8_f32 v63, v63, 2, v62
	v_add_f32_e32 v62, v61, v69
	v_mul_f32_e32 v62, 0xbfb8aa3b, v62
	v_exp_f32_e32 v62, v62
	s_nop 0
	v_add_f32_e32 v62, 1.0, v62
	v_rcp_f32_e32 v62, v62
	s_nop 0
	v_mul_f32_e32 v62, 0x437f0000, v62
	v_rndne_f32_e32 v62, v62
	v_cvt_pk_u8_f32 v62, v62, 3, v15
	v_add_f32_e32 v15, v57, v65
	v_mul_f32_e32 v15, 0xbfb8aa3b, v15
	v_exp_f32_e32 v15, v15
	v_lshl_add_u64 v[64:65], s[58:59], 0, v[70:71]
	v_lshl_add_u64 v[64:65], v[64:65], 0, s[18:19]
	v_lshl_add_u64 v[64:65], v[64:65], 0, s[26:27]
	v_add_f32_e32 v15, 1.0, v15
	v_rcp_f32_e32 v15, v15
	v_lshl_add_u64 v[64:65], v[64:65], 0, v[156:157]
	v_mul_f32_e32 v15, 0x437f0000, v15
	v_rndne_f32_e32 v15, v15
	v_cvt_pk_u8_f32 v63, v15, 3, v63
	global_store_dwordx2 v[64:65], v[62:63], off

.LBB0_382:
	ds_read_b128 v[62:65], v190
	s_waitcnt lgkmcnt(0)
	v_mov_b32_e32 v66, v63
	v_mov_b32_e32 v67, v64
	v_mov_b32_e32 v63, v65
	v_pk_add_f32 v[62:63], v[66:67], v[62:63]
	s_nop 0
	v_add_f32_e32 v15, v62, v63
	v_fmamk_f32 v15, v15, 0x3c000000, v250
	v_mul_f32_e32 v62, 0x4b800000, v15
	v_cmp_gt_f32_e32 vcc, s28, v15
	s_nop 1
	v_cndmask_b32_e32 v15, v15, v62, vcc
	v_rsq_f32_e32 v15, v15
	s_nop 0
	v_mul_f32_e32 v62, 0x45800000, v15
	v_cndmask_b32_e32 v62, v15, v62, vcc
	v_pk_mul_f32 v[58:59], v[58:59], v[62:63] op_sel_hi:[1,0]
	v_pk_mul_f32 v[60:61], v[60:61], v[62:63] op_sel_hi:[1,0]
	v_pk_mul_f32 v[54:55], v[54:55], v[62:63] op_sel_hi:[1,0]
	v_pk_mul_f32 v[56:57], v[56:57], v[62:63] op_sel_hi:[1,0]
	v_pk_mul_f32 v[64:65], v[12:13], v[60:61]
	v_pk_mul_f32 v[62:63], v[10:11], v[58:59]
	v_pk_mul_f32 v[68:69], v[20:21], v[56:57]
	v_pk_mul_f32 v[66:67], v[18:19], v[54:55]
	v_mad_i64_i32 v[72:73], s[20:21], v72, s56, v[166:167]
	s_branch .LBB0_394

.LBB0_384:
	s_cmp_gt_i32 s1, 2
	s_mov_b64 s[22:23], -1
	s_cbranch_scc0 .LBB0_386
	v_lshl_add_u64 v[58:59], s[18:19], 2, v[160:161]
	v_mov_b64_e32 v[54:55], v[208:209]
	v_mov_b64_e32 v[56:57], v[210:211]
	s_nop 0
	v_mov_b64_e32 v[58:59], v[216:217]
	v_mov_b64_e32 v[60:61], v[218:219]
	v_lshl_add_u64 v[62:63], s[58:59], 0, v[70:71]
	v_lshl_add_u64 v[62:63], v[62:63], 0, s[18:19]
	v_lshl_add_u64 v[62:63], v[62:63], 0, s[26:27]
	v_lshl_add_u64 v[62:63], v[62:63], 0, v[156:157]
	s_mov_b64 s[22:23], 0
	v_add_f32_e32 v15, v50, v54
	v_add_f32_e32 v54, v46, v58
	v_add_f32_e32 v55, v51, v55
	v_add_f32_e32 v58, v47, v59
	v_mul_f32_e32 v15, 0xbfb8aa3b, v15
	v_mul_f32_e32 v54, 0xbfb8aa3b, v54
	v_add_f32_e32 v56, v52, v56
	v_add_f32_e32 v59, v48, v60
	v_mul_f32_e32 v55, 0xbfb8aa3b, v55
	v_mul_f32_e32 v58, 0xbfb8aa3b, v58
	v_exp_f32_e32 v15, v15
	v_exp_f32_e32 v54, v54
	v_add_f32_e32 v57, v53, v57
	v_add_f32_e32 v60, v49, v61
	v_mul_f32_e32 v56, 0xbfb8aa3b, v56
	v_mul_f32_e32 v59, 0xbfb8aa3b, v59
	v_exp_f32_e32 v55, v55
	v_exp_f32_e32 v58, v58
	v_mul_f32_e32 v57, 0xbfb8aa3b, v57
	v_mul_f32_e32 v60, 0xbfb8aa3b, v60
	v_exp_f32_e32 v56, v56
	v_exp_f32_e32 v59, v59
	v_exp_f32_e32 v57, v57
	v_exp_f32_e32 v60, v60
	v_add_f32_e32 v15, 1.0, v15
	v_add_f32_e32 v54, 1.0, v54
	v_add_f32_e32 v55, 1.0, v55
	v_add_f32_e32 v58, 1.0, v58
	v_rcp_f32_e32 v15, v15
	v_rcp_f32_e32 v54, v54
	v_add_f32_e32 v56, 1.0, v56
	v_add_f32_e32 v59, 1.0, v59
	v_rcp_f32_e32 v55, v55
	v_rcp_f32_e32 v58, v58
	v_add_f32_e32 v57, 1.0, v57
	v_add_f32_e32 v60, 1.0, v60
	v_rcp_f32_e32 v56, v56
	v_rcp_f32_e32 v59, v59
	v_rcp_f32_e32 v57, v57
	v_rcp_f32_e32 v60, v60
	v_mul_f32_e32 v15, 0x437f0000, v15
	v_mul_f32_e32 v54, 0x437f0000, v54
	v_mul_f32_e32 v55, 0x437f0000, v55
	v_mul_f32_e32 v58, 0x437f0000, v58
	v_rndne_f32_e32 v15, v15
	v_rndne_f32_e32 v54, v54
	v_mul_f32_e32 v56, 0x437f0000, v56
	v_mul_f32_e32 v59, 0x437f0000, v59
	v_rndne_f32_e32 v55, v55
	v_rndne_f32_e32 v58, v58
	v_cvt_pk_u8_f32 v15, v15, 0, 0
	v_cvt_pk_u8_f32 v54, v54, 0, 0
	v_mul_f32_e32 v57, 0x437f0000, v57
	v_mul_f32_e32 v60, 0x437f0000, v60
	v_rndne_f32_e32 v56, v56
	v_rndne_f32_e32 v59, v59
	v_cvt_pk_u8_f32 v15, v55, 1, v15
	v_cvt_pk_u8_f32 v54, v58, 1, v54
	v_rndne_f32_e32 v57, v57
	v_rndne_f32_e32 v60, v60
	v_cvt_pk_u8_f32 v15, v56, 2, v15
	v_cvt_pk_u8_f32 v55, v59, 2, v54
	v_cvt_pk_u8_f32 v54, v57, 3, v15
	v_cvt_pk_u8_f32 v55, v60, 3, v55
	global_store_dwordx2 v[62:63], v[54:55], off offset:128

.LBB0_391:
	ds_read_b128 v[54:57], v190 offset:16
	s_waitcnt lgkmcnt(0)
	v_mov_b32_e32 v58, v55
	v_mov_b32_e32 v59, v56
	v_mov_b32_e32 v55, v57
	v_pk_add_f32 v[54:55], v[58:59], v[54:55]
	s_nop 0
	v_add_f32_e32 v15, v54, v55
	v_fmamk_f32 v15, v15, 0x3c000000, v250
	v_mul_f32_e32 v54, 0x4b800000, v15
	v_cmp_gt_f32_e32 vcc, s28, v15
	s_nop 1
	v_cndmask_b32_e32 v15, v15, v54, vcc
	v_rsq_f32_e32 v15, v15
	s_nop 0
	v_mul_f32_e32 v54, 0x45800000, v15
	v_cndmask_b32_e32 v54, v15, v54, vcc
	v_pk_mul_f32 v[50:51], v[50:51], v[54:55] op_sel_hi:[1,0]
	v_pk_mul_f32 v[52:53], v[52:53], v[54:55] op_sel_hi:[1,0]
	v_pk_mul_f32 v[46:47], v[46:47], v[54:55] op_sel_hi:[1,0]
	v_pk_mul_f32 v[48:49], v[48:49], v[54:55] op_sel_hi:[1,0]
	v_pk_mul_f32 v[56:57], v[12:13], v[52:53]
	v_pk_mul_f32 v[54:55], v[10:11], v[50:51]
	v_pk_mul_f32 v[60:61], v[20:21], v[48:49]
	v_pk_mul_f32 v[58:59], v[18:19], v[46:47]
	s_branch .LBB0_397

.LBB0_398:
	v_add_u32_e32 v56, 0xa0, v14
	v_ashrrev_i32_e32 v57, 31, v56
	s_and_b64 vcc, exec, s[46:47]
	v_lshlrev_b64 v[54:55], 13, v[56:57]
	s_cbranch_vccnz .LBB0_416
	s_cmp_gt_i32 s1, 2
	s_mov_b64 s[22:23], -1
	s_cbranch_scc0 .LBB0_401
	v_lshl_add_u64 v[50:51], s[18:19], 2, v[160:161]
	v_mov_b64_e32 v[46:47], v[204:205]
	v_mov_b64_e32 v[48:49], v[206:207]
	s_nop 0
	v_mov_b64_e32 v[50:51], v[200:201]
	v_mov_b64_e32 v[52:53], v[202:203]
	s_mov_b64 s[22:23], 0
	v_add_f32_e32 v46, v38, v46
	v_mul_f32_e32 v46, 0xbfb8aa3b, v46
	v_add_f32_e32 v47, v39, v47
	v_exp_f32_e32 v46, v46
	v_mul_f32_e32 v47, 0xbfb8aa3b, v47
	v_exp_f32_e32 v47, v47
	v_add_f32_e32 v15, v42, v50
	v_add_f32_e32 v46, 1.0, v46
	v_rcp_f32_e32 v46, v46
	v_add_f32_e32 v47, 1.0, v47
	v_rcp_f32_e32 v47, v47
	v_mul_f32_e32 v15, 0xbfb8aa3b, v15
	v_mul_f32_e32 v46, 0x437f0000, v46
	v_rndne_f32_e32 v46, v46
	v_mul_f32_e32 v47, 0x437f0000, v47
	v_cvt_pk_u8_f32 v46, v46, 0, 0
	v_add_f32_e32 v50, v43, v51
	v_rndne_f32_e32 v47, v47
	v_exp_f32_e32 v15, v15
	v_mul_f32_e32 v50, 0xbfb8aa3b, v50
	v_cvt_pk_u8_f32 v46, v47, 1, v46
	v_add_f32_e32 v47, v44, v52
	v_exp_f32_e32 v50, v50
	v_mul_f32_e32 v47, 0xbfb8aa3b, v47
	v_exp_f32_e32 v47, v47
	v_add_f32_e32 v15, 1.0, v15
	v_rcp_f32_e32 v15, v15
	v_add_f32_e32 v50, 1.0, v50
	v_rcp_f32_e32 v50, v50
	v_add_f32_e32 v47, 1.0, v47
	v_rcp_f32_e32 v47, v47
	v_mul_f32_e32 v15, 0x437f0000, v15
	v_rndne_f32_e32 v15, v15
	v_mul_f32_e32 v50, 0x437f0000, v50
	v_cvt_pk_u8_f32 v15, v15, 0, 0
	v_rndne_f32_e32 v50, v50
	v_mul_f32_e32 v47, 0x437f0000, v47
	v_cvt_pk_u8_f32 v15, v50, 1, v15
	v_rndne_f32_e32 v47, v47
	v_cvt_pk_u8_f32 v15, v47, 2, v15
	v_add_f32_e32 v47, v40, v48
	v_mul_f32_e32 v47, 0xbfb8aa3b, v47
	v_exp_f32_e32 v47, v47
	s_nop 0
	v_add_f32_e32 v47, 1.0, v47
	v_rcp_f32_e32 v47, v47
	s_nop 0
	v_mul_f32_e32 v47, 0x437f0000, v47
	v_rndne_f32_e32 v47, v47
	v_cvt_pk_u8_f32 v47, v47, 2, v46
	v_add_f32_e32 v46, v45, v53
	v_mul_f32_e32 v46, 0xbfb8aa3b, v46
	v_exp_f32_e32 v46, v46
	s_nop 0
	v_add_f32_e32 v46, 1.0, v46
	v_rcp_f32_e32 v46, v46
	s_nop 0
	v_mul_f32_e32 v46, 0x437f0000, v46
	v_rndne_f32_e32 v46, v46
	v_cvt_pk_u8_f32 v46, v46, 3, v15
	v_add_f32_e32 v15, v41, v49
	v_mul_f32_e32 v15, 0xbfb8aa3b, v15
	v_exp_f32_e32 v15, v15
	v_lshl_add_u64 v[48:49], s[58:59], 0, v[54:55]
	v_lshl_add_u64 v[48:49], v[48:49], 0, s[18:19]
	v_lshl_add_u64 v[48:49], v[48:49], 0, s[26:27]
	v_add_f32_e32 v15, 1.0, v15
	v_rcp_f32_e32 v15, v15
	v_lshl_add_u64 v[48:49], v[48:49], 0, v[156:157]
	v_mul_f32_e32 v15, 0x437f0000, v15
	v_rndne_f32_e32 v15, v15
	v_cvt_pk_u8_f32 v47, v15, 3, v47
	global_store_dwordx2 v[48:49], v[46:47], off

.LBB0_406:
	ds_read_b128 v[46:49], v193
	s_waitcnt lgkmcnt(0)
	v_mov_b32_e32 v50, v47
	v_mov_b32_e32 v51, v48
	v_mov_b32_e32 v47, v49
	v_pk_add_f32 v[46:47], v[50:51], v[46:47]
	s_nop 0
	v_add_f32_e32 v15, v46, v47
	v_fmamk_f32 v15, v15, 0x3c000000, v250
	v_mul_f32_e32 v46, 0x4b800000, v15
	v_cmp_gt_f32_e32 vcc, s28, v15
	s_nop 1
	v_cndmask_b32_e32 v15, v15, v46, vcc
	v_rsq_f32_e32 v15, v15
	s_nop 0
	v_mul_f32_e32 v46, 0x45800000, v15
	v_cndmask_b32_e32 v46, v15, v46, vcc
	v_pk_mul_f32 v[42:43], v[42:43], v[46:47] op_sel_hi:[1,0]
	v_pk_mul_f32 v[44:45], v[44:45], v[46:47] op_sel_hi:[1,0]
	v_pk_mul_f32 v[38:39], v[38:39], v[46:47] op_sel_hi:[1,0]
	v_pk_mul_f32 v[40:41], v[40:41], v[46:47] op_sel_hi:[1,0]
	v_pk_mul_f32 v[48:49], v[12:13], v[44:45]
	v_pk_mul_f32 v[46:47], v[10:11], v[42:43]
	v_pk_mul_f32 v[52:53], v[20:21], v[40:41]
	v_pk_mul_f32 v[50:51], v[18:19], v[38:39]
	v_mad_i64_i32 v[56:57], s[20:21], v56, s56, v[166:167]
	s_branch .LBB0_418

.LBB0_408:
	s_cmp_gt_i32 s1, 2
	s_mov_b64 s[22:23], -1
	s_cbranch_scc0 .LBB0_410
	v_lshl_add_u64 v[42:43], s[18:19], 2, v[160:161]
	v_mov_b64_e32 v[38:39], v[208:209]
	v_mov_b64_e32 v[40:41], v[210:211]
	s_nop 0
	v_mov_b64_e32 v[42:43], v[216:217]
	v_mov_b64_e32 v[44:45], v[218:219]
	v_lshl_add_u64 v[46:47], s[58:59], 0, v[54:55]
	v_lshl_add_u64 v[46:47], v[46:47], 0, s[18:19]
	v_lshl_add_u64 v[46:47], v[46:47], 0, s[26:27]
	v_lshl_add_u64 v[46:47], v[46:47], 0, v[156:157]
	s_mov_b64 s[22:23], 0
	v_add_f32_e32 v15, v34, v38
	v_add_f32_e32 v38, v30, v42
	v_add_f32_e32 v39, v35, v39
	v_add_f32_e32 v42, v31, v43
	v_mul_f32_e32 v15, 0xbfb8aa3b, v15
	v_mul_f32_e32 v38, 0xbfb8aa3b, v38
	v_add_f32_e32 v40, v36, v40
	v_add_f32_e32 v43, v32, v44
	v_mul_f32_e32 v39, 0xbfb8aa3b, v39
	v_mul_f32_e32 v42, 0xbfb8aa3b, v42
	v_exp_f32_e32 v15, v15
	v_exp_f32_e32 v38, v38
	v_add_f32_e32 v41, v37, v41
	v_add_f32_e32 v44, v33, v45
	v_mul_f32_e32 v40, 0xbfb8aa3b, v40
	v_mul_f32_e32 v43, 0xbfb8aa3b, v43
	v_exp_f32_e32 v39, v39
	v_exp_f32_e32 v42, v42
	v_mul_f32_e32 v41, 0xbfb8aa3b, v41
	v_mul_f32_e32 v44, 0xbfb8aa3b, v44
	v_exp_f32_e32 v40, v40
	v_exp_f32_e32 v43, v43
	v_exp_f32_e32 v41, v41
	v_exp_f32_e32 v44, v44
	v_add_f32_e32 v15, 1.0, v15
	v_add_f32_e32 v38, 1.0, v38
	v_add_f32_e32 v39, 1.0, v39
	v_add_f32_e32 v42, 1.0, v42
	v_rcp_f32_e32 v15, v15
	v_rcp_f32_e32 v38, v38
	v_add_f32_e32 v40, 1.0, v40
	v_add_f32_e32 v43, 1.0, v43
	v_rcp_f32_e32 v39, v39
	v_rcp_f32_e32 v42, v42
	v_add_f32_e32 v41, 1.0, v41
	v_add_f32_e32 v44, 1.0, v44
	v_rcp_f32_e32 v40, v40
	v_rcp_f32_e32 v43, v43
	v_rcp_f32_e32 v41, v41
	v_rcp_f32_e32 v44, v44
	v_mul_f32_e32 v15, 0x437f0000, v15
	v_mul_f32_e32 v38, 0x437f0000, v38
	v_mul_f32_e32 v39, 0x437f0000, v39
	v_mul_f32_e32 v42, 0x437f0000, v42
	v_rndne_f32_e32 v15, v15
	v_rndne_f32_e32 v38, v38
	v_mul_f32_e32 v40, 0x437f0000, v40
	v_mul_f32_e32 v43, 0x437f0000, v43
	v_rndne_f32_e32 v39, v39
	v_rndne_f32_e32 v42, v42
	v_cvt_pk_u8_f32 v15, v15, 0, 0
	v_cvt_pk_u8_f32 v38, v38, 0, 0
	v_mul_f32_e32 v41, 0x437f0000, v41
	v_mul_f32_e32 v44, 0x437f0000, v44
	v_rndne_f32_e32 v40, v40
	v_rndne_f32_e32 v43, v43
	v_cvt_pk_u8_f32 v15, v39, 1, v15
	v_cvt_pk_u8_f32 v38, v42, 1, v38
	v_rndne_f32_e32 v41, v41
	v_rndne_f32_e32 v44, v44
	v_cvt_pk_u8_f32 v15, v40, 2, v15
	v_cvt_pk_u8_f32 v39, v43, 2, v38
	v_cvt_pk_u8_f32 v38, v41, 3, v15
	v_cvt_pk_u8_f32 v39, v44, 3, v39
	global_store_dwordx2 v[46:47], v[38:39], off offset:128

.LBB0_415:
	ds_read_b128 v[38:41], v193 offset:16
	s_waitcnt lgkmcnt(0)
	v_mov_b32_e32 v42, v39
	v_mov_b32_e32 v43, v40
	v_mov_b32_e32 v39, v41
	v_pk_add_f32 v[38:39], v[42:43], v[38:39]
	s_nop 0
	v_add_f32_e32 v15, v38, v39
	v_fmamk_f32 v15, v15, 0x3c000000, v250
	v_mul_f32_e32 v38, 0x4b800000, v15
	v_cmp_gt_f32_e32 vcc, s28, v15
	s_nop 1
	v_cndmask_b32_e32 v15, v15, v38, vcc
	v_rsq_f32_e32 v15, v15
	s_nop 0
	v_mul_f32_e32 v38, 0x45800000, v15
	v_cndmask_b32_e32 v38, v15, v38, vcc
	v_pk_mul_f32 v[34:35], v[34:35], v[38:39] op_sel_hi:[1,0]
	v_pk_mul_f32 v[36:37], v[36:37], v[38:39] op_sel_hi:[1,0]
	v_pk_mul_f32 v[30:31], v[30:31], v[38:39] op_sel_hi:[1,0]
	v_pk_mul_f32 v[32:33], v[32:33], v[38:39] op_sel_hi:[1,0]
	v_pk_mul_f32 v[40:41], v[12:13], v[36:37]
	v_pk_mul_f32 v[38:39], v[10:11], v[34:35]
	v_pk_mul_f32 v[44:45], v[20:21], v[32:33]
	v_pk_mul_f32 v[42:43], v[18:19], v[30:31]
	s_branch .LBB0_421

.LBB0_422:
	v_add_u32_e32 v38, 0xb0, v14
	v_ashrrev_i32_e32 v39, 31, v38
	s_and_b64 vcc, exec, s[46:47]
	v_lshlrev_b64 v[14:15], 13, v[38:39]
	s_cbranch_vccnz .LBB0_440
	s_cmp_gt_i32 s1, 2
	s_mov_b64 s[22:23], -1
	s_cbranch_scc0 .LBB0_425
	v_lshl_add_u64 v[34:35], s[18:19], 2, v[160:161]
	v_mov_b64_e32 v[30:31], v[204:205]
	v_mov_b64_e32 v[32:33], v[206:207]
	s_nop 0
	v_mov_b64_e32 v[34:35], v[200:201]
	v_mov_b64_e32 v[36:37], v[202:203]
	s_mov_b64 s[22:23], 0
	v_add_f32_e32 v30, v22, v30
	v_mul_f32_e32 v30, 0xbfb8aa3b, v30
	v_add_f32_e32 v31, v23, v31
	v_exp_f32_e32 v30, v30
	v_mul_f32_e32 v31, 0xbfb8aa3b, v31
	v_add_f32_e32 v32, v24, v32
	v_exp_f32_e32 v31, v31
	v_mul_f32_e32 v32, 0xbfb8aa3b, v32
	v_exp_f32_e32 v32, v32
	v_add_f32_e32 v30, 1.0, v30
	v_rcp_f32_e32 v30, v30
	v_add_f32_e32 v31, 1.0, v31
	v_rcp_f32_e32 v31, v31
	v_add_f32_e32 v32, 1.0, v32
	v_rcp_f32_e32 v32, v32
	v_mul_f32_e32 v30, 0x437f0000, v30
	v_add_f32_e32 v34, v26, v34
	v_rndne_f32_e32 v30, v30
	v_mul_f32_e32 v31, 0x437f0000, v31
	v_mul_f32_e32 v34, 0xbfb8aa3b, v34
	v_cvt_pk_u8_f32 v30, v30, 0, 0
	v_add_f32_e32 v35, v27, v35
	v_rndne_f32_e32 v31, v31
	v_mul_f32_e32 v32, 0x437f0000, v32
	v_exp_f32_e32 v34, v34
	v_mul_f32_e32 v35, 0xbfb8aa3b, v35
	v_cvt_pk_u8_f32 v30, v31, 1, v30
	v_add_f32_e32 v31, v28, v36
	v_rndne_f32_e32 v32, v32
	v_exp_f32_e32 v35, v35
	v_mul_f32_e32 v31, 0xbfb8aa3b, v31
	v_cvt_pk_u8_f32 v32, v32, 2, v30
	v_add_f32_e32 v30, v29, v37
	v_exp_f32_e32 v31, v31
	v_mul_f32_e32 v30, 0xbfb8aa3b, v30
	v_exp_f32_e32 v30, v30
	v_add_f32_e32 v34, 1.0, v34
	v_rcp_f32_e32 v34, v34
	v_add_f32_e32 v35, 1.0, v35
	v_rcp_f32_e32 v35, v35
	v_add_f32_e32 v31, 1.0, v31
	v_rcp_f32_e32 v31, v31
	v_add_f32_e32 v30, 1.0, v30
	v_rcp_f32_e32 v30, v30
	v_mul_f32_e32 v34, 0x437f0000, v34
	v_rndne_f32_e32 v34, v34
	v_mul_f32_e32 v35, 0x437f0000, v35
	v_cvt_pk_u8_f32 v34, v34, 0, 0
	v_rndne_f32_e32 v35, v35
	v_mul_f32_e32 v31, 0x437f0000, v31
	v_cvt_pk_u8_f32 v34, v35, 1, v34
	v_rndne_f32_e32 v31, v31
	v_mul_f32_e32 v30, 0x437f0000, v30
	v_cvt_pk_u8_f32 v31, v31, 2, v34
	v_rndne_f32_e32 v30, v30
	v_cvt_pk_u8_f32 v30, v30, 3, v31
	v_add_f32_e32 v31, v25, v33
	v_mul_f32_e32 v31, 0xbfb8aa3b, v31
	v_exp_f32_e32 v31, v31
	s_nop 0
	v_add_f32_e32 v31, 1.0, v31
	v_rcp_f32_e32 v31, v31
	s_nop 0
	v_mul_f32_e32 v31, 0x437f0000, v31
	v_rndne_f32_e32 v31, v31
	v_cvt_pk_u8_f32 v31, v31, 3, v32
	v_lshl_add_u64 v[32:33], s[58:59], 0, v[14:15]
	v_lshl_add_u64 v[32:33], v[32:33], 0, s[18:19]
	v_lshl_add_u64 v[32:33], v[32:33], 0, s[26:27]
	v_lshl_add_u64 v[32:33], v[32:33], 0, v[156:157]
	global_store_dwordx2 v[32:33], v[30:31], off

.LBB0_430:
	ds_read_b128 v[30:33], v196
	s_waitcnt lgkmcnt(0)
	v_mov_b32_e32 v34, v31
	v_mov_b32_e32 v35, v32
	v_mov_b32_e32 v31, v33
	v_pk_add_f32 v[30:31], v[34:35], v[30:31]
	s_nop 0
	v_add_f32_e32 v30, v30, v31
	v_fmamk_f32 v30, v30, 0x3c000000, v250
	v_mul_f32_e32 v31, 0x4b800000, v30
	v_cmp_gt_f32_e32 vcc, s28, v30
	s_nop 1
	v_cndmask_b32_e32 v30, v30, v31, vcc
	v_rsq_f32_e32 v30, v30
	s_nop 0
	v_mul_f32_e32 v31, 0x45800000, v30
	v_cndmask_b32_e32 v30, v30, v31, vcc
	v_pk_mul_f32 v[26:27], v[26:27], v[30:31] op_sel_hi:[1,0]
	v_pk_mul_f32 v[28:29], v[28:29], v[30:31] op_sel_hi:[1,0]
	v_pk_mul_f32 v[22:23], v[22:23], v[30:31] op_sel_hi:[1,0]
	v_pk_mul_f32 v[24:25], v[24:25], v[30:31] op_sel_hi:[1,0]
	v_pk_mul_f32 v[32:33], v[12:13], v[28:29]
	v_pk_mul_f32 v[30:31], v[10:11], v[26:27]
	v_pk_mul_f32 v[36:37], v[20:21], v[24:25]
	v_pk_mul_f32 v[34:35], v[18:19], v[22:23]
	v_mad_i64_i32 v[38:39], s[20:21], v38, s56, v[166:167]
	s_branch .LBB0_442

.LBB0_432:
	s_cmp_gt_i32 s1, 2
	s_mov_b64 s[20:21], -1
	s_cbranch_scc0 .LBB0_434
	v_lshl_add_u64 v[26:27], s[18:19], 2, v[160:161]
	v_mov_b64_e32 v[22:23], v[208:209]
	v_mov_b64_e32 v[24:25], v[210:211]
	s_nop 0
	v_mov_b64_e32 v[26:27], v[216:217]
	v_mov_b64_e32 v[28:29], v[218:219]
	v_lshl_add_u64 v[14:15], s[58:59], 0, v[14:15]
	v_lshl_add_u64 v[14:15], v[14:15], 0, s[18:19]
	v_lshl_add_u64 v[14:15], v[14:15], 0, s[26:27]
	v_lshl_add_u64 v[14:15], v[14:15], 0, v[156:157]
	s_mov_b64 s[20:21], 0
	v_add_f32_e32 v22, v6, v22
	v_add_f32_e32 v26, v2, v26
	v_add_f32_e32 v23, v7, v23
	v_add_f32_e32 v27, v3, v27
	v_mul_f32_e32 v22, 0xbfb8aa3b, v22
	v_mul_f32_e32 v26, 0xbfb8aa3b, v26
	v_add_f32_e32 v24, v8, v24
	v_add_f32_e32 v28, v4, v28
	v_mul_f32_e32 v23, 0xbfb8aa3b, v23
	v_mul_f32_e32 v27, 0xbfb8aa3b, v27
	v_exp_f32_e32 v22, v22
	v_exp_f32_e32 v26, v26
	v_add_f32_e32 v25, v9, v25
	v_add_f32_e32 v29, v5, v29
	v_mul_f32_e32 v24, 0xbfb8aa3b, v24
	v_mul_f32_e32 v28, 0xbfb8aa3b, v28
	v_exp_f32_e32 v23, v23
	v_exp_f32_e32 v27, v27
	v_mul_f32_e32 v25, 0xbfb8aa3b, v25
	v_mul_f32_e32 v29, 0xbfb8aa3b, v29
	v_exp_f32_e32 v24, v24
	v_exp_f32_e32 v28, v28
	v_exp_f32_e32 v25, v25
	v_exp_f32_e32 v29, v29
	v_add_f32_e32 v22, 1.0, v22
	v_add_f32_e32 v26, 1.0, v26
	v_add_f32_e32 v23, 1.0, v23
	v_add_f32_e32 v27, 1.0, v27
	v_rcp_f32_e32 v22, v22
	v_rcp_f32_e32 v26, v26
	v_add_f32_e32 v24, 1.0, v24
	v_add_f32_e32 v28, 1.0, v28
	v_rcp_f32_e32 v23, v23
	v_rcp_f32_e32 v27, v27
	v_add_f32_e32 v25, 1.0, v25
	v_add_f32_e32 v29, 1.0, v29
	v_rcp_f32_e32 v24, v24
	v_rcp_f32_e32 v28, v28
	v_rcp_f32_e32 v25, v25
	v_rcp_f32_e32 v29, v29
	v_mul_f32_e32 v22, 0x437f0000, v22
	v_mul_f32_e32 v26, 0x437f0000, v26
	v_mul_f32_e32 v23, 0x437f0000, v23
	v_mul_f32_e32 v27, 0x437f0000, v27
	v_rndne_f32_e32 v22, v22
	v_rndne_f32_e32 v26, v26
	v_mul_f32_e32 v24, 0x437f0000, v24
	v_mul_f32_e32 v28, 0x437f0000, v28
	v_rndne_f32_e32 v23, v23
	v_rndne_f32_e32 v27, v27
	v_cvt_pk_u8_f32 v22, v22, 0, 0
	v_cvt_pk_u8_f32 v26, v26, 0, 0
	v_mul_f32_e32 v25, 0x437f0000, v25
	v_mul_f32_e32 v29, 0x437f0000, v29
	v_rndne_f32_e32 v24, v24
	v_rndne_f32_e32 v28, v28
	v_cvt_pk_u8_f32 v22, v23, 1, v22
	v_cvt_pk_u8_f32 v23, v27, 1, v26
	v_rndne_f32_e32 v25, v25
	v_rndne_f32_e32 v29, v29
	v_cvt_pk_u8_f32 v22, v24, 2, v22
	v_cvt_pk_u8_f32 v23, v28, 2, v23
	v_cvt_pk_u8_f32 v22, v25, 3, v22
	v_cvt_pk_u8_f32 v23, v29, 3, v23
	global_store_dwordx2 v[14:15], v[22:23], off offset:128

.LBB0_439:
	ds_read_b128 v[22:25], v196 offset:16
	s_waitcnt lgkmcnt(0)
	v_mov_b32_e32 v14, v23
	v_mov_b32_e32 v15, v24
	v_mov_b32_e32 v23, v25
	v_pk_add_f32 v[14:15], v[14:15], v[22:23]
	s_nop 0
	v_add_f32_e32 v14, v14, v15
	v_fmamk_f32 v14, v14, 0x3c000000, v250
	v_mul_f32_e32 v15, 0x4b800000, v14
	v_cmp_gt_f32_e32 vcc, s28, v14
	s_nop 1
	v_cndmask_b32_e32 v14, v14, v15, vcc
	v_rsq_f32_e32 v14, v14
	s_nop 0
	v_mul_f32_e32 v15, 0x45800000, v14
	v_cndmask_b32_e32 v14, v14, v15, vcc
	v_pk_mul_f32 v[6:7], v[6:7], v[14:15] op_sel_hi:[1,0]
	v_pk_mul_f32 v[8:9], v[8:9], v[14:15] op_sel_hi:[1,0]
	v_pk_mul_f32 v[2:3], v[2:3], v[14:15] op_sel_hi:[1,0]
	v_pk_mul_f32 v[4:5], v[4:5], v[14:15] op_sel_hi:[1,0]
	v_pk_mul_f32 v[24:25], v[12:13], v[8:9]
	v_pk_mul_f32 v[22:23], v[10:11], v[6:7]
	v_pk_mul_f32 v[28:29], v[20:21], v[4:5]
	v_pk_mul_f32 v[26:27], v[18:19], v[2:3]
	s_branch .LBB0_445

.LBB0_601:
	s_or_b64 exec, exec, s[0:1]
	s_mul_i32 s0, s8, s86
	s_mul_hi_u32 s1, s52, s86
	s_add_i32 s1, s1, s0
	s_mul_i32 s0, s52, s86
	s_lshl_b64 s[0:1], s[0:1], 1
	s_add_u32 s0, s42, s0
	v_mul_lo_u32 v0, v220, s86
	s_addc_u32 s1, s43, s1
	v_or_b32_e32 v0, v0, v219
	v_and_b32_e32 v14, 1, v218
	v_cmp_eq_u32_e32 vcc, 0, v14
	v_lshl_add_u64 v[14:15], v[0:1], 1, s[0:1]
	ds_read_b32 v0, v217
	s_waitcnt lgkmcnt(0)
	v_rcp_f32_e32 v0, v0
	s_nop 0
	v_mul_f32_e32 v17, v80, v0
	v_mul_f32_e32 v18, v64, v0
	v_mul_f32_e32 v19, v48, v0
	v_mul_f32_e32 v20, v32, v0
	v_mov_b32_dpp v21, v17 quad_perm:[1,0,3,2] row_mask:0xf bank_mask:0xf bound_ctrl:1
	v_mov_b32_dpp v22, v18 quad_perm:[1,0,3,2] row_mask:0xf bank_mask:0xf bound_ctrl:1
	v_mov_b32_dpp v23, v19 quad_perm:[1,0,3,2] row_mask:0xf bank_mask:0xf bound_ctrl:1
	v_mov_b32_dpp v24, v20 quad_perm:[1,0,3,2] row_mask:0xf bank_mask:0xf bound_ctrl:1
	v_cvt_pk_bf16_f32 v17, v17, v21
	v_cvt_pk_bf16_f32 v18, v18, v22
	v_cvt_pk_bf16_f32 v19, v19, v23
	v_cvt_pk_bf16_f32 v20, v20, v24
	s_and_saveexec_b64 s[0:1], vcc
	global_store_dword v[14:15], v17, off
	global_store_dword v[14:15], v18, off offset:64
	global_store_dword v[14:15], v19, off offset:128
	global_store_dword v[14:15], v20, off offset:192
	s_or_b64 exec, exec, s[0:1]
	ds_read_b32 v0, v217 offset:4
	v_lshl_add_u64 v[14:15], s[86:87], 1, v[14:15]
	s_waitcnt lgkmcnt(0)
	v_rcp_f32_e32 v0, v0
	s_nop 0
	v_mul_f32_e32 v17, v81, v0
	v_mul_f32_e32 v18, v65, v0
	v_mul_f32_e32 v19, v49, v0
	v_mul_f32_e32 v20, v33, v0
	v_mov_b32_dpp v21, v17 quad_perm:[1,0,3,2] row_mask:0xf bank_mask:0xf bound_ctrl:1
	v_mov_b32_dpp v22, v18 quad_perm:[1,0,3,2] row_mask:0xf bank_mask:0xf bound_ctrl:1
	v_mov_b32_dpp v23, v19 quad_perm:[1,0,3,2] row_mask:0xf bank_mask:0xf bound_ctrl:1
	v_mov_b32_dpp v24, v20 quad_perm:[1,0,3,2] row_mask:0xf bank_mask:0xf bound_ctrl:1
	v_cvt_pk_bf16_f32 v17, v17, v21
	v_cvt_pk_bf16_f32 v18, v18, v22
	v_cvt_pk_bf16_f32 v19, v19, v23
	v_cvt_pk_bf16_f32 v20, v20, v24
	s_and_saveexec_b64 s[0:1], vcc
	global_store_dword v[14:15], v17, off
	global_store_dword v[14:15], v18, off offset:64
	global_store_dword v[14:15], v19, off offset:128
	global_store_dword v[14:15], v20, off offset:192
	s_or_b64 exec, exec, s[0:1]
	ds_read_b32 v0, v217 offset:8
	s_lshl_b64 s[0:1], s[86:87], 1
	v_lshl_add_u64 v[14:15], v[14:15], 0, s[0:1]
	s_waitcnt lgkmcnt(0)
	v_rcp_f32_e32 v0, v0
	s_nop 0
	v_mul_f32_e32 v17, v82, v0
	v_mul_f32_e32 v18, v66, v0
	v_mul_f32_e32 v19, v50, v0
	v_mul_f32_e32 v20, v34, v0
	v_mov_b32_dpp v21, v17 quad_perm:[1,0,3,2] row_mask:0xf bank_mask:0xf bound_ctrl:1
	v_mov_b32_dpp v22, v18 quad_perm:[1,0,3,2] row_mask:0xf bank_mask:0xf bound_ctrl:1
	v_mov_b32_dpp v23, v19 quad_perm:[1,0,3,2] row_mask:0xf bank_mask:0xf bound_ctrl:1
	v_mov_b32_dpp v24, v20 quad_perm:[1,0,3,2] row_mask:0xf bank_mask:0xf bound_ctrl:1
	v_cvt_pk_bf16_f32 v17, v17, v21
	v_cvt_pk_bf16_f32 v18, v18, v22
	v_cvt_pk_bf16_f32 v19, v19, v23
	v_cvt_pk_bf16_f32 v20, v20, v24
	s_and_saveexec_b64 s[22:23], vcc
	global_store_dword v[14:15], v17, off
	global_store_dword v[14:15], v18, off offset:64
	global_store_dword v[14:15], v19, off offset:128
	global_store_dword v[14:15], v20, off offset:192
	s_or_b64 exec, exec, s[22:23]
	ds_read_b32 v0, v217 offset:12
	v_lshl_add_u64 v[14:15], v[14:15], 0, s[0:1]
	s_waitcnt lgkmcnt(0)
	v_rcp_f32_e32 v0, v0
	s_nop 0
	v_mul_f32_e32 v17, v83, v0
	v_mul_f32_e32 v18, v67, v0
	v_mul_f32_e32 v19, v51, v0
	v_mul_f32_e32 v20, v35, v0
	v_mov_b32_dpp v21, v17 quad_perm:[1,0,3,2] row_mask:0xf bank_mask:0xf bound_ctrl:1
	v_mov_b32_dpp v22, v18 quad_perm:[1,0,3,2] row_mask:0xf bank_mask:0xf bound_ctrl:1
	v_mov_b32_dpp v23, v19 quad_perm:[1,0,3,2] row_mask:0xf bank_mask:0xf bound_ctrl:1
	v_mov_b32_dpp v24, v20 quad_perm:[1,0,3,2] row_mask:0xf bank_mask:0xf bound_ctrl:1
	v_cvt_pk_bf16_f32 v17, v17, v21
	v_cvt_pk_bf16_f32 v18, v18, v22
	v_cvt_pk_bf16_f32 v19, v19, v23
	v_cvt_pk_bf16_f32 v20, v20, v24
	s_and_saveexec_b64 s[22:23], vcc
	global_store_dword v[14:15], v17, off
	global_store_dword v[14:15], v18, off offset:64
	global_store_dword v[14:15], v19, off offset:128
	global_store_dword v[14:15], v20, off offset:192
	s_or_b64 exec, exec, s[22:23]
	ds_read_b32 v0, v217 offset:32
	v_mad_u64_u32 v[14:15], s[8:9], s86, 10, v[14:15]
	s_waitcnt lgkmcnt(0)
	v_rcp_f32_e32 v0, v0
	s_nop 0
	v_mul_f32_e32 v17, v84, v0
	v_mul_f32_e32 v18, v68, v0
	v_mul_f32_e32 v19, v52, v0
	v_mul_f32_e32 v20, v36, v0
	v_mov_b32_dpp v21, v17 quad_perm:[1,0,3,2] row_mask:0xf bank_mask:0xf bound_ctrl:1
	v_mov_b32_dpp v22, v18 quad_perm:[1,0,3,2] row_mask:0xf bank_mask:0xf bound_ctrl:1
	v_mov_b32_dpp v23, v19 quad_perm:[1,0,3,2] row_mask:0xf bank_mask:0xf bound_ctrl:1
	v_mov_b32_dpp v24, v20 quad_perm:[1,0,3,2] row_mask:0xf bank_mask:0xf bound_ctrl:1
	v_cvt_pk_bf16_f32 v17, v17, v21
	v_cvt_pk_bf16_f32 v18, v18, v22
	v_cvt_pk_bf16_f32 v19, v19, v23
	v_cvt_pk_bf16_f32 v20, v20, v24
	s_and_saveexec_b64 s[22:23], vcc
	global_store_dword v[14:15], v17, off
	global_store_dword v[14:15], v18, off offset:64
	global_store_dword v[14:15], v19, off offset:128
	global_store_dword v[14:15], v20, off offset:192
	s_or_b64 exec, exec, s[22:23]
	ds_read_b32 v0, v217 offset:36
	v_lshl_add_u64 v[14:15], v[14:15], 0, s[0:1]
	s_waitcnt lgkmcnt(0)
	v_rcp_f32_e32 v0, v0
	s_nop 0
	v_mul_f32_e32 v17, v85, v0
	v_mul_f32_e32 v18, v69, v0
	v_mul_f32_e32 v19, v53, v0
	v_mul_f32_e32 v20, v37, v0
	v_mov_b32_dpp v21, v17 quad_perm:[1,0,3,2] row_mask:0xf bank_mask:0xf bound_ctrl:1
	v_mov_b32_dpp v22, v18 quad_perm:[1,0,3,2] row_mask:0xf bank_mask:0xf bound_ctrl:1
	v_mov_b32_dpp v23, v19 quad_perm:[1,0,3,2] row_mask:0xf bank_mask:0xf bound_ctrl:1
	v_mov_b32_dpp v24, v20 quad_perm:[1,0,3,2] row_mask:0xf bank_mask:0xf bound_ctrl:1
	v_cvt_pk_bf16_f32 v17, v17, v21
	v_cvt_pk_bf16_f32 v18, v18, v22
	v_cvt_pk_bf16_f32 v19, v19, v23
	v_cvt_pk_bf16_f32 v20, v20, v24
	s_and_saveexec_b64 s[22:23], vcc
	global_store_dword v[14:15], v17, off
	global_store_dword v[14:15], v18, off offset:64
	global_store_dword v[14:15], v19, off offset:128
	global_store_dword v[14:15], v20, off offset:192
	s_or_b64 exec, exec, s[22:23]
	ds_read_b32 v0, v217 offset:40
	v_lshl_add_u64 v[14:15], v[14:15], 0, s[0:1]
	s_waitcnt lgkmcnt(0)
	v_rcp_f32_e32 v0, v0
	s_nop 0
	v_mul_f32_e32 v17, v86, v0
	v_mul_f32_e32 v18, v70, v0
	v_mul_f32_e32 v19, v54, v0
	v_mul_f32_e32 v20, v38, v0
	v_mov_b32_dpp v21, v17 quad_perm:[1,0,3,2] row_mask:0xf bank_mask:0xf bound_ctrl:1
	v_mov_b32_dpp v22, v18 quad_perm:[1,0,3,2] row_mask:0xf bank_mask:0xf bound_ctrl:1
	v_mov_b32_dpp v23, v19 quad_perm:[1,0,3,2] row_mask:0xf bank_mask:0xf bound_ctrl:1
	v_mov_b32_dpp v24, v20 quad_perm:[1,0,3,2] row_mask:0xf bank_mask:0xf bound_ctrl:1
	v_cvt_pk_bf16_f32 v17, v17, v21
	v_cvt_pk_bf16_f32 v18, v18, v22
	v_cvt_pk_bf16_f32 v19, v19, v23
	v_cvt_pk_bf16_f32 v20, v20, v24
	s_and_saveexec_b64 s[22:23], vcc
	global_store_dword v[14:15], v17, off
	global_store_dword v[14:15], v18, off offset:64
	global_store_dword v[14:15], v19, off offset:128
	global_store_dword v[14:15], v20, off offset:192
	s_or_b64 exec, exec, s[22:23]
	ds_read_b32 v0, v217 offset:44
	v_lshl_add_u64 v[14:15], v[14:15], 0, s[0:1]
	s_waitcnt lgkmcnt(0)
	v_rcp_f32_e32 v0, v0
	s_nop 0
	v_mul_f32_e32 v17, v87, v0
	v_mul_f32_e32 v18, v71, v0
	v_mul_f32_e32 v19, v55, v0
	v_mul_f32_e32 v20, v39, v0
	v_mov_b32_dpp v21, v17 quad_perm:[1,0,3,2] row_mask:0xf bank_mask:0xf bound_ctrl:1
	v_mov_b32_dpp v22, v18 quad_perm:[1,0,3,2] row_mask:0xf bank_mask:0xf bound_ctrl:1
	v_mov_b32_dpp v23, v19 quad_perm:[1,0,3,2] row_mask:0xf bank_mask:0xf bound_ctrl:1
	v_mov_b32_dpp v24, v20 quad_perm:[1,0,3,2] row_mask:0xf bank_mask:0xf bound_ctrl:1
	v_cvt_pk_bf16_f32 v17, v17, v21
	v_cvt_pk_bf16_f32 v18, v18, v22
	v_cvt_pk_bf16_f32 v19, v19, v23
	v_cvt_pk_bf16_f32 v20, v20, v24
	s_and_saveexec_b64 s[22:23], vcc
	global_store_dword v[14:15], v17, off
	global_store_dword v[14:15], v18, off offset:64
	global_store_dword v[14:15], v19, off offset:128
	global_store_dword v[14:15], v20, off offset:192
	s_or_b64 exec, exec, s[22:23]
	ds_read_b32 v0, v217 offset:64
	s_mul_hi_u32 s23, s86, 10
	s_mul_i32 s22, s86, 10
	v_lshl_add_u64 v[14:15], v[14:15], 0, s[22:23]
	s_waitcnt lgkmcnt(0)
	v_rcp_f32_e32 v0, v0
	s_nop 0
	v_mul_f32_e32 v17, v88, v0
	v_mul_f32_e32 v18, v72, v0
	v_mul_f32_e32 v19, v56, v0
	v_mul_f32_e32 v20, v40, v0
	v_mov_b32_dpp v21, v17 quad_perm:[1,0,3,2] row_mask:0xf bank_mask:0xf bound_ctrl:1
	v_mov_b32_dpp v22, v18 quad_perm:[1,0,3,2] row_mask:0xf bank_mask:0xf bound_ctrl:1
	v_mov_b32_dpp v23, v19 quad_perm:[1,0,3,2] row_mask:0xf bank_mask:0xf bound_ctrl:1
	v_mov_b32_dpp v24, v20 quad_perm:[1,0,3,2] row_mask:0xf bank_mask:0xf bound_ctrl:1
	v_cvt_pk_bf16_f32 v17, v17, v21
	v_cvt_pk_bf16_f32 v18, v18, v22
	v_cvt_pk_bf16_f32 v19, v19, v23
	v_cvt_pk_bf16_f32 v20, v20, v24
	s_and_saveexec_b64 s[24:25], vcc
	global_store_dword v[14:15], v17, off
	global_store_dword v[14:15], v18, off offset:64
	global_store_dword v[14:15], v19, off offset:128
	global_store_dword v[14:15], v20, off offset:192
	s_or_b64 exec, exec, s[24:25]
	ds_read_b32 v0, v217 offset:68
	v_lshl_add_u64 v[14:15], v[14:15], 0, s[0:1]
	s_waitcnt lgkmcnt(0)
	v_rcp_f32_e32 v0, v0
	s_nop 0
	v_mul_f32_e32 v17, v89, v0
	v_mul_f32_e32 v18, v73, v0
	v_mul_f32_e32 v19, v57, v0
	v_mul_f32_e32 v20, v41, v0
	v_mov_b32_dpp v21, v17 quad_perm:[1,0,3,2] row_mask:0xf bank_mask:0xf bound_ctrl:1
	v_mov_b32_dpp v22, v18 quad_perm:[1,0,3,2] row_mask:0xf bank_mask:0xf bound_ctrl:1
	v_mov_b32_dpp v23, v19 quad_perm:[1,0,3,2] row_mask:0xf bank_mask:0xf bound_ctrl:1
	v_mov_b32_dpp v24, v20 quad_perm:[1,0,3,2] row_mask:0xf bank_mask:0xf bound_ctrl:1
	v_cvt_pk_bf16_f32 v17, v17, v21
	v_cvt_pk_bf16_f32 v18, v18, v22
	v_cvt_pk_bf16_f32 v19, v19, v23
	v_cvt_pk_bf16_f32 v20, v20, v24
	s_and_saveexec_b64 s[24:25], vcc
	global_store_dword v[14:15], v17, off
	global_store_dword v[14:15], v18, off offset:64
	global_store_dword v[14:15], v19, off offset:128
	global_store_dword v[14:15], v20, off offset:192
	s_or_b64 exec, exec, s[24:25]
	ds_read_b32 v0, v217 offset:72
	v_lshl_add_u64 v[14:15], v[14:15], 0, s[0:1]
	s_waitcnt lgkmcnt(0)
	v_rcp_f32_e32 v0, v0
	s_nop 0
	v_mul_f32_e32 v17, v90, v0
	v_mul_f32_e32 v18, v74, v0
	v_mul_f32_e32 v19, v58, v0
	v_mul_f32_e32 v20, v42, v0
	v_mov_b32_dpp v21, v17 quad_perm:[1,0,3,2] row_mask:0xf bank_mask:0xf bound_ctrl:1
	v_mov_b32_dpp v22, v18 quad_perm:[1,0,3,2] row_mask:0xf bank_mask:0xf bound_ctrl:1
	v_mov_b32_dpp v23, v19 quad_perm:[1,0,3,2] row_mask:0xf bank_mask:0xf bound_ctrl:1
	v_mov_b32_dpp v24, v20 quad_perm:[1,0,3,2] row_mask:0xf bank_mask:0xf bound_ctrl:1
	v_cvt_pk_bf16_f32 v17, v17, v21
	v_cvt_pk_bf16_f32 v18, v18, v22
	v_cvt_pk_bf16_f32 v19, v19, v23
	v_cvt_pk_bf16_f32 v20, v20, v24
	s_and_saveexec_b64 s[24:25], vcc
	global_store_dword v[14:15], v17, off
	global_store_dword v[14:15], v18, off offset:64
	global_store_dword v[14:15], v19, off offset:128
	global_store_dword v[14:15], v20, off offset:192
	s_or_b64 exec, exec, s[24:25]
	ds_read_b32 v0, v217 offset:76
	v_lshl_add_u64 v[14:15], v[14:15], 0, s[0:1]
	s_waitcnt lgkmcnt(0)
	v_rcp_f32_e32 v0, v0
	s_nop 0
	v_mul_f32_e32 v17, v91, v0
	v_mul_f32_e32 v18, v75, v0
	v_mul_f32_e32 v19, v59, v0
	v_mul_f32_e32 v20, v43, v0
	v_mov_b32_dpp v21, v17 quad_perm:[1,0,3,2] row_mask:0xf bank_mask:0xf bound_ctrl:1
	v_mov_b32_dpp v22, v18 quad_perm:[1,0,3,2] row_mask:0xf bank_mask:0xf bound_ctrl:1
	v_mov_b32_dpp v23, v19 quad_perm:[1,0,3,2] row_mask:0xf bank_mask:0xf bound_ctrl:1
	v_mov_b32_dpp v24, v20 quad_perm:[1,0,3,2] row_mask:0xf bank_mask:0xf bound_ctrl:1
	v_cvt_pk_bf16_f32 v17, v17, v21
	v_cvt_pk_bf16_f32 v18, v18, v22
	v_cvt_pk_bf16_f32 v19, v19, v23
	v_cvt_pk_bf16_f32 v20, v20, v24
	s_and_saveexec_b64 s[24:25], vcc
	global_store_dword v[14:15], v17, off
	global_store_dword v[14:15], v18, off offset:64
	global_store_dword v[14:15], v19, off offset:128
	global_store_dword v[14:15], v20, off offset:192
	s_or_b64 exec, exec, s[24:25]
	ds_read_b32 v0, v217 offset:96
	v_lshl_add_u64 v[14:15], v[14:15], 0, s[22:23]
	s_waitcnt lgkmcnt(0)
	v_rcp_f32_e32 v0, v0
	s_nop 0
	v_mul_f32_e32 v17, v92, v0
	v_mul_f32_e32 v18, v76, v0
	v_mul_f32_e32 v19, v60, v0
	v_mul_f32_e32 v20, v44, v0
	v_mov_b32_dpp v21, v17 quad_perm:[1,0,3,2] row_mask:0xf bank_mask:0xf bound_ctrl:1
	v_mov_b32_dpp v22, v18 quad_perm:[1,0,3,2] row_mask:0xf bank_mask:0xf bound_ctrl:1
	v_mov_b32_dpp v23, v19 quad_perm:[1,0,3,2] row_mask:0xf bank_mask:0xf bound_ctrl:1
	v_mov_b32_dpp v24, v20 quad_perm:[1,0,3,2] row_mask:0xf bank_mask:0xf bound_ctrl:1
	v_cvt_pk_bf16_f32 v17, v17, v21
	v_cvt_pk_bf16_f32 v18, v18, v22
	v_cvt_pk_bf16_f32 v19, v19, v23
	v_cvt_pk_bf16_f32 v20, v20, v24
	s_and_saveexec_b64 s[22:23], vcc
	global_store_dword v[14:15], v17, off
	global_store_dword v[14:15], v18, off offset:64
	global_store_dword v[14:15], v19, off offset:128
	global_store_dword v[14:15], v20, off offset:192
	s_or_b64 exec, exec, s[22:23]
	ds_read_b32 v0, v217 offset:100
	v_lshl_add_u64 v[14:15], v[14:15], 0, s[0:1]
	s_waitcnt lgkmcnt(0)
	v_rcp_f32_e32 v0, v0
	s_nop 0
	v_mul_f32_e32 v17, v93, v0
	v_mul_f32_e32 v18, v77, v0
	v_mul_f32_e32 v19, v61, v0
	v_mul_f32_e32 v20, v45, v0
	v_mov_b32_dpp v21, v17 quad_perm:[1,0,3,2] row_mask:0xf bank_mask:0xf bound_ctrl:1
	v_mov_b32_dpp v22, v18 quad_perm:[1,0,3,2] row_mask:0xf bank_mask:0xf bound_ctrl:1
	v_mov_b32_dpp v23, v19 quad_perm:[1,0,3,2] row_mask:0xf bank_mask:0xf bound_ctrl:1
	v_mov_b32_dpp v24, v20 quad_perm:[1,0,3,2] row_mask:0xf bank_mask:0xf bound_ctrl:1
	v_cvt_pk_bf16_f32 v17, v17, v21
	v_cvt_pk_bf16_f32 v18, v18, v22
	v_cvt_pk_bf16_f32 v19, v19, v23
	v_cvt_pk_bf16_f32 v20, v20, v24
	s_and_saveexec_b64 s[22:23], vcc
	global_store_dword v[14:15], v17, off
	global_store_dword v[14:15], v18, off offset:64
	global_store_dword v[14:15], v19, off offset:128
	global_store_dword v[14:15], v20, off offset:192
	s_or_b64 exec, exec, s[22:23]
	ds_read_b32 v0, v217 offset:104
	v_lshl_add_u64 v[14:15], v[14:15], 0, s[0:1]
	s_waitcnt lgkmcnt(0)
	v_rcp_f32_e32 v0, v0
	s_nop 0
	v_mul_f32_e32 v17, v94, v0
	v_mul_f32_e32 v18, v78, v0
	v_mul_f32_e32 v19, v62, v0
	v_mul_f32_e32 v20, v46, v0
	v_mov_b32_dpp v21, v17 quad_perm:[1,0,3,2] row_mask:0xf bank_mask:0xf bound_ctrl:1
	v_mov_b32_dpp v22, v18 quad_perm:[1,0,3,2] row_mask:0xf bank_mask:0xf bound_ctrl:1
	v_mov_b32_dpp v23, v19 quad_perm:[1,0,3,2] row_mask:0xf bank_mask:0xf bound_ctrl:1
	v_mov_b32_dpp v24, v20 quad_perm:[1,0,3,2] row_mask:0xf bank_mask:0xf bound_ctrl:1
	v_cvt_pk_bf16_f32 v17, v17, v21
	v_cvt_pk_bf16_f32 v18, v18, v22
	v_cvt_pk_bf16_f32 v19, v19, v23
	v_cvt_pk_bf16_f32 v20, v20, v24
	s_and_saveexec_b64 s[22:23], vcc
	global_store_dword v[14:15], v17, off
	global_store_dword v[14:15], v18, off offset:64
	global_store_dword v[14:15], v19, off offset:128
	global_store_dword v[14:15], v20, off offset:192
	s_or_b64 exec, exec, s[22:23]
	ds_read_b32 v0, v217 offset:108
	v_lshl_add_u64 v[14:15], v[14:15], 0, s[0:1]
	s_waitcnt lgkmcnt(0)
	v_rcp_f32_e32 v0, v0
	s_nop 0
	v_mul_f32_e32 v17, v95, v0
	v_mul_f32_e32 v18, v79, v0
	v_mul_f32_e32 v19, v63, v0
	v_mul_f32_e32 v20, v47, v0
	v_mov_b32_dpp v21, v17 quad_perm:[1,0,3,2] row_mask:0xf bank_mask:0xf bound_ctrl:1
	v_mov_b32_dpp v22, v18 quad_perm:[1,0,3,2] row_mask:0xf bank_mask:0xf bound_ctrl:1
	v_mov_b32_dpp v23, v19 quad_perm:[1,0,3,2] row_mask:0xf bank_mask:0xf bound_ctrl:1
	v_mov_b32_dpp v24, v20 quad_perm:[1,0,3,2] row_mask:0xf bank_mask:0xf bound_ctrl:1
	v_cvt_pk_bf16_f32 v17, v17, v21
	v_cvt_pk_bf16_f32 v18, v18, v22
	v_cvt_pk_bf16_f32 v19, v19, v23
	v_cvt_pk_bf16_f32 v20, v20, v24
	s_and_saveexec_b64 s[0:1], vcc
	global_store_dword v[14:15], v17, off
	global_store_dword v[14:15], v18, off offset:64
	global_store_dword v[14:15], v19, off offset:128
	global_store_dword v[14:15], v20, off offset:192
	s_or_b64 exec, exec, s[0:1]
	s_branch .LBB0_505

.LBB0_975:
	v_add_u32_e32 v14, s7, v17
	v_ashrrev_i32_e32 v15, 31, v14
	v_readlane_b32 s80, v255, 24
	v_lshlrev_b64 v[166:167], 13, v[14:15]
	s_and_b64 vcc, exec, s[24:25]
	v_readlane_b32 s81, v255, 25
	s_cbranch_vccz .LBB0_995
	s_cmp_gt_i32 s5, 2
	s_mov_b64 s[78:79], -1
	s_cbranch_scc0 .LBB0_978
	v_lshl_add_u64 v[146:147], s[8:9], 2, v[158:159]
	global_load_dwordx4 v[200:203], v[146:147], off
	global_load_dwordx4 v[204:207], v[146:147], off offset:16
	global_load_dwordx4 v[208:211], v[146:147], off offset:512
	global_load_dwordx4 v[216:219], v[146:147], off offset:528
	s_nop 0
	s_mov_b64 s[78:79], 0
	s_waitcnt vmcnt(0)
	v_mov_b64_e32 v[142:143], v[204:205]
	v_mov_b64_e32 v[144:145], v[206:207]
	v_mov_b64_e32 v[146:147], v[200:201]
	v_mov_b64_e32 v[148:149], v[202:203]
	v_add_f32_e32 v142, v134, v142
	v_mul_f32_e32 v142, 0xbfb8aa3b, v142
	v_add_f32_e32 v143, v135, v143
	v_exp_f32_e32 v142, v142
	v_mul_f32_e32 v143, 0xbfb8aa3b, v143
	v_exp_f32_e32 v143, v143
	v_add_f32_e32 v15, v138, v146
	v_add_f32_e32 v142, 1.0, v142
	v_rcp_f32_e32 v142, v142
	v_add_f32_e32 v143, 1.0, v143
	v_rcp_f32_e32 v143, v143
	v_mul_f32_e32 v15, 0xbfb8aa3b, v15
	v_mul_f32_e32 v142, 0x437f0000, v142
	v_rndne_f32_e32 v142, v142
	v_mul_f32_e32 v143, 0x437f0000, v143
	v_cvt_pk_u8_f32 v142, v142, 0, 0
	v_add_f32_e32 v146, v139, v147
	v_rndne_f32_e32 v143, v143
	v_exp_f32_e32 v15, v15
	v_mul_f32_e32 v146, 0xbfb8aa3b, v146
	v_cvt_pk_u8_f32 v142, v143, 1, v142
	v_add_f32_e32 v143, v140, v148
	v_exp_f32_e32 v146, v146
	v_mul_f32_e32 v143, 0xbfb8aa3b, v143
	v_exp_f32_e32 v143, v143
	v_add_f32_e32 v15, 1.0, v15
	v_rcp_f32_e32 v15, v15
	v_add_f32_e32 v146, 1.0, v146
	v_rcp_f32_e32 v146, v146
	v_add_f32_e32 v143, 1.0, v143
	v_rcp_f32_e32 v143, v143
	v_mul_f32_e32 v15, 0x437f0000, v15
	v_rndne_f32_e32 v15, v15
	v_mul_f32_e32 v146, 0x437f0000, v146
	v_cvt_pk_u8_f32 v15, v15, 0, 0
	v_rndne_f32_e32 v146, v146
	v_mul_f32_e32 v143, 0x437f0000, v143
	v_cvt_pk_u8_f32 v15, v146, 1, v15
	v_rndne_f32_e32 v143, v143
	v_cvt_pk_u8_f32 v15, v143, 2, v15
	v_add_f32_e32 v143, v136, v144
	v_mul_f32_e32 v143, 0xbfb8aa3b, v143
	v_exp_f32_e32 v143, v143
	s_nop 0
	v_add_f32_e32 v143, 1.0, v143
	v_rcp_f32_e32 v143, v143
	s_nop 0
	v_mul_f32_e32 v143, 0x437f0000, v143
	v_rndne_f32_e32 v143, v143
	v_cvt_pk_u8_f32 v143, v143, 2, v142
	v_add_f32_e32 v142, v141, v149
	v_mul_f32_e32 v142, 0xbfb8aa3b, v142
	v_exp_f32_e32 v142, v142
	s_nop 0
	v_add_f32_e32 v142, 1.0, v142
	v_rcp_f32_e32 v142, v142
	s_nop 0
	v_mul_f32_e32 v142, 0x437f0000, v142
	v_rndne_f32_e32 v142, v142
	v_cvt_pk_u8_f32 v142, v142, 3, v15
	v_add_f32_e32 v15, v137, v145
	v_mul_f32_e32 v15, 0xbfb8aa3b, v15
	v_exp_f32_e32 v15, v15
	v_lshl_add_u64 v[144:145], s[58:59], 0, v[166:167]
	v_lshl_add_u64 v[144:145], v[144:145], 0, s[8:9]
	v_lshl_add_u64 v[144:145], v[144:145], 0, s[94:95]
	v_add_f32_e32 v15, 1.0, v15
	v_rcp_f32_e32 v15, v15
	v_lshl_add_u64 v[144:145], v[144:145], 0, v[156:157]
	v_mul_f32_e32 v15, 0x437f0000, v15
	v_rndne_f32_e32 v15, v15
	v_cvt_pk_u8_f32 v143, v15, 3, v143
	global_store_dwordx2 v[144:145], v[142:143], off

.LBB0_986:
	v_cndmask_b32_e64 v15, 0, 1, s[24:25]
	v_cmp_ne_u32_e64 s[46:47], 1, v15
	s_andn2_b64 vcc, exec, s[24:25]
	s_cbranch_vccnz .LBB0_996
	s_cmp_gt_i32 s5, 2
	s_mov_b64 s[24:25], -1
	s_cbranch_scc0 .LBB0_989
	v_lshl_add_u64 v[138:139], s[8:9], 2, v[158:159]
	v_mov_b64_e32 v[134:135], v[208:209]
	v_mov_b64_e32 v[136:137], v[210:211]
	s_nop 0
	v_mov_b64_e32 v[138:139], v[216:217]
	v_mov_b64_e32 v[140:141], v[218:219]
	v_lshl_add_u64 v[142:143], s[58:59], 0, v[166:167]
	v_lshl_add_u64 v[142:143], v[142:143], 0, s[8:9]
	v_lshl_add_u64 v[142:143], v[142:143], 0, s[94:95]
	v_lshl_add_u64 v[142:143], v[142:143], 0, v[156:157]
	s_mov_b64 s[24:25], 0
	v_add_f32_e32 v15, v130, v134
	v_add_f32_e32 v134, v126, v138
	v_add_f32_e32 v135, v131, v135
	v_add_f32_e32 v138, v127, v139
	v_mul_f32_e32 v15, 0xbfb8aa3b, v15
	v_mul_f32_e32 v134, 0xbfb8aa3b, v134
	v_add_f32_e32 v136, v132, v136
	v_add_f32_e32 v139, v128, v140
	v_mul_f32_e32 v135, 0xbfb8aa3b, v135
	v_mul_f32_e32 v138, 0xbfb8aa3b, v138
	v_exp_f32_e32 v15, v15
	v_exp_f32_e32 v134, v134
	v_add_f32_e32 v137, v133, v137
	v_add_f32_e32 v140, v129, v141
	v_mul_f32_e32 v136, 0xbfb8aa3b, v136
	v_mul_f32_e32 v139, 0xbfb8aa3b, v139
	v_exp_f32_e32 v135, v135
	v_exp_f32_e32 v138, v138
	v_mul_f32_e32 v137, 0xbfb8aa3b, v137
	v_mul_f32_e32 v140, 0xbfb8aa3b, v140
	v_exp_f32_e32 v136, v136
	v_exp_f32_e32 v139, v139
	v_exp_f32_e32 v137, v137
	v_exp_f32_e32 v140, v140
	v_add_f32_e32 v15, 1.0, v15
	v_add_f32_e32 v134, 1.0, v134
	v_add_f32_e32 v135, 1.0, v135
	v_add_f32_e32 v138, 1.0, v138
	v_rcp_f32_e32 v15, v15
	v_rcp_f32_e32 v134, v134
	v_add_f32_e32 v136, 1.0, v136
	v_add_f32_e32 v139, 1.0, v139
	v_rcp_f32_e32 v135, v135
	v_rcp_f32_e32 v138, v138
	v_add_f32_e32 v137, 1.0, v137
	v_add_f32_e32 v140, 1.0, v140
	v_rcp_f32_e32 v136, v136
	v_rcp_f32_e32 v139, v139
	v_rcp_f32_e32 v137, v137
	v_rcp_f32_e32 v140, v140
	v_mul_f32_e32 v15, 0x437f0000, v15
	v_mul_f32_e32 v134, 0x437f0000, v134
	v_mul_f32_e32 v135, 0x437f0000, v135
	v_mul_f32_e32 v138, 0x437f0000, v138
	v_rndne_f32_e32 v15, v15
	v_rndne_f32_e32 v134, v134
	v_mul_f32_e32 v136, 0x437f0000, v136
	v_mul_f32_e32 v139, 0x437f0000, v139
	v_rndne_f32_e32 v135, v135
	v_rndne_f32_e32 v138, v138
	v_cvt_pk_u8_f32 v15, v15, 0, 0
	v_cvt_pk_u8_f32 v134, v134, 0, 0
	v_mul_f32_e32 v137, 0x437f0000, v137
	v_mul_f32_e32 v140, 0x437f0000, v140
	v_rndne_f32_e32 v136, v136
	v_rndne_f32_e32 v139, v139
	v_cvt_pk_u8_f32 v15, v135, 1, v15
	v_cvt_pk_u8_f32 v134, v138, 1, v134
	v_rndne_f32_e32 v137, v137
	v_rndne_f32_e32 v140, v140
	v_cvt_pk_u8_f32 v15, v136, 2, v15
	v_cvt_pk_u8_f32 v135, v139, 2, v134
	v_cvt_pk_u8_f32 v134, v137, 3, v15
	v_cvt_pk_u8_f32 v135, v140, 3, v135
	global_store_dwordx2 v[142:143], v[134:135], off offset:128

.LBB0_994:
	ds_read_b128 v[134:137], v173 offset:16
	s_waitcnt lgkmcnt(0)
	v_mov_b32_e32 v138, v135
	v_mov_b32_e32 v139, v136
	v_mov_b32_e32 v135, v137
	v_pk_add_f32 v[134:135], v[138:139], v[134:135]
	s_nop 0
	v_add_f32_e32 v15, v134, v135
	v_fmamk_f32 v15, v15, 0x3c000000, v250
	v_mul_f32_e32 v134, 0x4b800000, v15
	v_cmp_gt_f32_e32 vcc, s28, v15
	s_nop 1
	v_cndmask_b32_e32 v15, v15, v134, vcc
	v_rsq_f32_e32 v15, v15
	s_nop 0
	v_mul_f32_e32 v134, 0x45800000, v15
	v_cndmask_b32_e32 v134, v15, v134, vcc
	v_pk_mul_f32 v[130:131], v[130:131], v[134:135] op_sel_hi:[1,0]
	v_pk_mul_f32 v[132:133], v[132:133], v[134:135] op_sel_hi:[1,0]
	v_pk_mul_f32 v[126:127], v[126:127], v[134:135] op_sel_hi:[1,0]
	v_pk_mul_f32 v[128:129], v[128:129], v[134:135] op_sel_hi:[1,0]
	v_pk_mul_f32 v[136:137], v[12:13], v[132:133]
	v_pk_mul_f32 v[134:135], v[10:11], v[130:131]
	v_pk_mul_f32 v[140:141], v[20:21], v[128:129]
	v_pk_mul_f32 v[138:139], v[18:19], v[126:127]
	s_branch .LBB0_998

.LBB0_999:
	v_or_b32_e32 v136, 16, v14
	v_ashrrev_i32_e32 v137, 31, v136
	s_and_b64 vcc, exec, s[46:47]
	v_lshlrev_b64 v[134:135], 13, v[136:137]
	s_cbranch_vccnz .LBB0_1017
	s_cmp_gt_i32 s5, 2
	s_mov_b64 s[24:25], -1
	s_cbranch_scc0 .LBB0_1002
	v_lshl_add_u64 v[130:131], s[8:9], 2, v[158:159]
	v_mov_b64_e32 v[126:127], v[204:205]
	v_mov_b64_e32 v[128:129], v[206:207]
	s_nop 0
	v_mov_b64_e32 v[130:131], v[200:201]
	v_mov_b64_e32 v[132:133], v[202:203]
	s_mov_b64 s[24:25], 0
	v_add_f32_e32 v126, v118, v126
	v_mul_f32_e32 v126, 0xbfb8aa3b, v126
	v_add_f32_e32 v127, v119, v127
	v_exp_f32_e32 v126, v126
	v_mul_f32_e32 v127, 0xbfb8aa3b, v127
	v_exp_f32_e32 v127, v127
	v_add_f32_e32 v15, v122, v130
	v_add_f32_e32 v126, 1.0, v126
	v_rcp_f32_e32 v126, v126
	v_add_f32_e32 v127, 1.0, v127
	v_rcp_f32_e32 v127, v127
	v_mul_f32_e32 v15, 0xbfb8aa3b, v15
	v_mul_f32_e32 v126, 0x437f0000, v126
	v_rndne_f32_e32 v126, v126
	v_mul_f32_e32 v127, 0x437f0000, v127
	v_cvt_pk_u8_f32 v126, v126, 0, 0
	v_add_f32_e32 v130, v123, v131
	v_rndne_f32_e32 v127, v127
	v_exp_f32_e32 v15, v15
	v_mul_f32_e32 v130, 0xbfb8aa3b, v130
	v_cvt_pk_u8_f32 v126, v127, 1, v126
	v_add_f32_e32 v127, v124, v132
	v_exp_f32_e32 v130, v130
	v_mul_f32_e32 v127, 0xbfb8aa3b, v127
	v_exp_f32_e32 v127, v127
	v_add_f32_e32 v15, 1.0, v15
	v_rcp_f32_e32 v15, v15
	v_add_f32_e32 v130, 1.0, v130
	v_rcp_f32_e32 v130, v130
	v_add_f32_e32 v127, 1.0, v127
	v_rcp_f32_e32 v127, v127
	v_mul_f32_e32 v15, 0x437f0000, v15
	v_rndne_f32_e32 v15, v15
	v_mul_f32_e32 v130, 0x437f0000, v130
	v_cvt_pk_u8_f32 v15, v15, 0, 0
	v_rndne_f32_e32 v130, v130
	v_mul_f32_e32 v127, 0x437f0000, v127
	v_cvt_pk_u8_f32 v15, v130, 1, v15
	v_rndne_f32_e32 v127, v127
	v_cvt_pk_u8_f32 v15, v127, 2, v15
	v_add_f32_e32 v127, v120, v128
	v_mul_f32_e32 v127, 0xbfb8aa3b, v127
	v_exp_f32_e32 v127, v127
	s_nop 0
	v_add_f32_e32 v127, 1.0, v127
	v_rcp_f32_e32 v127, v127
	s_nop 0
	v_mul_f32_e32 v127, 0x437f0000, v127
	v_rndne_f32_e32 v127, v127
	v_cvt_pk_u8_f32 v127, v127, 2, v126
	v_add_f32_e32 v126, v125, v133
	v_mul_f32_e32 v126, 0xbfb8aa3b, v126
	v_exp_f32_e32 v126, v126
	s_nop 0
	v_add_f32_e32 v126, 1.0, v126
	v_rcp_f32_e32 v126, v126
	s_nop 0
	v_mul_f32_e32 v126, 0x437f0000, v126
	v_rndne_f32_e32 v126, v126
	v_cvt_pk_u8_f32 v126, v126, 3, v15
	v_add_f32_e32 v15, v121, v129
	v_mul_f32_e32 v15, 0xbfb8aa3b, v15
	v_exp_f32_e32 v15, v15
	v_lshl_add_u64 v[128:129], s[58:59], 0, v[134:135]
	v_lshl_add_u64 v[128:129], v[128:129], 0, s[8:9]
	v_lshl_add_u64 v[128:129], v[128:129], 0, s[94:95]
	v_add_f32_e32 v15, 1.0, v15
	v_rcp_f32_e32 v15, v15
	v_lshl_add_u64 v[128:129], v[128:129], 0, v[156:157]
	v_mul_f32_e32 v15, 0x437f0000, v15
	v_rndne_f32_e32 v15, v15
	v_cvt_pk_u8_f32 v127, v15, 3, v127
	global_store_dwordx2 v[128:129], v[126:127], off

.LBB0_1007:
	ds_read_b128 v[126:129], v176
	s_waitcnt lgkmcnt(0)
	v_mov_b32_e32 v130, v127
	v_mov_b32_e32 v131, v128
	v_mov_b32_e32 v127, v129
	v_pk_add_f32 v[126:127], v[130:131], v[126:127]
	s_nop 0
	v_add_f32_e32 v15, v126, v127
	v_fmamk_f32 v15, v15, 0x3c000000, v250
	v_mul_f32_e32 v126, 0x4b800000, v15
	v_cmp_gt_f32_e32 vcc, s28, v15
	s_nop 1
	v_cndmask_b32_e32 v15, v15, v126, vcc
	v_rsq_f32_e32 v15, v15
	s_nop 0
	v_mul_f32_e32 v126, 0x45800000, v15
	v_cndmask_b32_e32 v126, v15, v126, vcc
	v_pk_mul_f32 v[122:123], v[122:123], v[126:127] op_sel_hi:[1,0]
	v_pk_mul_f32 v[124:125], v[124:125], v[126:127] op_sel_hi:[1,0]
	v_pk_mul_f32 v[118:119], v[118:119], v[126:127] op_sel_hi:[1,0]
	v_pk_mul_f32 v[120:121], v[120:121], v[126:127] op_sel_hi:[1,0]
	v_pk_mul_f32 v[128:129], v[12:13], v[124:125]
	v_pk_mul_f32 v[126:127], v[10:11], v[122:123]
	v_pk_mul_f32 v[132:133], v[20:21], v[120:121]
	v_pk_mul_f32 v[130:131], v[18:19], v[118:119]
	v_mad_i64_i32 v[118:119], s[22:23], s20, v136, 0
	v_lshl_add_u64 v[136:137], v[118:119], 1, v[164:165]
	s_branch .LBB0_1019

.LBB0_1009:
	s_cmp_gt_i32 s5, 2
	s_mov_b64 s[24:25], -1
	s_cbranch_scc0 .LBB0_1011
	v_lshl_add_u64 v[122:123], s[8:9], 2, v[158:159]
	v_mov_b64_e32 v[118:119], v[208:209]
	v_mov_b64_e32 v[120:121], v[210:211]
	s_nop 0
	v_mov_b64_e32 v[122:123], v[216:217]
	v_mov_b64_e32 v[124:125], v[218:219]
	v_lshl_add_u64 v[126:127], s[58:59], 0, v[134:135]
	v_lshl_add_u64 v[126:127], v[126:127], 0, s[8:9]
	v_lshl_add_u64 v[126:127], v[126:127], 0, s[94:95]
	v_lshl_add_u64 v[126:127], v[126:127], 0, v[156:157]
	s_mov_b64 s[24:25], 0
	v_add_f32_e32 v15, v114, v118
	v_add_f32_e32 v118, v110, v122
	v_add_f32_e32 v119, v115, v119
	v_add_f32_e32 v122, v111, v123
	v_mul_f32_e32 v15, 0xbfb8aa3b, v15
	v_mul_f32_e32 v118, 0xbfb8aa3b, v118
	v_add_f32_e32 v120, v116, v120
	v_add_f32_e32 v123, v112, v124
	v_mul_f32_e32 v119, 0xbfb8aa3b, v119
	v_mul_f32_e32 v122, 0xbfb8aa3b, v122
	v_exp_f32_e32 v15, v15
	v_exp_f32_e32 v118, v118
	v_add_f32_e32 v121, v117, v121
	v_add_f32_e32 v124, v113, v125
	v_mul_f32_e32 v120, 0xbfb8aa3b, v120
	v_mul_f32_e32 v123, 0xbfb8aa3b, v123
	v_exp_f32_e32 v119, v119
	v_exp_f32_e32 v122, v122
	v_mul_f32_e32 v121, 0xbfb8aa3b, v121
	v_mul_f32_e32 v124, 0xbfb8aa3b, v124
	v_exp_f32_e32 v120, v120
	v_exp_f32_e32 v123, v123
	v_exp_f32_e32 v121, v121
	v_exp_f32_e32 v124, v124
	v_add_f32_e32 v15, 1.0, v15
	v_add_f32_e32 v118, 1.0, v118
	v_add_f32_e32 v119, 1.0, v119
	v_add_f32_e32 v122, 1.0, v122
	v_rcp_f32_e32 v15, v15
	v_rcp_f32_e32 v118, v118
	v_add_f32_e32 v120, 1.0, v120
	v_add_f32_e32 v123, 1.0, v123
	v_rcp_f32_e32 v119, v119
	v_rcp_f32_e32 v122, v122
	v_add_f32_e32 v121, 1.0, v121
	v_add_f32_e32 v124, 1.0, v124
	v_rcp_f32_e32 v120, v120
	v_rcp_f32_e32 v123, v123
	v_rcp_f32_e32 v121, v121
	v_rcp_f32_e32 v124, v124
	v_mul_f32_e32 v15, 0x437f0000, v15
	v_mul_f32_e32 v118, 0x437f0000, v118
	v_mul_f32_e32 v119, 0x437f0000, v119
	v_mul_f32_e32 v122, 0x437f0000, v122
	v_rndne_f32_e32 v15, v15
	v_rndne_f32_e32 v118, v118
	v_mul_f32_e32 v120, 0x437f0000, v120
	v_mul_f32_e32 v123, 0x437f0000, v123
	v_rndne_f32_e32 v119, v119
	v_rndne_f32_e32 v122, v122
	v_cvt_pk_u8_f32 v15, v15, 0, 0
	v_cvt_pk_u8_f32 v118, v118, 0, 0
	v_mul_f32_e32 v121, 0x437f0000, v121
	v_mul_f32_e32 v124, 0x437f0000, v124
	v_rndne_f32_e32 v120, v120
	v_rndne_f32_e32 v123, v123
	v_cvt_pk_u8_f32 v15, v119, 1, v15
	v_cvt_pk_u8_f32 v118, v122, 1, v118
	v_rndne_f32_e32 v121, v121
	v_rndne_f32_e32 v124, v124
	v_cvt_pk_u8_f32 v15, v120, 2, v15
	v_cvt_pk_u8_f32 v119, v123, 2, v118
	v_cvt_pk_u8_f32 v118, v121, 3, v15
	v_cvt_pk_u8_f32 v119, v124, 3, v119
	global_store_dwordx2 v[126:127], v[118:119], off offset:128

.LBB0_1016:
	ds_read_b128 v[118:121], v176 offset:16
	s_waitcnt lgkmcnt(0)
	v_mov_b32_e32 v122, v119
	v_mov_b32_e32 v123, v120
	v_mov_b32_e32 v119, v121
	v_pk_add_f32 v[118:119], v[122:123], v[118:119]
	s_nop 0
	v_add_f32_e32 v15, v118, v119
	v_fmamk_f32 v15, v15, 0x3c000000, v250
	v_mul_f32_e32 v118, 0x4b800000, v15
	v_cmp_gt_f32_e32 vcc, s28, v15
	s_nop 1
	v_cndmask_b32_e32 v15, v15, v118, vcc
	v_rsq_f32_e32 v15, v15
	s_nop 0
	v_mul_f32_e32 v118, 0x45800000, v15
	v_cndmask_b32_e32 v118, v15, v118, vcc
	v_pk_mul_f32 v[114:115], v[114:115], v[118:119] op_sel_hi:[1,0]
	v_pk_mul_f32 v[116:117], v[116:117], v[118:119] op_sel_hi:[1,0]
	v_pk_mul_f32 v[110:111], v[110:111], v[118:119] op_sel_hi:[1,0]
	v_pk_mul_f32 v[112:113], v[112:113], v[118:119] op_sel_hi:[1,0]
	v_pk_mul_f32 v[120:121], v[12:13], v[116:117]
	v_pk_mul_f32 v[118:119], v[10:11], v[114:115]
	v_pk_mul_f32 v[124:125], v[20:21], v[112:113]
	v_pk_mul_f32 v[122:123], v[18:19], v[110:111]
	s_branch .LBB0_1022

.LBB0_1023:
	v_or_b32_e32 v120, 32, v14
	v_ashrrev_i32_e32 v121, 31, v120
	s_and_b64 vcc, exec, s[46:47]
	v_lshlrev_b64 v[118:119], 13, v[120:121]
	s_cbranch_vccnz .LBB0_1041
	s_cmp_gt_i32 s5, 2
	s_mov_b64 s[24:25], -1
	s_cbranch_scc0 .LBB0_1026
	v_lshl_add_u64 v[114:115], s[8:9], 2, v[158:159]
	v_mov_b64_e32 v[110:111], v[204:205]
	v_mov_b64_e32 v[112:113], v[206:207]
	s_nop 0
	v_mov_b64_e32 v[114:115], v[200:201]
	v_mov_b64_e32 v[116:117], v[202:203]
	s_mov_b64 s[24:25], 0
	v_add_f32_e32 v110, v102, v110
	v_mul_f32_e32 v110, 0xbfb8aa3b, v110
	v_add_f32_e32 v111, v103, v111
	v_exp_f32_e32 v110, v110
	v_mul_f32_e32 v111, 0xbfb8aa3b, v111
	v_exp_f32_e32 v111, v111
	v_add_f32_e32 v15, v106, v114
	v_add_f32_e32 v110, 1.0, v110
	v_rcp_f32_e32 v110, v110
	v_add_f32_e32 v111, 1.0, v111
	v_rcp_f32_e32 v111, v111
	v_mul_f32_e32 v15, 0xbfb8aa3b, v15
	v_mul_f32_e32 v110, 0x437f0000, v110
	v_rndne_f32_e32 v110, v110
	v_mul_f32_e32 v111, 0x437f0000, v111
	v_cvt_pk_u8_f32 v110, v110, 0, 0
	v_add_f32_e32 v114, v107, v115
	v_rndne_f32_e32 v111, v111
	v_exp_f32_e32 v15, v15
	v_mul_f32_e32 v114, 0xbfb8aa3b, v114
	v_cvt_pk_u8_f32 v110, v111, 1, v110
	v_add_f32_e32 v111, v108, v116
	v_exp_f32_e32 v114, v114
	v_mul_f32_e32 v111, 0xbfb8aa3b, v111
	v_exp_f32_e32 v111, v111
	v_add_f32_e32 v15, 1.0, v15
	v_rcp_f32_e32 v15, v15
	v_add_f32_e32 v114, 1.0, v114
	v_rcp_f32_e32 v114, v114
	v_add_f32_e32 v111, 1.0, v111
	v_rcp_f32_e32 v111, v111
	v_mul_f32_e32 v15, 0x437f0000, v15
	v_rndne_f32_e32 v15, v15
	v_mul_f32_e32 v114, 0x437f0000, v114
	v_cvt_pk_u8_f32 v15, v15, 0, 0
	v_rndne_f32_e32 v114, v114
	v_mul_f32_e32 v111, 0x437f0000, v111
	v_cvt_pk_u8_f32 v15, v114, 1, v15
	v_rndne_f32_e32 v111, v111
	v_cvt_pk_u8_f32 v15, v111, 2, v15
	v_add_f32_e32 v111, v104, v112
	v_mul_f32_e32 v111, 0xbfb8aa3b, v111
	v_exp_f32_e32 v111, v111
	s_nop 0
	v_add_f32_e32 v111, 1.0, v111
	v_rcp_f32_e32 v111, v111
	s_nop 0
	v_mul_f32_e32 v111, 0x437f0000, v111
	v_rndne_f32_e32 v111, v111
	v_cvt_pk_u8_f32 v111, v111, 2, v110
	v_add_f32_e32 v110, v109, v117
	v_mul_f32_e32 v110, 0xbfb8aa3b, v110
	v_exp_f32_e32 v110, v110
	s_nop 0
	v_add_f32_e32 v110, 1.0, v110
	v_rcp_f32_e32 v110, v110
	s_nop 0
	v_mul_f32_e32 v110, 0x437f0000, v110
	v_rndne_f32_e32 v110, v110
	v_cvt_pk_u8_f32 v110, v110, 3, v15
	v_add_f32_e32 v15, v105, v113
	v_mul_f32_e32 v15, 0xbfb8aa3b, v15
	v_exp_f32_e32 v15, v15
	v_lshl_add_u64 v[112:113], s[58:59], 0, v[118:119]
	v_lshl_add_u64 v[112:113], v[112:113], 0, s[8:9]
	v_lshl_add_u64 v[112:113], v[112:113], 0, s[94:95]
	v_add_f32_e32 v15, 1.0, v15
	v_rcp_f32_e32 v15, v15
	v_lshl_add_u64 v[112:113], v[112:113], 0, v[156:157]
	v_mul_f32_e32 v15, 0x437f0000, v15
	v_rndne_f32_e32 v15, v15
	v_cvt_pk_u8_f32 v111, v15, 3, v111
	global_store_dwordx2 v[112:113], v[110:111], off

.LBB0_1031:
	ds_read_b128 v[110:113], v179
	s_waitcnt lgkmcnt(0)
	v_mov_b32_e32 v114, v111
	v_mov_b32_e32 v115, v112
	v_mov_b32_e32 v111, v113
	v_pk_add_f32 v[110:111], v[114:115], v[110:111]
	s_nop 0
	v_add_f32_e32 v15, v110, v111
	v_fmamk_f32 v15, v15, 0x3c000000, v250
	v_mul_f32_e32 v110, 0x4b800000, v15
	v_cmp_gt_f32_e32 vcc, s28, v15
	s_nop 1
	v_cndmask_b32_e32 v15, v15, v110, vcc
	v_rsq_f32_e32 v15, v15
	s_nop 0
	v_mul_f32_e32 v110, 0x45800000, v15
	v_cndmask_b32_e32 v110, v15, v110, vcc
	v_pk_mul_f32 v[106:107], v[106:107], v[110:111] op_sel_hi:[1,0]
	v_pk_mul_f32 v[108:109], v[108:109], v[110:111] op_sel_hi:[1,0]
	v_pk_mul_f32 v[102:103], v[102:103], v[110:111] op_sel_hi:[1,0]
	v_pk_mul_f32 v[104:105], v[104:105], v[110:111] op_sel_hi:[1,0]
	v_pk_mul_f32 v[112:113], v[12:13], v[108:109]
	v_pk_mul_f32 v[110:111], v[10:11], v[106:107]
	v_pk_mul_f32 v[116:117], v[20:21], v[104:105]
	v_pk_mul_f32 v[114:115], v[18:19], v[102:103]
	v_mad_i64_i32 v[102:103], s[22:23], s20, v120, 0
	v_lshl_add_u64 v[120:121], v[102:103], 1, v[164:165]
	s_branch .LBB0_1043

.LBB0_1033:
	s_cmp_gt_i32 s5, 2
	s_mov_b64 s[24:25], -1
	s_cbranch_scc0 .LBB0_1035
	v_lshl_add_u64 v[106:107], s[8:9], 2, v[158:159]
	v_mov_b64_e32 v[102:103], v[208:209]
	v_mov_b64_e32 v[104:105], v[210:211]
	s_nop 0
	v_mov_b64_e32 v[106:107], v[216:217]
	v_mov_b64_e32 v[108:109], v[218:219]
	v_lshl_add_u64 v[110:111], s[58:59], 0, v[118:119]
	v_lshl_add_u64 v[110:111], v[110:111], 0, s[8:9]
	v_lshl_add_u64 v[110:111], v[110:111], 0, s[94:95]
	v_lshl_add_u64 v[110:111], v[110:111], 0, v[156:157]
	s_mov_b64 s[24:25], 0
	v_add_f32_e32 v15, v98, v102
	v_add_f32_e32 v102, v94, v106
	v_add_f32_e32 v103, v99, v103
	v_add_f32_e32 v106, v95, v107
	v_mul_f32_e32 v15, 0xbfb8aa3b, v15
	v_mul_f32_e32 v102, 0xbfb8aa3b, v102
	v_add_f32_e32 v104, v100, v104
	v_add_f32_e32 v107, v96, v108
	v_mul_f32_e32 v103, 0xbfb8aa3b, v103
	v_mul_f32_e32 v106, 0xbfb8aa3b, v106
	v_exp_f32_e32 v15, v15
	v_exp_f32_e32 v102, v102
	v_add_f32_e32 v105, v101, v105
	v_add_f32_e32 v108, v97, v109
	v_mul_f32_e32 v104, 0xbfb8aa3b, v104
	v_mul_f32_e32 v107, 0xbfb8aa3b, v107
	v_exp_f32_e32 v103, v103
	v_exp_f32_e32 v106, v106
	v_mul_f32_e32 v105, 0xbfb8aa3b, v105
	v_mul_f32_e32 v108, 0xbfb8aa3b, v108
	v_exp_f32_e32 v104, v104
	v_exp_f32_e32 v107, v107
	v_exp_f32_e32 v105, v105
	v_exp_f32_e32 v108, v108
	v_add_f32_e32 v15, 1.0, v15
	v_add_f32_e32 v102, 1.0, v102
	v_add_f32_e32 v103, 1.0, v103
	v_add_f32_e32 v106, 1.0, v106
	v_rcp_f32_e32 v15, v15
	v_rcp_f32_e32 v102, v102
	v_add_f32_e32 v104, 1.0, v104
	v_add_f32_e32 v107, 1.0, v107
	v_rcp_f32_e32 v103, v103
	v_rcp_f32_e32 v106, v106
	v_add_f32_e32 v105, 1.0, v105
	v_add_f32_e32 v108, 1.0, v108
	v_rcp_f32_e32 v104, v104
	v_rcp_f32_e32 v107, v107
	v_rcp_f32_e32 v105, v105
	v_rcp_f32_e32 v108, v108
	v_mul_f32_e32 v15, 0x437f0000, v15
	v_mul_f32_e32 v102, 0x437f0000, v102
	v_mul_f32_e32 v103, 0x437f0000, v103
	v_mul_f32_e32 v106, 0x437f0000, v106
	v_rndne_f32_e32 v15, v15
	v_rndne_f32_e32 v102, v102
	v_mul_f32_e32 v104, 0x437f0000, v104
	v_mul_f32_e32 v107, 0x437f0000, v107
	v_rndne_f32_e32 v103, v103
	v_rndne_f32_e32 v106, v106
	v_cvt_pk_u8_f32 v15, v15, 0, 0
	v_cvt_pk_u8_f32 v102, v102, 0, 0
	v_mul_f32_e32 v105, 0x437f0000, v105
	v_mul_f32_e32 v108, 0x437f0000, v108
	v_rndne_f32_e32 v104, v104
	v_rndne_f32_e32 v107, v107
	v_cvt_pk_u8_f32 v15, v103, 1, v15
	v_cvt_pk_u8_f32 v102, v106, 1, v102
	v_rndne_f32_e32 v105, v105
	v_rndne_f32_e32 v108, v108
	v_cvt_pk_u8_f32 v15, v104, 2, v15
	v_cvt_pk_u8_f32 v103, v107, 2, v102
	v_cvt_pk_u8_f32 v102, v105, 3, v15
	v_cvt_pk_u8_f32 v103, v108, 3, v103
	global_store_dwordx2 v[110:111], v[102:103], off offset:128

.LBB0_1040:
	ds_read_b128 v[102:105], v179 offset:16
	s_waitcnt lgkmcnt(0)
	v_mov_b32_e32 v106, v103
	v_mov_b32_e32 v107, v104
	v_mov_b32_e32 v103, v105
	v_pk_add_f32 v[102:103], v[106:107], v[102:103]
	s_nop 0
	v_add_f32_e32 v15, v102, v103
	v_fmamk_f32 v15, v15, 0x3c000000, v250
	v_mul_f32_e32 v102, 0x4b800000, v15
	v_cmp_gt_f32_e32 vcc, s28, v15
	s_nop 1
	v_cndmask_b32_e32 v15, v15, v102, vcc
	v_rsq_f32_e32 v15, v15
	s_nop 0
	v_mul_f32_e32 v102, 0x45800000, v15
	v_cndmask_b32_e32 v102, v15, v102, vcc
	v_pk_mul_f32 v[98:99], v[98:99], v[102:103] op_sel_hi:[1,0]
	v_pk_mul_f32 v[100:101], v[100:101], v[102:103] op_sel_hi:[1,0]
	v_pk_mul_f32 v[94:95], v[94:95], v[102:103] op_sel_hi:[1,0]
	v_pk_mul_f32 v[96:97], v[96:97], v[102:103] op_sel_hi:[1,0]
	v_pk_mul_f32 v[104:105], v[12:13], v[100:101]
	v_pk_mul_f32 v[102:103], v[10:11], v[98:99]
	v_pk_mul_f32 v[108:109], v[20:21], v[96:97]
	v_pk_mul_f32 v[106:107], v[18:19], v[94:95]
	s_branch .LBB0_1046

.LBB0_1047:
	v_or_b32_e32 v104, 48, v14
	v_ashrrev_i32_e32 v105, 31, v104
	s_and_b64 vcc, exec, s[46:47]
	v_lshlrev_b64 v[102:103], 13, v[104:105]
	s_cbranch_vccnz .LBB0_1065
	s_cmp_gt_i32 s5, 2
	s_mov_b64 s[24:25], -1
	s_cbranch_scc0 .LBB0_1050
	v_lshl_add_u64 v[98:99], s[8:9], 2, v[158:159]
	v_mov_b64_e32 v[94:95], v[204:205]
	v_mov_b64_e32 v[96:97], v[206:207]
	s_nop 0
	v_mov_b64_e32 v[98:99], v[200:201]
	v_mov_b64_e32 v[100:101], v[202:203]
	s_mov_b64 s[24:25], 0
	v_add_f32_e32 v94, v86, v94
	v_mul_f32_e32 v94, 0xbfb8aa3b, v94
	v_add_f32_e32 v95, v87, v95
	v_exp_f32_e32 v94, v94
	v_mul_f32_e32 v95, 0xbfb8aa3b, v95
	v_exp_f32_e32 v95, v95
	v_add_f32_e32 v15, v90, v98
	v_add_f32_e32 v94, 1.0, v94
	v_rcp_f32_e32 v94, v94
	v_add_f32_e32 v95, 1.0, v95
	v_rcp_f32_e32 v95, v95
	v_mul_f32_e32 v15, 0xbfb8aa3b, v15
	v_mul_f32_e32 v94, 0x437f0000, v94
	v_rndne_f32_e32 v94, v94
	v_mul_f32_e32 v95, 0x437f0000, v95
	v_cvt_pk_u8_f32 v94, v94, 0, 0
	v_add_f32_e32 v98, v91, v99
	v_rndne_f32_e32 v95, v95
	v_exp_f32_e32 v15, v15
	v_mul_f32_e32 v98, 0xbfb8aa3b, v98
	v_cvt_pk_u8_f32 v94, v95, 1, v94
	v_add_f32_e32 v95, v92, v100
	v_exp_f32_e32 v98, v98
	v_mul_f32_e32 v95, 0xbfb8aa3b, v95
	v_exp_f32_e32 v95, v95
	v_add_f32_e32 v15, 1.0, v15
	v_rcp_f32_e32 v15, v15
	v_add_f32_e32 v98, 1.0, v98
	v_rcp_f32_e32 v98, v98
	v_add_f32_e32 v95, 1.0, v95
	v_rcp_f32_e32 v95, v95
	v_mul_f32_e32 v15, 0x437f0000, v15
	v_rndne_f32_e32 v15, v15
	v_mul_f32_e32 v98, 0x437f0000, v98
	v_cvt_pk_u8_f32 v15, v15, 0, 0
	v_rndne_f32_e32 v98, v98
	v_mul_f32_e32 v95, 0x437f0000, v95
	v_cvt_pk_u8_f32 v15, v98, 1, v15
	v_rndne_f32_e32 v95, v95
	v_cvt_pk_u8_f32 v15, v95, 2, v15
	v_add_f32_e32 v95, v88, v96
	v_mul_f32_e32 v95, 0xbfb8aa3b, v95
	v_exp_f32_e32 v95, v95
	s_nop 0
	v_add_f32_e32 v95, 1.0, v95
	v_rcp_f32_e32 v95, v95
	s_nop 0
	v_mul_f32_e32 v95, 0x437f0000, v95
	v_rndne_f32_e32 v95, v95
	v_cvt_pk_u8_f32 v95, v95, 2, v94
	v_add_f32_e32 v94, v93, v101
	v_mul_f32_e32 v94, 0xbfb8aa3b, v94
	v_exp_f32_e32 v94, v94
	s_nop 0
	v_add_f32_e32 v94, 1.0, v94
	v_rcp_f32_e32 v94, v94
	s_nop 0
	v_mul_f32_e32 v94, 0x437f0000, v94
	v_rndne_f32_e32 v94, v94
	v_cvt_pk_u8_f32 v94, v94, 3, v15
	v_add_f32_e32 v15, v89, v97
	v_mul_f32_e32 v15, 0xbfb8aa3b, v15
	v_exp_f32_e32 v15, v15
	v_lshl_add_u64 v[96:97], s[58:59], 0, v[102:103]
	v_lshl_add_u64 v[96:97], v[96:97], 0, s[8:9]
	v_lshl_add_u64 v[96:97], v[96:97], 0, s[94:95]
	v_add_f32_e32 v15, 1.0, v15
	v_rcp_f32_e32 v15, v15
	v_lshl_add_u64 v[96:97], v[96:97], 0, v[156:157]
	v_mul_f32_e32 v15, 0x437f0000, v15
	v_rndne_f32_e32 v15, v15
	v_cvt_pk_u8_f32 v95, v15, 3, v95
	global_store_dwordx2 v[96:97], v[94:95], off

.LBB0_1055:
	ds_read_b128 v[94:97], v182
	s_waitcnt lgkmcnt(0)
	v_mov_b32_e32 v98, v95
	v_mov_b32_e32 v99, v96
	v_mov_b32_e32 v95, v97
	v_pk_add_f32 v[94:95], v[98:99], v[94:95]
	s_nop 0
	v_add_f32_e32 v15, v94, v95
	v_fmamk_f32 v15, v15, 0x3c000000, v250
	v_mul_f32_e32 v94, 0x4b800000, v15
	v_cmp_gt_f32_e32 vcc, s28, v15
	s_nop 1
	v_cndmask_b32_e32 v15, v15, v94, vcc
	v_rsq_f32_e32 v15, v15
	s_nop 0
	v_mul_f32_e32 v94, 0x45800000, v15
	v_cndmask_b32_e32 v94, v15, v94, vcc
	v_pk_mul_f32 v[90:91], v[90:91], v[94:95] op_sel_hi:[1,0]
	v_pk_mul_f32 v[92:93], v[92:93], v[94:95] op_sel_hi:[1,0]
	v_pk_mul_f32 v[86:87], v[86:87], v[94:95] op_sel_hi:[1,0]
	v_pk_mul_f32 v[88:89], v[88:89], v[94:95] op_sel_hi:[1,0]
	v_pk_mul_f32 v[96:97], v[12:13], v[92:93]
	v_pk_mul_f32 v[94:95], v[10:11], v[90:91]
	v_pk_mul_f32 v[100:101], v[20:21], v[88:89]
	v_pk_mul_f32 v[98:99], v[18:19], v[86:87]
	v_mad_i64_i32 v[86:87], s[22:23], s20, v104, 0
	v_lshl_add_u64 v[104:105], v[86:87], 1, v[164:165]
	s_branch .LBB0_1067

.LBB0_1057:
	s_cmp_gt_i32 s5, 2
	s_mov_b64 s[24:25], -1
	s_cbranch_scc0 .LBB0_1059
	v_lshl_add_u64 v[90:91], s[8:9], 2, v[158:159]
	v_mov_b64_e32 v[86:87], v[208:209]
	v_mov_b64_e32 v[88:89], v[210:211]
	s_nop 0
	v_mov_b64_e32 v[90:91], v[216:217]
	v_mov_b64_e32 v[92:93], v[218:219]
	v_lshl_add_u64 v[94:95], s[58:59], 0, v[102:103]
	v_lshl_add_u64 v[94:95], v[94:95], 0, s[8:9]
	v_lshl_add_u64 v[94:95], v[94:95], 0, s[94:95]
	v_lshl_add_u64 v[94:95], v[94:95], 0, v[156:157]
	s_mov_b64 s[24:25], 0
	v_add_f32_e32 v15, v82, v86
	v_add_f32_e32 v86, v78, v90
	v_add_f32_e32 v87, v83, v87
	v_add_f32_e32 v90, v79, v91
	v_mul_f32_e32 v15, 0xbfb8aa3b, v15
	v_mul_f32_e32 v86, 0xbfb8aa3b, v86
	v_add_f32_e32 v88, v84, v88
	v_add_f32_e32 v91, v80, v92
	v_mul_f32_e32 v87, 0xbfb8aa3b, v87
	v_mul_f32_e32 v90, 0xbfb8aa3b, v90
	v_exp_f32_e32 v15, v15
	v_exp_f32_e32 v86, v86
	v_add_f32_e32 v89, v85, v89
	v_add_f32_e32 v92, v81, v93
	v_mul_f32_e32 v88, 0xbfb8aa3b, v88
	v_mul_f32_e32 v91, 0xbfb8aa3b, v91
	v_exp_f32_e32 v87, v87
	v_exp_f32_e32 v90, v90
	v_mul_f32_e32 v89, 0xbfb8aa3b, v89
	v_mul_f32_e32 v92, 0xbfb8aa3b, v92
	v_exp_f32_e32 v88, v88
	v_exp_f32_e32 v91, v91
	v_exp_f32_e32 v89, v89
	v_exp_f32_e32 v92, v92
	v_add_f32_e32 v15, 1.0, v15
	v_add_f32_e32 v86, 1.0, v86
	v_add_f32_e32 v87, 1.0, v87
	v_add_f32_e32 v90, 1.0, v90
	v_rcp_f32_e32 v15, v15
	v_rcp_f32_e32 v86, v86
	v_add_f32_e32 v88, 1.0, v88
	v_add_f32_e32 v91, 1.0, v91
	v_rcp_f32_e32 v87, v87
	v_rcp_f32_e32 v90, v90
	v_add_f32_e32 v89, 1.0, v89
	v_add_f32_e32 v92, 1.0, v92
	v_rcp_f32_e32 v88, v88
	v_rcp_f32_e32 v91, v91
	v_rcp_f32_e32 v89, v89
	v_rcp_f32_e32 v92, v92
	v_mul_f32_e32 v15, 0x437f0000, v15
	v_mul_f32_e32 v86, 0x437f0000, v86
	v_mul_f32_e32 v87, 0x437f0000, v87
	v_mul_f32_e32 v90, 0x437f0000, v90
	v_rndne_f32_e32 v15, v15
	v_rndne_f32_e32 v86, v86
	v_mul_f32_e32 v88, 0x437f0000, v88
	v_mul_f32_e32 v91, 0x437f0000, v91
	v_rndne_f32_e32 v87, v87
	v_rndne_f32_e32 v90, v90
	v_cvt_pk_u8_f32 v15, v15, 0, 0
	v_cvt_pk_u8_f32 v86, v86, 0, 0
	v_mul_f32_e32 v89, 0x437f0000, v89
	v_mul_f32_e32 v92, 0x437f0000, v92
	v_rndne_f32_e32 v88, v88
	v_rndne_f32_e32 v91, v91
	v_cvt_pk_u8_f32 v15, v87, 1, v15
	v_cvt_pk_u8_f32 v86, v90, 1, v86
	v_rndne_f32_e32 v89, v89
	v_rndne_f32_e32 v92, v92
	v_cvt_pk_u8_f32 v15, v88, 2, v15
	v_cvt_pk_u8_f32 v87, v91, 2, v86
	v_cvt_pk_u8_f32 v86, v89, 3, v15
	v_cvt_pk_u8_f32 v87, v92, 3, v87
	global_store_dwordx2 v[94:95], v[86:87], off offset:128

.LBB0_1064:
	ds_read_b128 v[86:89], v182 offset:16
	s_waitcnt lgkmcnt(0)
	v_mov_b32_e32 v90, v87
	v_mov_b32_e32 v91, v88
	v_mov_b32_e32 v87, v89
	v_pk_add_f32 v[86:87], v[90:91], v[86:87]
	s_nop 0
	v_add_f32_e32 v15, v86, v87
	v_fmamk_f32 v15, v15, 0x3c000000, v250
	v_mul_f32_e32 v86, 0x4b800000, v15
	v_cmp_gt_f32_e32 vcc, s28, v15
	s_nop 1
	v_cndmask_b32_e32 v15, v15, v86, vcc
	v_rsq_f32_e32 v15, v15
	s_nop 0
	v_mul_f32_e32 v86, 0x45800000, v15
	v_cndmask_b32_e32 v86, v15, v86, vcc
	v_pk_mul_f32 v[82:83], v[82:83], v[86:87] op_sel_hi:[1,0]
	v_pk_mul_f32 v[84:85], v[84:85], v[86:87] op_sel_hi:[1,0]
	v_pk_mul_f32 v[78:79], v[78:79], v[86:87] op_sel_hi:[1,0]
	v_pk_mul_f32 v[80:81], v[80:81], v[86:87] op_sel_hi:[1,0]
	v_pk_mul_f32 v[88:89], v[12:13], v[84:85]
	v_pk_mul_f32 v[86:87], v[10:11], v[82:83]
	v_pk_mul_f32 v[92:93], v[20:21], v[80:81]
	v_pk_mul_f32 v[90:91], v[18:19], v[78:79]
	s_branch .LBB0_1070

.LBB0_1071:
	v_add_u32_e32 v88, 0x80, v14
	v_ashrrev_i32_e32 v89, 31, v88
	s_and_b64 vcc, exec, s[46:47]
	v_lshlrev_b64 v[86:87], 13, v[88:89]
	s_cbranch_vccnz .LBB0_1089
	s_cmp_gt_i32 s5, 2
	s_mov_b64 s[24:25], -1
	s_cbranch_scc0 .LBB0_1074
	v_lshl_add_u64 v[82:83], s[8:9], 2, v[158:159]
	v_mov_b64_e32 v[78:79], v[204:205]
	v_mov_b64_e32 v[80:81], v[206:207]
	s_nop 0
	v_mov_b64_e32 v[82:83], v[200:201]
	v_mov_b64_e32 v[84:85], v[202:203]
	s_mov_b64 s[24:25], 0
	v_add_f32_e32 v78, v70, v78
	v_mul_f32_e32 v78, 0xbfb8aa3b, v78
	v_add_f32_e32 v79, v71, v79
	v_exp_f32_e32 v78, v78
	v_mul_f32_e32 v79, 0xbfb8aa3b, v79
	v_exp_f32_e32 v79, v79
	v_add_f32_e32 v15, v74, v82
	v_add_f32_e32 v78, 1.0, v78
	v_rcp_f32_e32 v78, v78
	v_add_f32_e32 v79, 1.0, v79
	v_rcp_f32_e32 v79, v79
	v_mul_f32_e32 v15, 0xbfb8aa3b, v15
	v_mul_f32_e32 v78, 0x437f0000, v78
	v_rndne_f32_e32 v78, v78
	v_mul_f32_e32 v79, 0x437f0000, v79
	v_cvt_pk_u8_f32 v78, v78, 0, 0
	v_add_f32_e32 v82, v75, v83
	v_rndne_f32_e32 v79, v79
	v_exp_f32_e32 v15, v15
	v_mul_f32_e32 v82, 0xbfb8aa3b, v82
	v_cvt_pk_u8_f32 v78, v79, 1, v78
	v_add_f32_e32 v79, v76, v84
	v_exp_f32_e32 v82, v82
	v_mul_f32_e32 v79, 0xbfb8aa3b, v79
	v_exp_f32_e32 v79, v79
	v_add_f32_e32 v15, 1.0, v15
	v_rcp_f32_e32 v15, v15
	v_add_f32_e32 v82, 1.0, v82
	v_rcp_f32_e32 v82, v82
	v_add_f32_e32 v79, 1.0, v79
	v_rcp_f32_e32 v79, v79
	v_mul_f32_e32 v15, 0x437f0000, v15
	v_rndne_f32_e32 v15, v15
	v_mul_f32_e32 v82, 0x437f0000, v82
	v_cvt_pk_u8_f32 v15, v15, 0, 0
	v_rndne_f32_e32 v82, v82
	v_mul_f32_e32 v79, 0x437f0000, v79
	v_cvt_pk_u8_f32 v15, v82, 1, v15
	v_rndne_f32_e32 v79, v79
	v_cvt_pk_u8_f32 v15, v79, 2, v15
	v_add_f32_e32 v79, v72, v80
	v_mul_f32_e32 v79, 0xbfb8aa3b, v79
	v_exp_f32_e32 v79, v79
	s_nop 0
	v_add_f32_e32 v79, 1.0, v79
	v_rcp_f32_e32 v79, v79
	s_nop 0
	v_mul_f32_e32 v79, 0x437f0000, v79
	v_rndne_f32_e32 v79, v79
	v_cvt_pk_u8_f32 v79, v79, 2, v78
	v_add_f32_e32 v78, v77, v85
	v_mul_f32_e32 v78, 0xbfb8aa3b, v78
	v_exp_f32_e32 v78, v78
	s_nop 0
	v_add_f32_e32 v78, 1.0, v78
	v_rcp_f32_e32 v78, v78
	s_nop 0
	v_mul_f32_e32 v78, 0x437f0000, v78
	v_rndne_f32_e32 v78, v78
	v_cvt_pk_u8_f32 v78, v78, 3, v15
	v_add_f32_e32 v15, v73, v81
	v_mul_f32_e32 v15, 0xbfb8aa3b, v15
	v_exp_f32_e32 v15, v15
	v_lshl_add_u64 v[80:81], s[58:59], 0, v[86:87]
	v_lshl_add_u64 v[80:81], v[80:81], 0, s[8:9]
	v_lshl_add_u64 v[80:81], v[80:81], 0, s[94:95]
	v_add_f32_e32 v15, 1.0, v15
	v_rcp_f32_e32 v15, v15
	v_lshl_add_u64 v[80:81], v[80:81], 0, v[156:157]
	v_mul_f32_e32 v15, 0x437f0000, v15
	v_rndne_f32_e32 v15, v15
	v_cvt_pk_u8_f32 v79, v15, 3, v79
	global_store_dwordx2 v[80:81], v[78:79], off

.LBB0_1079:
	ds_read_b128 v[78:81], v185
	s_waitcnt lgkmcnt(0)
	v_mov_b32_e32 v82, v79
	v_mov_b32_e32 v83, v80
	v_mov_b32_e32 v79, v81
	v_pk_add_f32 v[78:79], v[82:83], v[78:79]
	s_nop 0
	v_add_f32_e32 v15, v78, v79
	v_fmamk_f32 v15, v15, 0x3c000000, v250
	v_mul_f32_e32 v78, 0x4b800000, v15
	v_cmp_gt_f32_e32 vcc, s28, v15
	s_nop 1
	v_cndmask_b32_e32 v15, v15, v78, vcc
	v_rsq_f32_e32 v15, v15
	s_nop 0
	v_mul_f32_e32 v78, 0x45800000, v15
	v_cndmask_b32_e32 v78, v15, v78, vcc
	v_pk_mul_f32 v[74:75], v[74:75], v[78:79] op_sel_hi:[1,0]
	v_pk_mul_f32 v[76:77], v[76:77], v[78:79] op_sel_hi:[1,0]
	v_pk_mul_f32 v[70:71], v[70:71], v[78:79] op_sel_hi:[1,0]
	v_pk_mul_f32 v[72:73], v[72:73], v[78:79] op_sel_hi:[1,0]
	v_pk_mul_f32 v[80:81], v[12:13], v[76:77]
	v_pk_mul_f32 v[78:79], v[10:11], v[74:75]
	v_pk_mul_f32 v[84:85], v[20:21], v[72:73]
	v_pk_mul_f32 v[82:83], v[18:19], v[70:71]
	v_mad_i64_i32 v[70:71], s[22:23], s20, v88, 0
	v_lshl_add_u64 v[88:89], v[70:71], 1, v[164:165]
	s_branch .LBB0_1091

.LBB0_1081:
	s_cmp_gt_i32 s5, 2
	s_mov_b64 s[24:25], -1
	s_cbranch_scc0 .LBB0_1083
	v_lshl_add_u64 v[74:75], s[8:9], 2, v[158:159]
	v_mov_b64_e32 v[70:71], v[208:209]
	v_mov_b64_e32 v[72:73], v[210:211]
	s_nop 0
	v_mov_b64_e32 v[74:75], v[216:217]
	v_mov_b64_e32 v[76:77], v[218:219]
	v_lshl_add_u64 v[78:79], s[58:59], 0, v[86:87]
	v_lshl_add_u64 v[78:79], v[78:79], 0, s[8:9]
	v_lshl_add_u64 v[78:79], v[78:79], 0, s[94:95]
	v_lshl_add_u64 v[78:79], v[78:79], 0, v[156:157]
	s_mov_b64 s[24:25], 0
	v_add_f32_e32 v15, v66, v70
	v_add_f32_e32 v70, v62, v74
	v_add_f32_e32 v71, v67, v71
	v_add_f32_e32 v74, v63, v75
	v_mul_f32_e32 v15, 0xbfb8aa3b, v15
	v_mul_f32_e32 v70, 0xbfb8aa3b, v70
	v_add_f32_e32 v72, v68, v72
	v_add_f32_e32 v75, v64, v76
	v_mul_f32_e32 v71, 0xbfb8aa3b, v71
	v_mul_f32_e32 v74, 0xbfb8aa3b, v74
	v_exp_f32_e32 v15, v15
	v_exp_f32_e32 v70, v70
	v_add_f32_e32 v73, v69, v73
	v_add_f32_e32 v76, v65, v77
	v_mul_f32_e32 v72, 0xbfb8aa3b, v72
	v_mul_f32_e32 v75, 0xbfb8aa3b, v75
	v_exp_f32_e32 v71, v71
	v_exp_f32_e32 v74, v74
	v_mul_f32_e32 v73, 0xbfb8aa3b, v73
	v_mul_f32_e32 v76, 0xbfb8aa3b, v76
	v_exp_f32_e32 v72, v72
	v_exp_f32_e32 v75, v75
	v_exp_f32_e32 v73, v73
	v_exp_f32_e32 v76, v76
	v_add_f32_e32 v15, 1.0, v15
	v_add_f32_e32 v70, 1.0, v70
	v_add_f32_e32 v71, 1.0, v71
	v_add_f32_e32 v74, 1.0, v74
	v_rcp_f32_e32 v15, v15
	v_rcp_f32_e32 v70, v70
	v_add_f32_e32 v72, 1.0, v72
	v_add_f32_e32 v75, 1.0, v75
	v_rcp_f32_e32 v71, v71
	v_rcp_f32_e32 v74, v74
	v_add_f32_e32 v73, 1.0, v73
	v_add_f32_e32 v76, 1.0, v76
	v_rcp_f32_e32 v72, v72
	v_rcp_f32_e32 v75, v75
	v_rcp_f32_e32 v73, v73
	v_rcp_f32_e32 v76, v76
	v_mul_f32_e32 v15, 0x437f0000, v15
	v_mul_f32_e32 v70, 0x437f0000, v70
	v_mul_f32_e32 v71, 0x437f0000, v71
	v_mul_f32_e32 v74, 0x437f0000, v74
	v_rndne_f32_e32 v15, v15
	v_rndne_f32_e32 v70, v70
	v_mul_f32_e32 v72, 0x437f0000, v72
	v_mul_f32_e32 v75, 0x437f0000, v75
	v_rndne_f32_e32 v71, v71
	v_rndne_f32_e32 v74, v74
	v_cvt_pk_u8_f32 v15, v15, 0, 0
	v_cvt_pk_u8_f32 v70, v70, 0, 0
	v_mul_f32_e32 v73, 0x437f0000, v73
	v_mul_f32_e32 v76, 0x437f0000, v76
	v_rndne_f32_e32 v72, v72
	v_rndne_f32_e32 v75, v75
	v_cvt_pk_u8_f32 v15, v71, 1, v15
	v_cvt_pk_u8_f32 v70, v74, 1, v70
	v_rndne_f32_e32 v73, v73
	v_rndne_f32_e32 v76, v76
	v_cvt_pk_u8_f32 v15, v72, 2, v15
	v_cvt_pk_u8_f32 v71, v75, 2, v70
	v_cvt_pk_u8_f32 v70, v73, 3, v15
	v_cvt_pk_u8_f32 v71, v76, 3, v71
	global_store_dwordx2 v[78:79], v[70:71], off offset:128

.LBB0_1088:
	ds_read_b128 v[70:73], v185 offset:16
	s_waitcnt lgkmcnt(0)
	v_mov_b32_e32 v74, v71
	v_mov_b32_e32 v75, v72
	v_mov_b32_e32 v71, v73
	v_pk_add_f32 v[70:71], v[74:75], v[70:71]
	s_nop 0
	v_add_f32_e32 v15, v70, v71
	v_fmamk_f32 v15, v15, 0x3c000000, v250
	v_mul_f32_e32 v70, 0x4b800000, v15
	v_cmp_gt_f32_e32 vcc, s28, v15
	s_nop 1
	v_cndmask_b32_e32 v15, v15, v70, vcc
	v_rsq_f32_e32 v15, v15
	s_nop 0
	v_mul_f32_e32 v70, 0x45800000, v15
	v_cndmask_b32_e32 v70, v15, v70, vcc
	v_pk_mul_f32 v[66:67], v[66:67], v[70:71] op_sel_hi:[1,0]
	v_pk_mul_f32 v[68:69], v[68:69], v[70:71] op_sel_hi:[1,0]
	v_pk_mul_f32 v[62:63], v[62:63], v[70:71] op_sel_hi:[1,0]
	v_pk_mul_f32 v[64:65], v[64:65], v[70:71] op_sel_hi:[1,0]
	v_pk_mul_f32 v[72:73], v[12:13], v[68:69]
	v_pk_mul_f32 v[70:71], v[10:11], v[66:67]
	v_pk_mul_f32 v[76:77], v[20:21], v[64:65]
	v_pk_mul_f32 v[74:75], v[18:19], v[62:63]
	s_branch .LBB0_1094

.LBB0_1095:
	v_add_u32_e32 v72, 0x90, v14
	v_ashrrev_i32_e32 v73, 31, v72
	s_and_b64 vcc, exec, s[46:47]
	v_lshlrev_b64 v[70:71], 13, v[72:73]
	s_cbranch_vccnz .LBB0_1113
	s_cmp_gt_i32 s5, 2
	s_mov_b64 s[24:25], -1
	s_cbranch_scc0 .LBB0_1098
	v_lshl_add_u64 v[66:67], s[8:9], 2, v[158:159]
	v_mov_b64_e32 v[62:63], v[204:205]
	v_mov_b64_e32 v[64:65], v[206:207]
	s_nop 0
	v_mov_b64_e32 v[66:67], v[200:201]
	v_mov_b64_e32 v[68:69], v[202:203]
	s_mov_b64 s[24:25], 0
	v_add_f32_e32 v62, v54, v62
	v_mul_f32_e32 v62, 0xbfb8aa3b, v62
	v_add_f32_e32 v63, v55, v63
	v_exp_f32_e32 v62, v62
	v_mul_f32_e32 v63, 0xbfb8aa3b, v63
	v_exp_f32_e32 v63, v63
	v_add_f32_e32 v15, v58, v66
	v_add_f32_e32 v62, 1.0, v62
	v_rcp_f32_e32 v62, v62
	v_add_f32_e32 v63, 1.0, v63
	v_rcp_f32_e32 v63, v63
	v_mul_f32_e32 v15, 0xbfb8aa3b, v15
	v_mul_f32_e32 v62, 0x437f0000, v62
	v_rndne_f32_e32 v62, v62
	v_mul_f32_e32 v63, 0x437f0000, v63
	v_cvt_pk_u8_f32 v62, v62, 0, 0
	v_add_f32_e32 v66, v59, v67
	v_rndne_f32_e32 v63, v63
	v_exp_f32_e32 v15, v15
	v_mul_f32_e32 v66, 0xbfb8aa3b, v66
	v_cvt_pk_u8_f32 v62, v63, 1, v62
	v_add_f32_e32 v63, v60, v68
	v_exp_f32_e32 v66, v66
	v_mul_f32_e32 v63, 0xbfb8aa3b, v63
	v_exp_f32_e32 v63, v63
	v_add_f32_e32 v15, 1.0, v15
	v_rcp_f32_e32 v15, v15
	v_add_f32_e32 v66, 1.0, v66
	v_rcp_f32_e32 v66, v66
	v_add_f32_e32 v63, 1.0, v63
	v_rcp_f32_e32 v63, v63
	v_mul_f32_e32 v15, 0x437f0000, v15
	v_rndne_f32_e32 v15, v15
	v_mul_f32_e32 v66, 0x437f0000, v66
	v_cvt_pk_u8_f32 v15, v15, 0, 0
	v_rndne_f32_e32 v66, v66
	v_mul_f32_e32 v63, 0x437f0000, v63
	v_cvt_pk_u8_f32 v15, v66, 1, v15
	v_rndne_f32_e32 v63, v63
	v_cvt_pk_u8_f32 v15, v63, 2, v15
	v_add_f32_e32 v63, v56, v64
	v_mul_f32_e32 v63, 0xbfb8aa3b, v63
	v_exp_f32_e32 v63, v63
	s_nop 0
	v_add_f32_e32 v63, 1.0, v63
	v_rcp_f32_e32 v63, v63
	s_nop 0
	v_mul_f32_e32 v63, 0x437f0000, v63
	v_rndne_f32_e32 v63, v63
	v_cvt_pk_u8_f32 v63, v63, 2, v62
	v_add_f32_e32 v62, v61, v69
	v_mul_f32_e32 v62, 0xbfb8aa3b, v62
	v_exp_f32_e32 v62, v62
	s_nop 0
	v_add_f32_e32 v62, 1.0, v62
	v_rcp_f32_e32 v62, v62
	s_nop 0
	v_mul_f32_e32 v62, 0x437f0000, v62
	v_rndne_f32_e32 v62, v62
	v_cvt_pk_u8_f32 v62, v62, 3, v15
	v_add_f32_e32 v15, v57, v65
	v_mul_f32_e32 v15, 0xbfb8aa3b, v15
	v_exp_f32_e32 v15, v15
	v_lshl_add_u64 v[64:65], s[58:59], 0, v[70:71]
	v_lshl_add_u64 v[64:65], v[64:65], 0, s[8:9]
	v_lshl_add_u64 v[64:65], v[64:65], 0, s[94:95]
	v_add_f32_e32 v15, 1.0, v15
	v_rcp_f32_e32 v15, v15
	v_lshl_add_u64 v[64:65], v[64:65], 0, v[156:157]
	v_mul_f32_e32 v15, 0x437f0000, v15
	v_rndne_f32_e32 v15, v15
	v_cvt_pk_u8_f32 v63, v15, 3, v63
	global_store_dwordx2 v[64:65], v[62:63], off

.LBB0_1103:
	ds_read_b128 v[62:65], v188
	s_waitcnt lgkmcnt(0)
	v_mov_b32_e32 v66, v63
	v_mov_b32_e32 v67, v64
	v_mov_b32_e32 v63, v65
	v_pk_add_f32 v[62:63], v[66:67], v[62:63]
	s_nop 0
	v_add_f32_e32 v15, v62, v63
	v_fmamk_f32 v15, v15, 0x3c000000, v250
	v_mul_f32_e32 v62, 0x4b800000, v15
	v_cmp_gt_f32_e32 vcc, s28, v15
	s_nop 1
	v_cndmask_b32_e32 v15, v15, v62, vcc
	v_rsq_f32_e32 v15, v15
	s_nop 0
	v_mul_f32_e32 v62, 0x45800000, v15
	v_cndmask_b32_e32 v62, v15, v62, vcc
	v_pk_mul_f32 v[58:59], v[58:59], v[62:63] op_sel_hi:[1,0]
	v_pk_mul_f32 v[60:61], v[60:61], v[62:63] op_sel_hi:[1,0]
	v_pk_mul_f32 v[54:55], v[54:55], v[62:63] op_sel_hi:[1,0]
	v_pk_mul_f32 v[56:57], v[56:57], v[62:63] op_sel_hi:[1,0]
	v_pk_mul_f32 v[64:65], v[12:13], v[60:61]
	v_pk_mul_f32 v[62:63], v[10:11], v[58:59]
	v_pk_mul_f32 v[68:69], v[20:21], v[56:57]
	v_pk_mul_f32 v[66:67], v[18:19], v[54:55]
	v_mad_i64_i32 v[54:55], s[22:23], s20, v72, 0
	v_lshl_add_u64 v[72:73], v[54:55], 1, v[164:165]
	s_branch .LBB0_1115

.LBB0_1105:
	s_cmp_gt_i32 s5, 2
	s_mov_b64 s[24:25], -1
	s_cbranch_scc0 .LBB0_1107
	v_lshl_add_u64 v[58:59], s[8:9], 2, v[158:159]
	v_mov_b64_e32 v[54:55], v[208:209]
	v_mov_b64_e32 v[56:57], v[210:211]
	s_nop 0
	v_mov_b64_e32 v[58:59], v[216:217]
	v_mov_b64_e32 v[60:61], v[218:219]
	v_lshl_add_u64 v[62:63], s[58:59], 0, v[70:71]
	v_lshl_add_u64 v[62:63], v[62:63], 0, s[8:9]
	v_lshl_add_u64 v[62:63], v[62:63], 0, s[94:95]
	v_lshl_add_u64 v[62:63], v[62:63], 0, v[156:157]
	s_mov_b64 s[24:25], 0
	v_add_f32_e32 v15, v50, v54
	v_add_f32_e32 v54, v46, v58
	v_add_f32_e32 v55, v51, v55
	v_add_f32_e32 v58, v47, v59
	v_mul_f32_e32 v15, 0xbfb8aa3b, v15
	v_mul_f32_e32 v54, 0xbfb8aa3b, v54
	v_add_f32_e32 v56, v52, v56
	v_add_f32_e32 v59, v48, v60
	v_mul_f32_e32 v55, 0xbfb8aa3b, v55
	v_mul_f32_e32 v58, 0xbfb8aa3b, v58
	v_exp_f32_e32 v15, v15
	v_exp_f32_e32 v54, v54
	v_add_f32_e32 v57, v53, v57
	v_add_f32_e32 v60, v49, v61
	v_mul_f32_e32 v56, 0xbfb8aa3b, v56
	v_mul_f32_e32 v59, 0xbfb8aa3b, v59
	v_exp_f32_e32 v55, v55
	v_exp_f32_e32 v58, v58
	v_mul_f32_e32 v57, 0xbfb8aa3b, v57
	v_mul_f32_e32 v60, 0xbfb8aa3b, v60
	v_exp_f32_e32 v56, v56
	v_exp_f32_e32 v59, v59
	v_exp_f32_e32 v57, v57
	v_exp_f32_e32 v60, v60
	v_add_f32_e32 v15, 1.0, v15
	v_add_f32_e32 v54, 1.0, v54
	v_add_f32_e32 v55, 1.0, v55
	v_add_f32_e32 v58, 1.0, v58
	v_rcp_f32_e32 v15, v15
	v_rcp_f32_e32 v54, v54
	v_add_f32_e32 v56, 1.0, v56
	v_add_f32_e32 v59, 1.0, v59
	v_rcp_f32_e32 v55, v55
	v_rcp_f32_e32 v58, v58
	v_add_f32_e32 v57, 1.0, v57
	v_add_f32_e32 v60, 1.0, v60
	v_rcp_f32_e32 v56, v56
	v_rcp_f32_e32 v59, v59
	v_rcp_f32_e32 v57, v57
	v_rcp_f32_e32 v60, v60
	v_mul_f32_e32 v15, 0x437f0000, v15
	v_mul_f32_e32 v54, 0x437f0000, v54
	v_mul_f32_e32 v55, 0x437f0000, v55
	v_mul_f32_e32 v58, 0x437f0000, v58
	v_rndne_f32_e32 v15, v15
	v_rndne_f32_e32 v54, v54
	v_mul_f32_e32 v56, 0x437f0000, v56
	v_mul_f32_e32 v59, 0x437f0000, v59
	v_rndne_f32_e32 v55, v55
	v_rndne_f32_e32 v58, v58
	v_cvt_pk_u8_f32 v15, v15, 0, 0
	v_cvt_pk_u8_f32 v54, v54, 0, 0
	v_mul_f32_e32 v57, 0x437f0000, v57
	v_mul_f32_e32 v60, 0x437f0000, v60
	v_rndne_f32_e32 v56, v56
	v_rndne_f32_e32 v59, v59
	v_cvt_pk_u8_f32 v15, v55, 1, v15
	v_cvt_pk_u8_f32 v54, v58, 1, v54
	v_rndne_f32_e32 v57, v57
	v_rndne_f32_e32 v60, v60
	v_cvt_pk_u8_f32 v15, v56, 2, v15
	v_cvt_pk_u8_f32 v55, v59, 2, v54
	v_cvt_pk_u8_f32 v54, v57, 3, v15
	v_cvt_pk_u8_f32 v55, v60, 3, v55
	global_store_dwordx2 v[62:63], v[54:55], off offset:128

.LBB0_1112:
	ds_read_b128 v[54:57], v188 offset:16
	s_waitcnt lgkmcnt(0)
	v_mov_b32_e32 v58, v55
	v_mov_b32_e32 v59, v56
	v_mov_b32_e32 v55, v57
	v_pk_add_f32 v[54:55], v[58:59], v[54:55]
	s_nop 0
	v_add_f32_e32 v15, v54, v55
	v_fmamk_f32 v15, v15, 0x3c000000, v250
	v_mul_f32_e32 v54, 0x4b800000, v15
	v_cmp_gt_f32_e32 vcc, s28, v15
	s_nop 1
	v_cndmask_b32_e32 v15, v15, v54, vcc
	v_rsq_f32_e32 v15, v15
	s_nop 0
	v_mul_f32_e32 v54, 0x45800000, v15
	v_cndmask_b32_e32 v54, v15, v54, vcc
	v_pk_mul_f32 v[50:51], v[50:51], v[54:55] op_sel_hi:[1,0]
	v_pk_mul_f32 v[52:53], v[52:53], v[54:55] op_sel_hi:[1,0]
	v_pk_mul_f32 v[46:47], v[46:47], v[54:55] op_sel_hi:[1,0]
	v_pk_mul_f32 v[48:49], v[48:49], v[54:55] op_sel_hi:[1,0]
	v_pk_mul_f32 v[56:57], v[12:13], v[52:53]
	v_pk_mul_f32 v[54:55], v[10:11], v[50:51]
	v_pk_mul_f32 v[60:61], v[20:21], v[48:49]
	v_pk_mul_f32 v[58:59], v[18:19], v[46:47]
	s_branch .LBB0_1118

.LBB0_1119:
	v_add_u32_e32 v56, 0xa0, v14
	v_ashrrev_i32_e32 v57, 31, v56
	s_and_b64 vcc, exec, s[46:47]
	v_lshlrev_b64 v[54:55], 13, v[56:57]
	s_cbranch_vccnz .LBB0_1137
	s_cmp_gt_i32 s5, 2
	s_mov_b64 s[24:25], -1
	s_cbranch_scc0 .LBB0_1122
	v_lshl_add_u64 v[50:51], s[8:9], 2, v[158:159]
	v_mov_b64_e32 v[46:47], v[204:205]
	v_mov_b64_e32 v[48:49], v[206:207]
	s_nop 0
	v_mov_b64_e32 v[50:51], v[200:201]
	v_mov_b64_e32 v[52:53], v[202:203]
	s_mov_b64 s[24:25], 0
	v_add_f32_e32 v46, v38, v46
	v_mul_f32_e32 v46, 0xbfb8aa3b, v46
	v_add_f32_e32 v47, v39, v47
	v_exp_f32_e32 v46, v46
	v_mul_f32_e32 v47, 0xbfb8aa3b, v47
	v_exp_f32_e32 v47, v47
	v_add_f32_e32 v15, v42, v50
	v_add_f32_e32 v46, 1.0, v46
	v_rcp_f32_e32 v46, v46
	v_add_f32_e32 v47, 1.0, v47
	v_rcp_f32_e32 v47, v47
	v_mul_f32_e32 v15, 0xbfb8aa3b, v15
	v_mul_f32_e32 v46, 0x437f0000, v46
	v_rndne_f32_e32 v46, v46
	v_mul_f32_e32 v47, 0x437f0000, v47
	v_cvt_pk_u8_f32 v46, v46, 0, 0
	v_add_f32_e32 v50, v43, v51
	v_rndne_f32_e32 v47, v47
	v_exp_f32_e32 v15, v15
	v_mul_f32_e32 v50, 0xbfb8aa3b, v50
	v_cvt_pk_u8_f32 v46, v47, 1, v46
	v_add_f32_e32 v47, v44, v52
	v_exp_f32_e32 v50, v50
	v_mul_f32_e32 v47, 0xbfb8aa3b, v47
	v_exp_f32_e32 v47, v47
	v_add_f32_e32 v15, 1.0, v15
	v_rcp_f32_e32 v15, v15
	v_add_f32_e32 v50, 1.0, v50
	v_rcp_f32_e32 v50, v50
	v_add_f32_e32 v47, 1.0, v47
	v_rcp_f32_e32 v47, v47
	v_mul_f32_e32 v15, 0x437f0000, v15
	v_rndne_f32_e32 v15, v15
	v_mul_f32_e32 v50, 0x437f0000, v50
	v_cvt_pk_u8_f32 v15, v15, 0, 0
	v_rndne_f32_e32 v50, v50
	v_mul_f32_e32 v47, 0x437f0000, v47
	v_cvt_pk_u8_f32 v15, v50, 1, v15
	v_rndne_f32_e32 v47, v47
	v_cvt_pk_u8_f32 v15, v47, 2, v15
	v_add_f32_e32 v47, v40, v48
	v_mul_f32_e32 v47, 0xbfb8aa3b, v47
	v_exp_f32_e32 v47, v47
	s_nop 0
	v_add_f32_e32 v47, 1.0, v47
	v_rcp_f32_e32 v47, v47
	s_nop 0
	v_mul_f32_e32 v47, 0x437f0000, v47
	v_rndne_f32_e32 v47, v47
	v_cvt_pk_u8_f32 v47, v47, 2, v46
	v_add_f32_e32 v46, v45, v53
	v_mul_f32_e32 v46, 0xbfb8aa3b, v46
	v_exp_f32_e32 v46, v46
	s_nop 0
	v_add_f32_e32 v46, 1.0, v46
	v_rcp_f32_e32 v46, v46
	s_nop 0
	v_mul_f32_e32 v46, 0x437f0000, v46
	v_rndne_f32_e32 v46, v46
	v_cvt_pk_u8_f32 v46, v46, 3, v15
	v_add_f32_e32 v15, v41, v49
	v_mul_f32_e32 v15, 0xbfb8aa3b, v15
	v_exp_f32_e32 v15, v15
	v_lshl_add_u64 v[48:49], s[58:59], 0, v[54:55]
	v_lshl_add_u64 v[48:49], v[48:49], 0, s[8:9]
	v_lshl_add_u64 v[48:49], v[48:49], 0, s[94:95]
	v_add_f32_e32 v15, 1.0, v15
	v_rcp_f32_e32 v15, v15
	v_lshl_add_u64 v[48:49], v[48:49], 0, v[156:157]
	v_mul_f32_e32 v15, 0x437f0000, v15
	v_rndne_f32_e32 v15, v15
	v_cvt_pk_u8_f32 v47, v15, 3, v47
	global_store_dwordx2 v[48:49], v[46:47], off

.LBB0_1127:
	ds_read_b128 v[46:49], v191
	s_waitcnt lgkmcnt(0)
	v_mov_b32_e32 v50, v47
	v_mov_b32_e32 v51, v48
	v_mov_b32_e32 v47, v49
	v_pk_add_f32 v[46:47], v[50:51], v[46:47]
	s_nop 0
	v_add_f32_e32 v15, v46, v47
	v_fmamk_f32 v15, v15, 0x3c000000, v250
	v_mul_f32_e32 v46, 0x4b800000, v15
	v_cmp_gt_f32_e32 vcc, s28, v15
	s_nop 1
	v_cndmask_b32_e32 v15, v15, v46, vcc
	v_rsq_f32_e32 v15, v15
	s_nop 0
	v_mul_f32_e32 v46, 0x45800000, v15
	v_cndmask_b32_e32 v46, v15, v46, vcc
	v_pk_mul_f32 v[42:43], v[42:43], v[46:47] op_sel_hi:[1,0]
	v_pk_mul_f32 v[44:45], v[44:45], v[46:47] op_sel_hi:[1,0]
	v_pk_mul_f32 v[38:39], v[38:39], v[46:47] op_sel_hi:[1,0]
	v_pk_mul_f32 v[40:41], v[40:41], v[46:47] op_sel_hi:[1,0]
	v_pk_mul_f32 v[48:49], v[12:13], v[44:45]
	v_pk_mul_f32 v[46:47], v[10:11], v[42:43]
	v_pk_mul_f32 v[52:53], v[20:21], v[40:41]
	v_pk_mul_f32 v[50:51], v[18:19], v[38:39]
	v_mad_i64_i32 v[38:39], s[22:23], s20, v56, 0
	v_lshl_add_u64 v[56:57], v[38:39], 1, v[164:165]
	s_branch .LBB0_1139

.LBB0_1129:
	s_cmp_gt_i32 s5, 2
	s_mov_b64 s[24:25], -1
	s_cbranch_scc0 .LBB0_1131
	v_lshl_add_u64 v[42:43], s[8:9], 2, v[158:159]
	v_mov_b64_e32 v[38:39], v[208:209]
	v_mov_b64_e32 v[40:41], v[210:211]
	s_nop 0
	v_mov_b64_e32 v[42:43], v[216:217]
	v_mov_b64_e32 v[44:45], v[218:219]
	v_lshl_add_u64 v[46:47], s[58:59], 0, v[54:55]
	v_lshl_add_u64 v[46:47], v[46:47], 0, s[8:9]
	v_lshl_add_u64 v[46:47], v[46:47], 0, s[94:95]
	v_lshl_add_u64 v[46:47], v[46:47], 0, v[156:157]
	s_mov_b64 s[24:25], 0
	v_add_f32_e32 v15, v34, v38
	v_add_f32_e32 v38, v30, v42
	v_add_f32_e32 v39, v35, v39
	v_add_f32_e32 v42, v31, v43
	v_mul_f32_e32 v15, 0xbfb8aa3b, v15
	v_mul_f32_e32 v38, 0xbfb8aa3b, v38
	v_add_f32_e32 v40, v36, v40
	v_add_f32_e32 v43, v32, v44
	v_mul_f32_e32 v39, 0xbfb8aa3b, v39
	v_mul_f32_e32 v42, 0xbfb8aa3b, v42
	v_exp_f32_e32 v15, v15
	v_exp_f32_e32 v38, v38
	v_add_f32_e32 v41, v37, v41
	v_add_f32_e32 v44, v33, v45
	v_mul_f32_e32 v40, 0xbfb8aa3b, v40
	v_mul_f32_e32 v43, 0xbfb8aa3b, v43
	v_exp_f32_e32 v39, v39
	v_exp_f32_e32 v42, v42
	v_mul_f32_e32 v41, 0xbfb8aa3b, v41
	v_mul_f32_e32 v44, 0xbfb8aa3b, v44
	v_exp_f32_e32 v40, v40
	v_exp_f32_e32 v43, v43
	v_exp_f32_e32 v41, v41
	v_exp_f32_e32 v44, v44
	v_add_f32_e32 v15, 1.0, v15
	v_add_f32_e32 v38, 1.0, v38
	v_add_f32_e32 v39, 1.0, v39
	v_add_f32_e32 v42, 1.0, v42
	v_rcp_f32_e32 v15, v15
	v_rcp_f32_e32 v38, v38
	v_add_f32_e32 v40, 1.0, v40
	v_add_f32_e32 v43, 1.0, v43
	v_rcp_f32_e32 v39, v39
	v_rcp_f32_e32 v42, v42
	v_add_f32_e32 v41, 1.0, v41
	v_add_f32_e32 v44, 1.0, v44
	v_rcp_f32_e32 v40, v40
	v_rcp_f32_e32 v43, v43
	v_rcp_f32_e32 v41, v41
	v_rcp_f32_e32 v44, v44
	v_mul_f32_e32 v15, 0x437f0000, v15
	v_mul_f32_e32 v38, 0x437f0000, v38
	v_mul_f32_e32 v39, 0x437f0000, v39
	v_mul_f32_e32 v42, 0x437f0000, v42
	v_rndne_f32_e32 v15, v15
	v_rndne_f32_e32 v38, v38
	v_mul_f32_e32 v40, 0x437f0000, v40
	v_mul_f32_e32 v43, 0x437f0000, v43
	v_rndne_f32_e32 v39, v39
	v_rndne_f32_e32 v42, v42
	v_cvt_pk_u8_f32 v15, v15, 0, 0
	v_cvt_pk_u8_f32 v38, v38, 0, 0
	v_mul_f32_e32 v41, 0x437f0000, v41
	v_mul_f32_e32 v44, 0x437f0000, v44
	v_rndne_f32_e32 v40, v40
	v_rndne_f32_e32 v43, v43
	v_cvt_pk_u8_f32 v15, v39, 1, v15
	v_cvt_pk_u8_f32 v38, v42, 1, v38
	v_rndne_f32_e32 v41, v41
	v_rndne_f32_e32 v44, v44
	v_cvt_pk_u8_f32 v15, v40, 2, v15
	v_cvt_pk_u8_f32 v39, v43, 2, v38
	v_cvt_pk_u8_f32 v38, v41, 3, v15
	v_cvt_pk_u8_f32 v39, v44, 3, v39
	global_store_dwordx2 v[46:47], v[38:39], off offset:128

.LBB0_1136:
	ds_read_b128 v[38:41], v191 offset:16
	s_waitcnt lgkmcnt(0)
	v_mov_b32_e32 v42, v39
	v_mov_b32_e32 v43, v40
	v_mov_b32_e32 v39, v41
	v_pk_add_f32 v[38:39], v[42:43], v[38:39]
	s_nop 0
	v_add_f32_e32 v15, v38, v39
	v_fmamk_f32 v15, v15, 0x3c000000, v250
	v_mul_f32_e32 v38, 0x4b800000, v15
	v_cmp_gt_f32_e32 vcc, s28, v15
	s_nop 1
	v_cndmask_b32_e32 v15, v15, v38, vcc
	v_rsq_f32_e32 v15, v15
	s_nop 0
	v_mul_f32_e32 v38, 0x45800000, v15
	v_cndmask_b32_e32 v38, v15, v38, vcc
	v_pk_mul_f32 v[34:35], v[34:35], v[38:39] op_sel_hi:[1,0]
	v_pk_mul_f32 v[36:37], v[36:37], v[38:39] op_sel_hi:[1,0]
	v_pk_mul_f32 v[30:31], v[30:31], v[38:39] op_sel_hi:[1,0]
	v_pk_mul_f32 v[32:33], v[32:33], v[38:39] op_sel_hi:[1,0]
	v_pk_mul_f32 v[40:41], v[12:13], v[36:37]
	v_pk_mul_f32 v[38:39], v[10:11], v[34:35]
	v_pk_mul_f32 v[44:45], v[20:21], v[32:33]
	v_pk_mul_f32 v[42:43], v[18:19], v[30:31]
	s_branch .LBB0_1142

.LBB0_1143:
	v_add_u32_e32 v38, 0xb0, v14
	v_ashrrev_i32_e32 v39, 31, v38
	s_and_b64 vcc, exec, s[46:47]
	v_lshlrev_b64 v[14:15], 13, v[38:39]
	s_cbranch_vccnz .LBB0_1161
	s_cmp_gt_i32 s5, 2
	s_mov_b64 s[24:25], -1
	s_cbranch_scc0 .LBB0_1146
	v_lshl_add_u64 v[34:35], s[8:9], 2, v[158:159]
	v_mov_b64_e32 v[30:31], v[204:205]
	v_mov_b64_e32 v[32:33], v[206:207]
	s_nop 0
	v_mov_b64_e32 v[34:35], v[200:201]
	v_mov_b64_e32 v[36:37], v[202:203]
	s_mov_b64 s[24:25], 0
	v_add_f32_e32 v30, v22, v30
	v_mul_f32_e32 v30, 0xbfb8aa3b, v30
	v_add_f32_e32 v31, v23, v31
	v_exp_f32_e32 v30, v30
	v_mul_f32_e32 v31, 0xbfb8aa3b, v31
	v_add_f32_e32 v32, v24, v32
	v_exp_f32_e32 v31, v31
	v_mul_f32_e32 v32, 0xbfb8aa3b, v32
	v_exp_f32_e32 v32, v32
	v_add_f32_e32 v30, 1.0, v30
	v_rcp_f32_e32 v30, v30
	v_add_f32_e32 v31, 1.0, v31
	v_rcp_f32_e32 v31, v31
	v_add_f32_e32 v32, 1.0, v32
	v_rcp_f32_e32 v32, v32
	v_mul_f32_e32 v30, 0x437f0000, v30
	v_add_f32_e32 v34, v26, v34
	v_rndne_f32_e32 v30, v30
	v_mul_f32_e32 v31, 0x437f0000, v31
	v_mul_f32_e32 v34, 0xbfb8aa3b, v34
	v_cvt_pk_u8_f32 v30, v30, 0, 0
	v_add_f32_e32 v35, v27, v35
	v_rndne_f32_e32 v31, v31
	v_mul_f32_e32 v32, 0x437f0000, v32
	v_exp_f32_e32 v34, v34
	v_mul_f32_e32 v35, 0xbfb8aa3b, v35
	v_cvt_pk_u8_f32 v30, v31, 1, v30
	v_add_f32_e32 v31, v28, v36
	v_rndne_f32_e32 v32, v32
	v_exp_f32_e32 v35, v35
	v_mul_f32_e32 v31, 0xbfb8aa3b, v31
	v_cvt_pk_u8_f32 v32, v32, 2, v30
	v_add_f32_e32 v30, v29, v37
	v_exp_f32_e32 v31, v31
	v_mul_f32_e32 v30, 0xbfb8aa3b, v30
	v_exp_f32_e32 v30, v30
	v_add_f32_e32 v34, 1.0, v34
	v_rcp_f32_e32 v34, v34
	v_add_f32_e32 v35, 1.0, v35
	v_rcp_f32_e32 v35, v35
	v_add_f32_e32 v31, 1.0, v31
	v_rcp_f32_e32 v31, v31
	v_add_f32_e32 v30, 1.0, v30
	v_rcp_f32_e32 v30, v30
	v_mul_f32_e32 v34, 0x437f0000, v34
	v_rndne_f32_e32 v34, v34
	v_mul_f32_e32 v35, 0x437f0000, v35
	v_cvt_pk_u8_f32 v34, v34, 0, 0
	v_rndne_f32_e32 v35, v35
	v_mul_f32_e32 v31, 0x437f0000, v31
	v_cvt_pk_u8_f32 v34, v35, 1, v34
	v_rndne_f32_e32 v31, v31
	v_mul_f32_e32 v30, 0x437f0000, v30
	v_cvt_pk_u8_f32 v31, v31, 2, v34
	v_rndne_f32_e32 v30, v30
	v_cvt_pk_u8_f32 v30, v30, 3, v31
	v_add_f32_e32 v31, v25, v33
	v_mul_f32_e32 v31, 0xbfb8aa3b, v31
	v_exp_f32_e32 v31, v31
	s_nop 0
	v_add_f32_e32 v31, 1.0, v31
	v_rcp_f32_e32 v31, v31
	s_nop 0
	v_mul_f32_e32 v31, 0x437f0000, v31
	v_rndne_f32_e32 v31, v31
	v_cvt_pk_u8_f32 v31, v31, 3, v32
	v_lshl_add_u64 v[32:33], s[58:59], 0, v[14:15]
	v_lshl_add_u64 v[32:33], v[32:33], 0, s[8:9]
	v_lshl_add_u64 v[32:33], v[32:33], 0, s[94:95]
	v_lshl_add_u64 v[32:33], v[32:33], 0, v[156:157]
	global_store_dwordx2 v[32:33], v[30:31], off

.LBB0_1151:
	ds_read_b128 v[30:33], v194
	s_waitcnt lgkmcnt(0)
	v_mov_b32_e32 v34, v31
	v_mov_b32_e32 v35, v32
	v_mov_b32_e32 v31, v33
	v_pk_add_f32 v[30:31], v[34:35], v[30:31]
	s_nop 0
	v_add_f32_e32 v30, v30, v31
	v_fmamk_f32 v30, v30, 0x3c000000, v250
	v_mul_f32_e32 v31, 0x4b800000, v30
	v_cmp_gt_f32_e32 vcc, s28, v30
	s_nop 1
	v_cndmask_b32_e32 v30, v30, v31, vcc
	v_rsq_f32_e32 v30, v30
	s_nop 0
	v_mul_f32_e32 v31, 0x45800000, v30
	v_cndmask_b32_e32 v30, v30, v31, vcc
	v_pk_mul_f32 v[26:27], v[26:27], v[30:31] op_sel_hi:[1,0]
	v_pk_mul_f32 v[28:29], v[28:29], v[30:31] op_sel_hi:[1,0]
	v_pk_mul_f32 v[22:23], v[22:23], v[30:31] op_sel_hi:[1,0]
	v_pk_mul_f32 v[24:25], v[24:25], v[30:31] op_sel_hi:[1,0]
	v_pk_mul_f32 v[32:33], v[12:13], v[28:29]
	v_pk_mul_f32 v[30:31], v[10:11], v[26:27]
	v_pk_mul_f32 v[36:37], v[20:21], v[24:25]
	v_pk_mul_f32 v[34:35], v[18:19], v[22:23]
	v_mad_i64_i32 v[22:23], s[20:21], s20, v38, 0
	v_lshl_add_u64 v[38:39], v[22:23], 1, v[164:165]
	s_branch .LBB0_1163

.LBB0_1153:
	s_cmp_gt_i32 s5, 2
	s_mov_b64 s[20:21], -1
	s_cbranch_scc0 .LBB0_1155
	v_lshl_add_u64 v[26:27], s[8:9], 2, v[158:159]
	v_mov_b64_e32 v[22:23], v[208:209]
	v_mov_b64_e32 v[24:25], v[210:211]
	s_nop 0
	v_mov_b64_e32 v[26:27], v[216:217]
	v_mov_b64_e32 v[28:29], v[218:219]
	v_lshl_add_u64 v[14:15], s[58:59], 0, v[14:15]
	v_lshl_add_u64 v[14:15], v[14:15], 0, s[8:9]
	v_lshl_add_u64 v[14:15], v[14:15], 0, s[94:95]
	v_lshl_add_u64 v[14:15], v[14:15], 0, v[156:157]
	s_mov_b64 s[20:21], 0
	v_add_f32_e32 v22, v6, v22
	v_add_f32_e32 v26, v2, v26
	v_add_f32_e32 v23, v7, v23
	v_add_f32_e32 v27, v3, v27
	v_mul_f32_e32 v22, 0xbfb8aa3b, v22
	v_mul_f32_e32 v26, 0xbfb8aa3b, v26
	v_add_f32_e32 v24, v8, v24
	v_add_f32_e32 v28, v4, v28
	v_mul_f32_e32 v23, 0xbfb8aa3b, v23
	v_mul_f32_e32 v27, 0xbfb8aa3b, v27
	v_exp_f32_e32 v22, v22
	v_exp_f32_e32 v26, v26
	v_add_f32_e32 v25, v9, v25
	v_add_f32_e32 v29, v5, v29
	v_mul_f32_e32 v24, 0xbfb8aa3b, v24
	v_mul_f32_e32 v28, 0xbfb8aa3b, v28
	v_exp_f32_e32 v23, v23
	v_exp_f32_e32 v27, v27
	v_mul_f32_e32 v25, 0xbfb8aa3b, v25
	v_mul_f32_e32 v29, 0xbfb8aa3b, v29
	v_exp_f32_e32 v24, v24
	v_exp_f32_e32 v28, v28
	v_exp_f32_e32 v25, v25
	v_exp_f32_e32 v29, v29
	v_add_f32_e32 v22, 1.0, v22
	v_add_f32_e32 v26, 1.0, v26
	v_add_f32_e32 v23, 1.0, v23
	v_add_f32_e32 v27, 1.0, v27
	v_rcp_f32_e32 v22, v22
	v_rcp_f32_e32 v26, v26
	v_add_f32_e32 v24, 1.0, v24
	v_add_f32_e32 v28, 1.0, v28
	v_rcp_f32_e32 v23, v23
	v_rcp_f32_e32 v27, v27
	v_add_f32_e32 v25, 1.0, v25
	v_add_f32_e32 v29, 1.0, v29
	v_rcp_f32_e32 v24, v24
	v_rcp_f32_e32 v28, v28
	v_rcp_f32_e32 v25, v25
	v_rcp_f32_e32 v29, v29
	v_mul_f32_e32 v22, 0x437f0000, v22
	v_mul_f32_e32 v26, 0x437f0000, v26
	v_mul_f32_e32 v23, 0x437f0000, v23
	v_mul_f32_e32 v27, 0x437f0000, v27
	v_rndne_f32_e32 v22, v22
	v_rndne_f32_e32 v26, v26
	v_mul_f32_e32 v24, 0x437f0000, v24
	v_mul_f32_e32 v28, 0x437f0000, v28
	v_rndne_f32_e32 v23, v23
	v_rndne_f32_e32 v27, v27
	v_cvt_pk_u8_f32 v22, v22, 0, 0
	v_cvt_pk_u8_f32 v26, v26, 0, 0
	v_mul_f32_e32 v25, 0x437f0000, v25
	v_mul_f32_e32 v29, 0x437f0000, v29
	v_rndne_f32_e32 v24, v24
	v_rndne_f32_e32 v28, v28
	v_cvt_pk_u8_f32 v22, v23, 1, v22
	v_cvt_pk_u8_f32 v23, v27, 1, v26
	v_rndne_f32_e32 v25, v25
	v_rndne_f32_e32 v29, v29
	v_cvt_pk_u8_f32 v22, v24, 2, v22
	v_cvt_pk_u8_f32 v23, v28, 2, v23
	v_cvt_pk_u8_f32 v22, v25, 3, v22
	v_cvt_pk_u8_f32 v23, v29, 3, v23
	global_store_dwordx2 v[14:15], v[22:23], off offset:128

.LBB0_1160:
	ds_read_b128 v[22:25], v194 offset:16
	s_waitcnt lgkmcnt(0)
	v_mov_b32_e32 v14, v23
	v_mov_b32_e32 v15, v24
	v_mov_b32_e32 v23, v25
	v_pk_add_f32 v[14:15], v[14:15], v[22:23]
	s_nop 0
	v_add_f32_e32 v14, v14, v15
	v_fmamk_f32 v14, v14, 0x3c000000, v250
	v_mul_f32_e32 v15, 0x4b800000, v14
	v_cmp_gt_f32_e32 vcc, s28, v14
	s_nop 1
	v_cndmask_b32_e32 v14, v14, v15, vcc
	v_rsq_f32_e32 v14, v14
	s_nop 0
	v_mul_f32_e32 v15, 0x45800000, v14
	v_cndmask_b32_e32 v14, v14, v15, vcc
	v_pk_mul_f32 v[6:7], v[6:7], v[14:15] op_sel_hi:[1,0]
	v_pk_mul_f32 v[8:9], v[8:9], v[14:15] op_sel_hi:[1,0]
	v_pk_mul_f32 v[2:3], v[2:3], v[14:15] op_sel_hi:[1,0]
	v_pk_mul_f32 v[4:5], v[4:5], v[14:15] op_sel_hi:[1,0]
	v_pk_mul_f32 v[24:25], v[12:13], v[8:9]
	v_pk_mul_f32 v[22:23], v[10:11], v[6:7]
	v_pk_mul_f32 v[28:29], v[20:21], v[4:5]
	v_pk_mul_f32 v[26:27], v[18:19], v[2:3]
	s_branch .LBB0_1166
